# prep: adaLN weight rows streamed 48 loads deep; filter w3 rows all requested up front
# speedup vs baseline: 1.0273x; 1.0059x over previous
.LBB0_13:
	v_readlane_b32 s0, v252, 0
	v_readlane_b32 s8, v252, 3
	s_mov_b32 s70, s0
	v_readlane_b32 s0, v252, 1
	v_readlane_b32 s9, v252, 4
	s_mov_b32 s72, s0
	s_load_dwordx2 s[80:81], s[8:9], 0x140
	v_readlane_b32 s1, v252, 2
	s_mov_b64 s[10:11], -1
	s_mov_b64 s[12:13], 0
	s_cmp_lt_i32 s56, 35
	s_mov_b64 s[0:1], 0
	s_waitcnt lgkmcnt(0)
	s_mov_b64 s[100:101], s[80:81]
	s_mov_b64 s[4:5], -1
	s_cbranch_scc1 .LBB0_17
	s_cmp_eq_u32 s56, 35
	s_mov_b64 s[0:1], -1
	s_cbranch_scc0 .LBB0_16
	s_mov_b64 s[0:1], 0

.LBB0_602:
	s_add_i32 s98, s76, s10
	s_lshl_b32 s98, s98, 1
	s_lshl_b32 s99, s10, 1
	s_add_i32 s99, s6, s99
	s_and_b64 vcc, s[24:25], exec
	s_cselect_b32 s98, s98, s99
	s_or_b32 s98, s98, s14
	s_lshl_b32 s98, s98, 14
	v_lshlrev_b32_e32 v196, 5, v202
	s_add_u32 s98, s98, 0x4f28000
	s_add_u32 s98, s100, s98
	s_addc_u32 s99, s101, 0
	global_load_dwordx4 v[228:231], v196, s[98:99]
	global_load_dwordx4 v[232:235], v196, s[98:99] offset:16
	v_cndmask_b32_e64 v0, v94, v85, s[74:75]
	v_add_u32_e32 v0, s18, v0
	v_mad_i64_i32 v[2:3], s[20:21], v0, s88, v[22:23]
	v_cndmask_b32_e64 v0, v95, v84, s[74:75]
	v_add_u32_e32 v0, s18, v0
	global_load_ushort v157, v[2:3], off
	global_load_ushort v156, v[2:3], off offset:512
	v_mad_i64_i32 v[2:3], s[20:21], v0, s88, v[22:23]
	v_cndmask_b32_e64 v0, v96, v82, s[74:75]
	v_add_u32_e32 v0, s18, v0
	global_load_ushort v155, v[2:3], off
	global_load_ushort v154, v[2:3], off offset:512
	v_mad_i64_i32 v[2:3], s[20:21], v0, s88, v[22:23]
	v_cndmask_b32_e64 v0, v97, v81, s[74:75]
	v_add_u32_e32 v0, s18, v0
	global_load_ushort v153, v[2:3], off
	global_load_ushort v152, v[2:3], off offset:512
	v_mad_i64_i32 v[2:3], s[20:21], v0, s88, v[22:23]
	v_cndmask_b32_e64 v0, v98, v77, s[74:75]
	v_add_u32_e32 v0, s18, v0
	global_load_ushort v151, v[2:3], off
	global_load_ushort v150, v[2:3], off offset:512
	v_mad_i64_i32 v[2:3], s[20:21], v0, s88, v[22:23]
	v_cndmask_b32_e64 v0, v99, v75, s[74:75]
	v_add_u32_e32 v0, s18, v0
	global_load_ushort v149, v[2:3], off
	global_load_ushort v148, v[2:3], off offset:512
	v_mad_i64_i32 v[2:3], s[20:21], v0, s88, v[22:23]
	v_cndmask_b32_e64 v0, v100, v66, s[74:75]
	v_add_u32_e32 v0, s18, v0
	global_load_ushort v147, v[2:3], off
	global_load_ushort v146, v[2:3], off offset:512
	v_mad_i64_i32 v[2:3], s[20:21], v0, s88, v[22:23]
	v_cndmask_b32_e64 v0, v101, v65, s[74:75]
	v_add_u32_e32 v0, s18, v0
	global_load_ushort v145, v[2:3], off
	global_load_ushort v144, v[2:3], off offset:512
	v_mad_i64_i32 v[2:3], s[20:21], v0, s88, v[22:23]
	v_mov_b32_e32 v0, v202
	global_load_ushort v143, v[2:3], off
	global_load_ushort v142, v[2:3], off offset:512
	s_andn2_b64 vcc, exec, s[86:87]
	v_ashrrev_i32_e32 v6, 3, v0
	v_and_b32_e32 v11, -16, v6
	v_and_b32_e32 v10, 0x7f, v0
	v_sub_u32_e32 v0, 63, v11
	v_sub_u32_e32 v2, 62, v11
	v_or_b32_e32 v3, 1, v11
	v_cndmask_b32_e64 v0, v0, v11, s[74:75]
	v_cndmask_b32_e64 v2, v2, v3, s[74:75]
	v_add_u32_e32 v0, s18, v0
	v_add_u32_e32 v7, s18, v2
	v_mov_b64_e32 v[2:3], s[94:95]
	v_mad_i64_i32 v[4:5], s[20:21], v0, s88, v[2:3]
	v_lshlrev_b32_e32 v0, 1, v10
	v_lshl_add_u64 v[4:5], v[4:5], 0, v[0:1]
	global_load_ushort v8, v[4:5], off offset:1024
	v_mad_i64_i32 v[4:5], s[20:21], v7, s88, v[2:3]
	v_lshl_add_u64 v[4:5], v[4:5], 0, v[0:1]
	global_load_ushort v7, v[4:5], off offset:1024
	v_or_b32_e32 v4, 2, v11
	v_sub_u32_e32 v5, 63, v4
	v_cndmask_b32_e64 v5, v5, v4, s[74:75]
	v_sub_u32_e32 v4, 62, v4
	v_or_b32_e32 v9, 3, v11
	v_add_u32_e32 v5, s18, v5
	v_cndmask_b32_e64 v4, v4, v9, s[74:75]
	v_add_u32_e32 v9, s18, v4
	v_mad_i64_i32 v[4:5], s[20:21], v5, s88, v[2:3]
	v_lshl_add_u64 v[4:5], v[4:5], 0, v[0:1]
	global_load_ushort v12, v[4:5], off offset:1024
	v_mad_i64_i32 v[4:5], s[20:21], v9, s88, v[2:3]
	v_lshl_add_u64 v[4:5], v[4:5], 0, v[0:1]
	global_load_ushort v9, v[4:5], off offset:1024
	v_or_b32_e32 v4, 4, v11
	v_sub_u32_e32 v5, 63, v4
	v_cndmask_b32_e64 v5, v5, v4, s[74:75]
	v_sub_u32_e32 v4, 62, v4
	v_or_b32_e32 v13, 5, v11
	v_add_u32_e32 v5, s18, v5
	v_cndmask_b32_e64 v4, v4, v13, s[74:75]
	v_add_u32_e32 v13, s18, v4
	v_mad_i64_i32 v[4:5], s[20:21], v5, s88, v[2:3]
	v_lshl_add_u64 v[4:5], v[4:5], 0, v[0:1]
	global_load_ushort v14, v[4:5], off offset:1024
	v_mad_i64_i32 v[4:5], s[20:21], v13, s88, v[2:3]
	v_lshl_add_u64 v[4:5], v[4:5], 0, v[0:1]
	global_load_ushort v13, v[4:5], off offset:1024
	v_or_b32_e32 v4, 6, v11
	v_sub_u32_e32 v5, 63, v4
	v_cndmask_b32_e64 v5, v5, v4, s[74:75]
	v_sub_u32_e32 v4, 62, v4
	v_or_b32_e32 v15, 7, v11
	v_add_u32_e32 v5, s18, v5
	v_cndmask_b32_e64 v4, v4, v15, s[74:75]
	v_add_u32_e32 v15, s18, v4
	v_mad_i64_i32 v[4:5], s[20:21], v5, s88, v[2:3]
	v_lshl_add_u64 v[4:5], v[4:5], 0, v[0:1]
	global_load_ushort v16, v[4:5], off offset:1024
	v_mad_i64_i32 v[4:5], s[20:21], v15, s88, v[2:3]
	v_lshl_add_u64 v[4:5], v[4:5], 0, v[0:1]
	global_load_ushort v15, v[4:5], off offset:1024
	v_or_b32_e32 v4, 8, v11
	v_sub_u32_e32 v5, 63, v4
	v_cndmask_b32_e64 v5, v5, v4, s[74:75]
	v_sub_u32_e32 v4, 62, v4
	v_or_b32_e32 v17, 9, v11
	v_add_u32_e32 v5, s18, v5
	v_cndmask_b32_e64 v4, v4, v17, s[74:75]
	v_add_u32_e32 v17, s18, v4
	v_mad_i64_i32 v[4:5], s[20:21], v5, s88, v[2:3]
	v_lshl_add_u64 v[4:5], v[4:5], 0, v[0:1]
	global_load_ushort v60, v[4:5], off offset:1024
	v_mad_i64_i32 v[4:5], s[20:21], v17, s88, v[2:3]
	v_lshl_add_u64 v[4:5], v[4:5], 0, v[0:1]
	global_load_ushort v17, v[4:5], off offset:1024
	v_or_b32_e32 v4, 10, v11
	v_sub_u32_e32 v5, 63, v4
	v_cndmask_b32_e64 v5, v5, v4, s[74:75]
	v_sub_u32_e32 v4, 62, v4
	v_or_b32_e32 v61, 11, v11
	v_add_u32_e32 v5, s18, v5
	v_cndmask_b32_e64 v4, v4, v61, s[74:75]
	v_add_u32_e32 v61, s18, v4
	v_mad_i64_i32 v[4:5], s[20:21], v5, s88, v[2:3]
	v_lshl_add_u64 v[4:5], v[4:5], 0, v[0:1]
	global_load_ushort v158, v[4:5], off offset:1024
	v_mad_i64_i32 v[4:5], s[20:21], v61, s88, v[2:3]
	v_lshl_add_u64 v[4:5], v[4:5], 0, v[0:1]
	global_load_ushort v61, v[4:5], off offset:1024
	v_or_b32_e32 v4, 12, v11
	v_sub_u32_e32 v5, 63, v4
	v_cndmask_b32_e64 v5, v5, v4, s[74:75]
	v_sub_u32_e32 v4, 62, v4
	v_or_b32_e32 v159, 13, v11
	v_add_u32_e32 v5, s18, v5
	v_cndmask_b32_e64 v4, v4, v159, s[74:75]
	v_add_u32_e32 v159, s18, v4
	v_mad_i64_i32 v[4:5], s[20:21], v5, s88, v[2:3]
	v_lshl_add_u64 v[4:5], v[4:5], 0, v[0:1]
	global_load_ushort v160, v[4:5], off offset:1024
	v_mad_i64_i32 v[4:5], s[20:21], v159, s88, v[2:3]
	v_lshl_add_u64 v[4:5], v[4:5], 0, v[0:1]
	global_load_ushort v159, v[4:5], off offset:1024
	v_or_b32_e32 v4, 14, v11
	v_sub_u32_e32 v5, 63, v4
	v_cndmask_b32_e64 v5, v5, v4, s[74:75]
	v_sub_u32_e32 v4, 62, v4
	v_or_b32_e32 v6, 15, v6
	v_cndmask_b32_e64 v4, v4, v6, s[74:75]
	v_add_u32_e32 v5, s18, v5
	v_add_u32_e32 v6, s18, v4
	v_mad_i64_i32 v[4:5], s[20:21], v5, s88, v[2:3]
	v_mad_i64_i32 v[2:3], s[20:21], v6, s88, v[2:3]
	v_lshl_add_u64 v[4:5], v[4:5], 0, v[0:1]
	v_lshl_add_u64 v[2:3], v[2:3], 0, v[0:1]
	global_load_ushort v161, v[4:5], off offset:1024
	global_load_ushort v0, v[2:3], off offset:1024
	s_waitcnt vmcnt(12)
	v_lshl_or_b32 v3, v9, 16, v12
	v_lshl_or_b32 v2, v7, 16, v8
	s_waitcnt vmcnt(10)
	v_lshl_or_b32 v4, v13, 16, v14
	s_waitcnt vmcnt(8)
	v_lshl_or_b32 v5, v15, 16, v16
	s_waitcnt vmcnt(6)
	v_lshl_or_b32 v6, v17, 16, v60
	s_waitcnt vmcnt(4)
	v_lshl_or_b32 v7, v61, 16, v158
	s_waitcnt vmcnt(2)
	v_lshl_or_b32 v8, v159, 16, v160
	s_waitcnt vmcnt(0)
	v_lshl_or_b32 v9, v0, 16, v161
	v_mul_u32_u24_e32 v0, 0x90, v10
	v_lshlrev_b32_e32 v10, 1, v11
	v_add3_u32 v0, 0, v0, v10
	ds_write_b128 v0, v[2:5] offset:61440
	ds_write_b128 v0, v[6:9] offset:61456
	s_cbranch_vccnz .LBB0_604
	s_and_b64 s[20:21], s[74:75], exec
	s_cselect_b32 s4, 16, 24
	s_add_u32 s20, s8, s4
	s_addc_u32 s21, s9, 0
	s_load_dwordx2 s[20:21], s[20:21], 0x0
	s_waitcnt lgkmcnt(0)
	s_add_u32 s4, s20, s82
	s_addc_u32 s5, s21, s83
	s_add_u32 s20, s4, s91
	s_addc_u32 s21, s5, 0
	v_lshl_add_u64 v[10:11], v[24:25], 2, s[20:21]
	v_add_co_u32_e32 v60, vcc, 0x1000, v10
	global_load_dword v2, v[10:11], off
	global_load_dword v3, v[10:11], off offset:512
	global_load_dword v4, v[10:11], off offset:1024
	global_load_dword v5, v[10:11], off offset:1536
	global_load_dword v6, v[10:11], off offset:2048
	global_load_dword v7, v[10:11], off offset:2560
	global_load_dword v8, v[10:11], off offset:3072
	global_load_dword v9, v[10:11], off offset:3584
	v_addc_co_u32_e32 v61, vcc, 0, v11, vcc
	global_load_dword v10, v[60:61], off
	global_load_dword v11, v[60:61], off offset:512
	global_load_dword v12, v[60:61], off offset:1024
	global_load_dword v13, v[60:61], off offset:1536
	global_load_dword v14, v[60:61], off offset:2048
	global_load_dword v15, v[60:61], off offset:2560
	global_load_dword v16, v[60:61], off offset:3072
	global_load_dword v17, v[60:61], off offset:3584
	s_and_b64 s[20:21], s[74:75], exec
	s_cselect_b32 s15, s10, s11
	s_cmp_lt_i32 s15, 1
	s_cbranch_scc0 .LBB0_605
	s_branch .LBB0_610

.LBB0_675:
	s_or_b64 exec, exec, s[24:25]
	s_and_b64 s[10:11], vcc, exec
	s_movk_i32 s4, 0x68
	s_cselect_b32 s4, s4, 0x78
	s_add_u32 s10, s8, s4
	s_addc_u32 s11, s9, 0
	s_waitcnt lgkmcnt(0)
	s_barrier
	s_load_dwordx2 s[10:11], s[10:11], 0x0
	v_and_b32_e32 v3, 63, v2
	v_lshlrev_b32_e32 v0, 2, v3
	s_waitcnt lgkmcnt(0)
	s_add_u32 s4, s10, s22
	s_addc_u32 s5, s11, s23
	s_lshl_b32 s7, s6, 2
	s_add_u32 s10, s4, s7
	s_addc_u32 s11, s5, 0
	v_lshl_add_u64 v[8:9], s[10:11], 0, v[0:1]
	v_add_co_u32_e64 v34, s[40:41], s37, v8
	s_and_b64 s[14:15], vcc, exec
	s_nop 0
	v_addc_co_u32_e64 v35, s[40:41], 0, v9, s[40:41]
	s_movk_i32 s4, 0x70
	v_add_co_u32_e64 v36, s[40:41], s85, v8
	s_cselect_b32 s4, s4, 0x80
	s_nop 0
	v_addc_co_u32_e64 v37, s[40:41], 0, v9, s[40:41]
	s_add_u32 s14, s8, s4
	v_add_co_u32_e64 v26, s[40:41], s68, v8
	s_addc_u32 s15, s9, 0
	global_load_dword v6, v[36:37], off
	global_load_dword v7, v[36:37], off offset:1024
	global_load_dword v4, v[36:37], off offset:2048
	global_load_dword v5, v[36:37], off offset:3072
	v_addc_co_u32_e64 v27, s[40:41], 0, v9, s[40:41]
	global_load_dword v12, v[34:35], off offset:2048
	global_load_dword v13, v[34:35], off offset:3072
	global_load_dword v8, v[26:27], off
	s_load_dwordx2 s[14:15], s[14:15], 0x0
	v_readlane_b32 s4, v254, 41
	s_or_b32 s4, s6, s4
	global_load_dword v9, v[26:27], off offset:1024
	global_load_dword v10, v[26:27], off offset:2048
	global_load_dword v11, v[26:27], off offset:3072
	v_or_b32_e32 v26, s4, v3
	v_mov_b32_e32 v27, v1
	s_waitcnt lgkmcnt(0)
	v_lshl_add_u64 v[26:27], v[26:27], 2, s[14:15]
	global_load_dword v26, v[26:27], off
	s_nop 0
	global_load_dword v29, v0, s[10:11]
	global_load_dword v30, v0, s[10:11] offset:1024
	global_load_dword v31, v0, s[10:11] offset:2048
	global_load_dword v32, v0, s[10:11] offset:3072
	global_load_dword v28, v[36:37], off offset:-4096
	global_load_dword v27, v[34:35], off offset:1024
	v_ashrrev_i32_e32 v3, 6, v2
	v_lshl_add_u32 v25, v3, 9, 0
	ds_read_b128 v[34:37], v25 offset:27664
	ds_read_b128 v[38:41], v25 offset:27680
	ds_read_b128 v[42:45], v25 offset:27696
	ds_read_b128 v[46:49], v25 offset:27648
	s_mov_b32 s4, 0x3d800000
	v_lshl_add_u32 v2, v2, 2, 0
	v_add_u32_e32 v0, 0, v0
	v_readlane_b32 s5, v254, 42
	s_waitcnt vmcnt(15) lgkmcnt(2)
	v_pk_mul_f32 v[38:39], v[6:7], v[38:39]
	s_waitcnt vmcnt(13)
	v_pk_mul_f32 v[40:41], v[4:5], v[40:41]
	s_waitcnt vmcnt(11)
	v_pk_mul_f32 v[36:37], v[12:13], v[36:37]
	s_waitcnt vmcnt(9) lgkmcnt(1)
	v_pk_mul_f32 v[42:43], v[8:9], v[42:43]
	s_waitcnt vmcnt(5) lgkmcnt(0)
	v_fma_f32 v33, v29, v46, v26
	s_waitcnt vmcnt(4)
	v_fmac_f32_e32 v33, v30, v47
	s_waitcnt vmcnt(3)
	v_fmac_f32_e32 v33, v31, v48
	s_waitcnt vmcnt(2)
	v_fmac_f32_e32 v33, v32, v49
	s_waitcnt vmcnt(1)
	v_fmac_f32_e32 v33, v28, v34
	s_waitcnt vmcnt(0)
	v_fmac_f32_e32 v33, v27, v35
	v_add_f32_e32 v33, v33, v36
	v_add_f32_e32 v33, v33, v37
	v_add_f32_e32 v33, v33, v38
	v_add_f32_e32 v33, v33, v39
	v_add_f32_e32 v33, v33, v40
	v_add_f32_e32 v33, v33, v41
	v_add_f32_e32 v33, v33, v42
	v_pk_mul_f32 v[44:45], v[10:11], v[44:45]
	v_add_f32_e32 v33, v33, v43
	v_add_f32_e32 v33, v33, v44
	v_add_f32_e32 v33, v33, v45
	v_mul_f32_e64 v34, |v33|, s90
	v_exp_f32_e32 v38, v34
	v_min_f32_e32 v33, 0, v33
	v_add_f32_e32 v36, 1.0, v38
	v_add_f32_e32 v37, -1.0, v36
	v_frexp_mant_f32_e32 v39, v36
	v_cvt_f64_f32_e32 v[34:35], v36
	v_sub_f32_e32 v40, v37, v36
	v_frexp_exp_i32_f64_e32 v34, v[34:35]
	v_cmp_gt_f32_e32 vcc, s36, v39
	v_sub_f32_e32 v37, v38, v37
	v_add_f32_e32 v35, 1.0, v40
	v_subbrev_co_u32_e32 v34, vcc, 0, v34, vcc
	v_add_f32_e32 v35, v37, v35
	v_sub_u32_e32 v37, 0, v34
	v_cvt_f32_i32_e32 v34, v34
	v_ldexp_f32 v36, v36, v37
	v_ldexp_f32 v35, v35, v37
	v_add_f32_e32 v37, -1.0, v36
	v_add_f32_e32 v39, 1.0, v36
	v_add_f32_e32 v40, 1.0, v37
	v_add_f32_e32 v41, -1.0, v39
	v_sub_f32_e32 v40, v36, v40
	v_sub_f32_e32 v36, v36, v41
	v_mul_f32_e32 v41, 0x3f317218, v34
	v_add_f32_e32 v40, v35, v40
	v_add_f32_e32 v35, v35, v36
	v_fma_f32 v36, v34, s78, -v41
	v_add_f32_e32 v42, v37, v40
	v_add_f32_e32 v43, v39, v35
	v_fmac_f32_e32 v36, 0xb102e308, v34
	v_sub_f32_e32 v34, v42, v37
	v_sub_f32_e32 v37, v43, v39
	v_rcp_f32_e32 v39, v43
	v_add_f32_e32 v44, v41, v36
	v_sub_f32_e32 v35, v35, v37
	v_sub_f32_e32 v37, v44, v41
	v_sub_f32_e32 v36, v36, v37
	v_mul_f32_e32 v37, v42, v39
	v_sub_f32_e32 v34, v40, v34
	v_mul_f32_e32 v40, v43, v37
	v_fma_f32 v41, v37, v43, -v40
	v_fmac_f32_e32 v41, v37, v35
	v_add_f32_e32 v45, v40, v41
	v_sub_f32_e32 v46, v42, v45
	v_sub_f32_e32 v40, v45, v40
	v_sub_f32_e32 v42, v42, v46
	v_sub_f32_e32 v40, v40, v41
	v_sub_f32_e32 v41, v42, v45
	v_add_f32_e32 v34, v34, v41
	v_add_f32_e32 v34, v40, v34
	v_add_f32_e32 v40, v46, v34
	v_mul_f32_e32 v41, v39, v40
	v_sub_f32_e32 v42, v46, v40
	v_mul_f32_e32 v45, v43, v41
	v_add_f32_e32 v34, v34, v42
	v_add_f32_e32 v42, v37, v41
	v_fma_f32 v43, v41, v43, -v45
	v_sub_f32_e32 v37, v42, v37
	v_fmac_f32_e32 v43, v41, v35
	v_sub_f32_e32 v35, v41, v37
	v_add_f32_e32 v37, v45, v43
	v_sub_f32_e32 v41, v37, v45
	v_sub_f32_e32 v45, v40, v37
	v_sub_f32_e32 v40, v40, v45
	v_sub_f32_e32 v37, v40, v37
	v_sub_f32_e32 v41, v41, v43
	v_add_f32_e32 v34, v34, v37
	v_add_f32_e32 v34, v41, v34
	v_add_f32_e32 v34, v45, v34
	v_mul_f32_e32 v34, v39, v34
	v_add_f32_e32 v34, v35, v34
	v_add_f32_e32 v35, v42, v34
	v_mul_f32_e32 v37, v35, v35
	v_fmamk_f32 v41, v37, 0x3e9b6dac, v204
	v_sub_f32_e32 v39, v35, v42
	v_ldexp_f32 v40, v35, 1
	v_mul_f32_e32 v35, v35, v37
	v_fmaak_f32 v37, v37, v41, 0x3f2aaada
	v_mul_f32_e32 v35, v35, v37
	v_add_f32_e32 v37, v40, v35
	v_sub_f32_e32 v34, v34, v39
	v_sub_f32_e32 v39, v37, v40
	v_ldexp_f32 v34, v34, 1
	v_sub_f32_e32 v35, v35, v39
	v_add_f32_e32 v34, v34, v35
	v_add_f32_e32 v35, v37, v34
	v_sub_f32_e32 v37, v35, v37
	v_add_f32_e32 v39, v44, v35
	v_sub_f32_e32 v34, v34, v37
	v_sub_f32_e32 v37, v39, v44
	v_sub_f32_e32 v40, v39, v37
	v_sub_f32_e32 v35, v35, v37
	v_add_f32_e32 v37, v36, v34
	v_sub_f32_e32 v40, v44, v40
	v_add_f32_e32 v35, v35, v40
	v_sub_f32_e32 v40, v37, v36
	v_sub_f32_e32 v41, v37, v40
	v_sub_f32_e32 v36, v36, v41
	v_sub_f32_e32 v34, v34, v40
	v_add_f32_e32 v35, v37, v35
	v_add_f32_e32 v34, v34, v36
	v_add_f32_e32 v36, v39, v35
	v_sub_f32_e32 v37, v36, v39
	v_sub_f32_e32 v35, v35, v37
	v_add_f32_e32 v34, v34, v35
	v_add_f32_e32 v34, v36, v34
	v_cmp_neq_f32_e32 vcc, s79, v38
	s_nop 1
	v_cndmask_b32_e32 v34, v211, v34, vcc
	v_cmp_ngt_f32_e32 vcc, -1.0, v38
	s_nop 1
	v_cndmask_b32_e32 v39, v212, v34, vcc
	ds_read_b128 v[34:37], v25 offset:27712
	v_cmp_neq_f32_e32 vcc, -1.0, v38
	s_nop 1
	v_cndmask_b32_e32 v39, v213, v39, vcc
	v_cmp_lt_f32_e64 vcc, |v38|, s2
	s_nop 1
	v_cndmask_b32_e32 v42, v39, v38, vcc
	ds_read_b128 v[38:41], v25 offset:27728
	s_waitcnt lgkmcnt(1)
	v_fma_f32 v43, v29, v34, v26
	v_fmac_f32_e32 v43, v30, v35
	v_fmac_f32_e32 v43, v31, v36
	v_fmac_f32_e32 v43, v32, v37
	ds_read_b128 v[34:37], v25 offset:27744
	s_waitcnt lgkmcnt(1)
	v_fmac_f32_e32 v43, v28, v38
	v_fmac_f32_e32 v43, v27, v39
	v_pk_mul_f32 v[38:39], v[12:13], v[40:41]
	v_sub_f32_e32 v33, v33, v42
	v_add_f32_e32 v38, v43, v38
	v_add_f32_e32 v43, v38, v39
	ds_read_b128 v[38:41], v25 offset:27760
	s_waitcnt lgkmcnt(1)
	v_pk_mul_f32 v[34:35], v[6:7], v[34:35]
	v_fma_f32 v33, v33, s4, 0
	v_add_f32_e32 v34, v43, v34
	v_add_f32_e32 v43, v34, v35
	v_pk_mul_f32 v[34:35], v[4:5], v[36:37]
	s_nop 0
	v_add_f32_e32 v34, v43, v34
	v_add_f32_e32 v36, v34, v35
	s_waitcnt lgkmcnt(0)
	v_pk_mul_f32 v[34:35], v[8:9], v[38:39]
	s_nop 0
	v_add_f32_e32 v34, v36, v34
	v_add_f32_e32 v36, v34, v35
	v_pk_mul_f32 v[34:35], v[10:11], v[40:41]
	s_nop 0
	v_add_f32_e32 v34, v36, v34
	v_add_f32_e32 v34, v34, v35
	v_mul_f32_e64 v35, |v34|, s90
	v_exp_f32_e32 v38, v35
	v_min_f32_e32 v42, 0, v34
	v_add_f32_e32 v36, 1.0, v38
	v_add_f32_e32 v34, -1.0, v36
	v_sub_f32_e32 v35, v34, v36
	v_add_f32_e32 v35, 1.0, v35
	v_sub_f32_e32 v34, v38, v34
	v_add_f32_e32 v37, v34, v35
	v_frexp_mant_f32_e32 v39, v36
	v_cvt_f64_f32_e32 v[34:35], v36
	v_frexp_exp_i32_f64_e32 v34, v[34:35]
	v_cmp_gt_f32_e32 vcc, s36, v39
	s_nop 1
	v_subbrev_co_u32_e32 v34, vcc, 0, v34, vcc
	v_sub_u32_e32 v35, 0, v34
	v_ldexp_f32 v36, v36, v35
	v_ldexp_f32 v35, v37, v35
	v_add_f32_e32 v37, -1.0, v36
	v_add_f32_e32 v41, 1.0, v36
	v_add_f32_e32 v39, 1.0, v37
	v_add_f32_e32 v43, -1.0, v41
	v_sub_f32_e32 v39, v36, v39
	v_sub_f32_e32 v36, v36, v43
	v_add_f32_e32 v39, v35, v39
	v_add_f32_e32 v35, v35, v36
	v_add_f32_e32 v36, v41, v35
	v_rcp_f32_e32 v43, v36
	v_add_f32_e32 v40, v37, v39
	v_sub_f32_e32 v37, v40, v37
	v_sub_f32_e32 v37, v39, v37
	v_sub_f32_e32 v39, v36, v41
	v_sub_f32_e32 v35, v35, v39
	v_mul_f32_e32 v39, v40, v43
	v_mul_f32_e32 v41, v36, v39
	v_fma_f32 v44, v39, v36, -v41
	v_fmac_f32_e32 v44, v39, v35
	v_add_f32_e32 v45, v41, v44
	v_sub_f32_e32 v46, v40, v45
	v_sub_f32_e32 v40, v40, v46
	v_sub_f32_e32 v41, v45, v41
	v_sub_f32_e32 v40, v40, v45
	v_add_f32_e32 v37, v37, v40
	v_sub_f32_e32 v40, v41, v44
	v_add_f32_e32 v37, v40, v37
	v_add_f32_e32 v40, v46, v37
	v_mul_f32_e32 v41, v43, v40
	v_mul_f32_e32 v44, v36, v41
	v_fma_f32 v36, v41, v36, -v44
	v_fmac_f32_e32 v36, v41, v35
	v_sub_f32_e32 v35, v46, v40
	v_add_f32_e32 v35, v37, v35
	v_add_f32_e32 v37, v44, v36
	v_sub_f32_e32 v45, v40, v37
	v_sub_f32_e32 v40, v40, v45
	v_sub_f32_e32 v44, v37, v44
	v_sub_f32_e32 v37, v40, v37
	v_add_f32_e32 v35, v35, v37
	v_sub_f32_e32 v36, v44, v36
	v_cvt_f32_i32_e32 v34, v34
	v_add_f32_e32 v35, v36, v35
	v_add_f32_e32 v36, v39, v41
	v_add_f32_e32 v35, v45, v35
	v_sub_f32_e32 v37, v36, v39
	v_mul_f32_e32 v35, v43, v35
	v_sub_f32_e32 v37, v41, v37
	v_add_f32_e32 v35, v37, v35
	v_mul_f32_e32 v41, 0x3f317218, v34
	v_add_f32_e32 v37, v36, v35
	v_fma_f32 v43, v34, s78, -v41
	v_mul_f32_e32 v39, v37, v37
	v_fmac_f32_e32 v43, 0xb102e308, v34
	v_sub_f32_e32 v34, v37, v36
	v_fmamk_f32 v40, v39, 0x3e9b6dac, v204
	v_sub_f32_e32 v34, v35, v34
	v_add_f32_e32 v35, v41, v43
	v_fmaak_f32 v40, v39, v40, 0x3f2aaada
	v_sub_f32_e32 v36, v35, v41
	v_ldexp_f32 v41, v37, 1
	v_mul_f32_e32 v37, v37, v39
	v_mul_f32_e32 v37, v37, v40
	v_add_f32_e32 v39, v41, v37
	v_sub_f32_e32 v40, v39, v41
	v_ldexp_f32 v34, v34, 1
	v_sub_f32_e32 v37, v37, v40
	v_add_f32_e32 v34, v34, v37
	v_add_f32_e32 v37, v39, v34
	v_sub_f32_e32 v39, v37, v39
	v_sub_f32_e32 v34, v34, v39
	v_add_f32_e32 v39, v35, v37
	v_sub_f32_e32 v40, v39, v35
	v_sub_f32_e32 v41, v39, v40
	v_sub_f32_e32 v36, v43, v36
	v_sub_f32_e32 v35, v35, v41
	v_sub_f32_e32 v37, v37, v40
	v_add_f32_e32 v35, v37, v35
	v_add_f32_e32 v37, v36, v34
	v_sub_f32_e32 v40, v37, v36
	v_sub_f32_e32 v41, v37, v40
	v_sub_f32_e32 v36, v36, v41
	v_sub_f32_e32 v34, v34, v40
	v_add_f32_e32 v35, v37, v35
	v_add_f32_e32 v34, v34, v36
	v_add_f32_e32 v36, v39, v35
	v_sub_f32_e32 v37, v36, v39
	v_sub_f32_e32 v35, v35, v37
	v_add_f32_e32 v34, v34, v35
	v_add_f32_e32 v34, v36, v34
	v_cmp_neq_f32_e32 vcc, s79, v38
	s_nop 1
	v_cndmask_b32_e32 v34, v211, v34, vcc
	v_cmp_ngt_f32_e32 vcc, -1.0, v38
	s_nop 1
	v_cndmask_b32_e32 v39, v212, v34, vcc
	ds_read_b128 v[34:37], v25 offset:27776
	v_cmp_neq_f32_e32 vcc, -1.0, v38
	s_nop 1
	v_cndmask_b32_e32 v39, v213, v39, vcc
	v_cmp_lt_f32_e64 vcc, |v38|, s2
	s_nop 1
	v_cndmask_b32_e32 v43, v39, v38, vcc
	ds_read_b128 v[38:41], v25 offset:27792
	s_waitcnt lgkmcnt(1)
	v_fma_f32 v44, v29, v34, v26
	v_fmac_f32_e32 v44, v30, v35
	v_fmac_f32_e32 v44, v31, v36
	v_fmac_f32_e32 v44, v32, v37
	ds_read_b128 v[34:37], v25 offset:27808
	s_waitcnt lgkmcnt(1)
	v_fmac_f32_e32 v44, v28, v38
	v_fmac_f32_e32 v44, v27, v39
	v_pk_mul_f32 v[38:39], v[12:13], v[40:41]
	s_nop 0
	v_add_f32_e32 v38, v44, v38
	v_add_f32_e32 v44, v38, v39
	ds_read_b128 v[38:41], v25 offset:27824
	s_waitcnt lgkmcnt(1)
	v_pk_mul_f32 v[34:35], v[6:7], v[34:35]
	s_nop 0
	v_add_f32_e32 v34, v44, v34
	v_add_f32_e32 v44, v34, v35
	v_pk_mul_f32 v[34:35], v[4:5], v[36:37]
	s_nop 0
	v_add_f32_e32 v34, v44, v34
	v_add_f32_e32 v36, v34, v35
	s_waitcnt lgkmcnt(0)
	v_pk_mul_f32 v[34:35], v[8:9], v[38:39]
	s_nop 0
	v_add_f32_e32 v34, v36, v34
	v_add_f32_e32 v36, v34, v35
	v_pk_mul_f32 v[34:35], v[10:11], v[40:41]
	s_nop 0
	v_add_f32_e32 v34, v36, v34
	v_add_f32_e32 v35, v34, v35
	v_mul_f32_e64 v34, |v35|, s90
	v_exp_f32_e32 v40, v34
	v_sub_f32_e32 v34, v42, v43
	v_min_f32_e32 v35, 0, v35
	v_fmamk_f32 v34, v34, 0x3d800000, v33
	v_add_f32_e32 v38, 1.0, v40
	v_add_f32_e32 v36, -1.0, v38
	v_sub_f32_e32 v37, v36, v38
	v_add_f32_e32 v37, 1.0, v37
	v_sub_f32_e32 v36, v40, v36
	v_add_f32_e32 v39, v36, v37
	v_frexp_mant_f32_e32 v41, v38
	v_cvt_f64_f32_e32 v[36:37], v38
	v_frexp_exp_i32_f64_e32 v36, v[36:37]
	v_cmp_gt_f32_e32 vcc, s36, v41
	s_nop 1
	v_subbrev_co_u32_e32 v36, vcc, 0, v36, vcc
	v_sub_u32_e32 v37, 0, v36
	v_ldexp_f32 v38, v38, v37
	v_ldexp_f32 v37, v39, v37
	v_add_f32_e32 v39, -1.0, v38
	v_add_f32_e32 v43, 1.0, v38
	v_add_f32_e32 v41, 1.0, v39
	v_add_f32_e32 v44, -1.0, v43
	v_sub_f32_e32 v41, v38, v41
	v_sub_f32_e32 v38, v38, v44
	v_add_f32_e32 v41, v37, v41
	v_add_f32_e32 v37, v37, v38
	v_add_f32_e32 v38, v43, v37
	v_rcp_f32_e32 v44, v38
	v_add_f32_e32 v42, v39, v41
	v_sub_f32_e32 v39, v42, v39
	v_sub_f32_e32 v39, v41, v39
	v_sub_f32_e32 v41, v38, v43
	v_sub_f32_e32 v37, v37, v41
	v_mul_f32_e32 v41, v42, v44
	v_mul_f32_e32 v43, v38, v41
	v_fma_f32 v45, v41, v38, -v43
	v_fmac_f32_e32 v45, v41, v37
	v_add_f32_e32 v46, v43, v45
	v_sub_f32_e32 v47, v42, v46
	v_sub_f32_e32 v42, v42, v47
	v_sub_f32_e32 v43, v46, v43
	v_sub_f32_e32 v42, v42, v46
	v_add_f32_e32 v39, v39, v42
	v_sub_f32_e32 v42, v43, v45
	v_add_f32_e32 v39, v42, v39
	v_add_f32_e32 v42, v47, v39
	v_mul_f32_e32 v43, v44, v42
	v_mul_f32_e32 v45, v38, v43
	v_fma_f32 v38, v43, v38, -v45
	v_fmac_f32_e32 v38, v43, v37
	v_sub_f32_e32 v37, v47, v42
	v_add_f32_e32 v37, v39, v37
	v_add_f32_e32 v39, v45, v38
	v_sub_f32_e32 v46, v42, v39
	v_sub_f32_e32 v42, v42, v46
	v_sub_f32_e32 v45, v39, v45
	v_sub_f32_e32 v39, v42, v39
	v_add_f32_e32 v37, v37, v39
	v_sub_f32_e32 v38, v45, v38
	v_cvt_f32_i32_e32 v36, v36
	v_add_f32_e32 v37, v38, v37
	v_add_f32_e32 v38, v41, v43
	v_add_f32_e32 v37, v46, v37
	v_sub_f32_e32 v39, v38, v41
	v_mul_f32_e32 v37, v44, v37
	v_sub_f32_e32 v39, v43, v39
	v_add_f32_e32 v37, v39, v37
	v_mul_f32_e32 v43, 0x3f317218, v36
	v_add_f32_e32 v39, v38, v37
	v_fma_f32 v44, v36, s78, -v43
	v_mul_f32_e32 v41, v39, v39
	v_fmac_f32_e32 v44, 0xb102e308, v36
	v_sub_f32_e32 v36, v39, v38
	v_fmamk_f32 v42, v41, 0x3e9b6dac, v204
	v_sub_f32_e32 v36, v37, v36
	v_add_f32_e32 v37, v43, v44
	v_fmaak_f32 v42, v41, v42, 0x3f2aaada
	v_sub_f32_e32 v38, v37, v43
	v_ldexp_f32 v43, v39, 1
	v_mul_f32_e32 v39, v39, v41
	v_mul_f32_e32 v39, v39, v42
	v_add_f32_e32 v41, v43, v39
	v_sub_f32_e32 v42, v41, v43
	v_ldexp_f32 v36, v36, 1
	v_sub_f32_e32 v39, v39, v42
	v_add_f32_e32 v36, v36, v39
	v_add_f32_e32 v39, v41, v36
	v_sub_f32_e32 v41, v39, v41
	v_sub_f32_e32 v36, v36, v41
	v_add_f32_e32 v41, v37, v39
	v_sub_f32_e32 v42, v41, v37
	v_sub_f32_e32 v43, v41, v42
	v_sub_f32_e32 v38, v44, v38
	v_sub_f32_e32 v37, v37, v43
	v_sub_f32_e32 v39, v39, v42
	v_add_f32_e32 v37, v39, v37
	v_add_f32_e32 v39, v38, v36
	v_sub_f32_e32 v42, v39, v38
	v_sub_f32_e32 v43, v39, v42
	v_sub_f32_e32 v38, v38, v43
	v_sub_f32_e32 v36, v36, v42
	v_add_f32_e32 v37, v39, v37
	v_add_f32_e32 v36, v36, v38
	v_add_f32_e32 v38, v41, v37
	v_sub_f32_e32 v39, v38, v41
	v_sub_f32_e32 v37, v37, v39
	v_add_f32_e32 v36, v36, v37
	v_add_f32_e32 v36, v38, v36
	v_cmp_neq_f32_e32 vcc, s79, v40
	s_nop 1
	v_cndmask_b32_e32 v36, v211, v36, vcc
	v_cmp_ngt_f32_e32 vcc, -1.0, v40
	s_nop 1
	v_cndmask_b32_e32 v41, v212, v36, vcc
	ds_read_b128 v[36:39], v25 offset:27840
	v_cmp_neq_f32_e32 vcc, -1.0, v40
	s_nop 1
	v_cndmask_b32_e32 v41, v213, v41, vcc
	v_cmp_lt_f32_e64 vcc, |v40|, s2
	s_nop 1
	v_cndmask_b32_e32 v44, v41, v40, vcc
	ds_read_b128 v[40:43], v25 offset:27856
	s_waitcnt lgkmcnt(1)
	v_fma_f32 v45, v29, v36, v26
	v_fmac_f32_e32 v45, v30, v37
	v_fmac_f32_e32 v45, v31, v38
	v_fmac_f32_e32 v45, v32, v39
	ds_read_b128 v[36:39], v25 offset:27872
	s_waitcnt lgkmcnt(1)
	v_fmac_f32_e32 v45, v28, v40
	v_fmac_f32_e32 v45, v27, v41
	v_pk_mul_f32 v[40:41], v[12:13], v[42:43]
	v_sub_f32_e32 v35, v35, v44
	v_add_f32_e32 v40, v45, v40
	v_add_f32_e32 v45, v40, v41
	ds_read_b128 v[40:43], v25 offset:27888
	s_waitcnt lgkmcnt(1)
	v_pk_mul_f32 v[36:37], v[6:7], v[36:37]
	v_fmamk_f32 v35, v35, 0x3d800000, v34
	v_add_f32_e32 v36, v45, v36
	v_add_f32_e32 v45, v36, v37
	v_pk_mul_f32 v[36:37], v[4:5], v[38:39]
	s_nop 0
	v_add_f32_e32 v36, v45, v36
	v_add_f32_e32 v38, v36, v37
	s_waitcnt lgkmcnt(0)
	v_pk_mul_f32 v[36:37], v[8:9], v[40:41]
	s_nop 0
	v_add_f32_e32 v36, v38, v36
	v_add_f32_e32 v38, v36, v37
	v_pk_mul_f32 v[36:37], v[10:11], v[42:43]
	s_nop 0
	v_add_f32_e32 v36, v38, v36
	v_add_f32_e32 v36, v36, v37
	v_mul_f32_e64 v37, |v36|, s90
	v_exp_f32_e32 v40, v37
	v_min_f32_e32 v44, 0, v36
	v_add_f32_e32 v38, 1.0, v40
	v_add_f32_e32 v36, -1.0, v38
	v_sub_f32_e32 v37, v36, v38
	v_add_f32_e32 v37, 1.0, v37
	v_sub_f32_e32 v36, v40, v36
	v_add_f32_e32 v39, v36, v37
	v_frexp_mant_f32_e32 v41, v38
	v_cvt_f64_f32_e32 v[36:37], v38
	v_frexp_exp_i32_f64_e32 v36, v[36:37]
	v_cmp_gt_f32_e32 vcc, s36, v41
	s_nop 1
	v_subbrev_co_u32_e32 v36, vcc, 0, v36, vcc
	v_sub_u32_e32 v37, 0, v36
	v_ldexp_f32 v38, v38, v37
	v_ldexp_f32 v37, v39, v37
	v_add_f32_e32 v39, -1.0, v38
	v_add_f32_e32 v43, 1.0, v38
	v_add_f32_e32 v41, 1.0, v39
	v_add_f32_e32 v45, -1.0, v43
	v_sub_f32_e32 v41, v38, v41
	v_sub_f32_e32 v38, v38, v45
	v_add_f32_e32 v41, v37, v41
	v_add_f32_e32 v37, v37, v38
	v_add_f32_e32 v38, v43, v37
	v_rcp_f32_e32 v45, v38
	v_add_f32_e32 v42, v39, v41
	v_sub_f32_e32 v39, v42, v39
	v_sub_f32_e32 v39, v41, v39
	v_sub_f32_e32 v41, v38, v43
	v_sub_f32_e32 v37, v37, v41
	v_mul_f32_e32 v41, v42, v45
	v_mul_f32_e32 v43, v38, v41
	v_fma_f32 v46, v41, v38, -v43
	v_fmac_f32_e32 v46, v41, v37
	v_add_f32_e32 v47, v43, v46
	v_sub_f32_e32 v48, v42, v47
	v_sub_f32_e32 v42, v42, v48
	v_sub_f32_e32 v43, v47, v43
	v_sub_f32_e32 v42, v42, v47
	v_add_f32_e32 v39, v39, v42
	v_sub_f32_e32 v42, v43, v46
	v_add_f32_e32 v39, v42, v39
	v_add_f32_e32 v42, v48, v39
	v_mul_f32_e32 v43, v45, v42
	v_mul_f32_e32 v46, v38, v43
	v_fma_f32 v38, v43, v38, -v46
	v_fmac_f32_e32 v38, v43, v37
	v_sub_f32_e32 v37, v48, v42
	v_add_f32_e32 v37, v39, v37
	v_add_f32_e32 v39, v46, v38
	v_sub_f32_e32 v47, v42, v39
	v_sub_f32_e32 v42, v42, v47
	v_sub_f32_e32 v46, v39, v46
	v_sub_f32_e32 v39, v42, v39
	v_add_f32_e32 v37, v37, v39
	v_sub_f32_e32 v38, v46, v38
	v_cvt_f32_i32_e32 v36, v36
	v_add_f32_e32 v37, v38, v37
	v_add_f32_e32 v38, v41, v43
	v_add_f32_e32 v37, v47, v37
	v_sub_f32_e32 v39, v38, v41
	v_mul_f32_e32 v37, v45, v37
	v_sub_f32_e32 v39, v43, v39
	v_add_f32_e32 v37, v39, v37
	v_mul_f32_e32 v43, 0x3f317218, v36
	v_add_f32_e32 v39, v38, v37
	v_fma_f32 v45, v36, s78, -v43
	v_mul_f32_e32 v41, v39, v39
	v_fmac_f32_e32 v45, 0xb102e308, v36
	v_sub_f32_e32 v36, v39, v38
	v_fmamk_f32 v42, v41, 0x3e9b6dac, v204
	v_sub_f32_e32 v36, v37, v36
	v_add_f32_e32 v37, v43, v45
	v_fmaak_f32 v42, v41, v42, 0x3f2aaada
	v_sub_f32_e32 v38, v37, v43
	v_ldexp_f32 v43, v39, 1
	v_mul_f32_e32 v39, v39, v41
	v_mul_f32_e32 v39, v39, v42
	v_add_f32_e32 v41, v43, v39
	v_sub_f32_e32 v42, v41, v43
	v_ldexp_f32 v36, v36, 1
	v_sub_f32_e32 v39, v39, v42
	v_add_f32_e32 v36, v36, v39
	v_add_f32_e32 v39, v41, v36
	v_sub_f32_e32 v41, v39, v41
	v_sub_f32_e32 v36, v36, v41
	v_add_f32_e32 v41, v37, v39
	v_sub_f32_e32 v42, v41, v37
	v_sub_f32_e32 v43, v41, v42
	v_sub_f32_e32 v38, v45, v38
	v_sub_f32_e32 v37, v37, v43
	v_sub_f32_e32 v39, v39, v42
	v_add_f32_e32 v37, v39, v37
	v_add_f32_e32 v39, v38, v36
	v_sub_f32_e32 v42, v39, v38
	v_sub_f32_e32 v43, v39, v42
	v_sub_f32_e32 v38, v38, v43
	v_sub_f32_e32 v36, v36, v42
	v_add_f32_e32 v37, v39, v37
	v_add_f32_e32 v36, v36, v38
	v_add_f32_e32 v38, v41, v37
	v_sub_f32_e32 v39, v38, v41
	v_sub_f32_e32 v37, v37, v39
	v_add_f32_e32 v36, v36, v37
	v_add_f32_e32 v36, v38, v36
	v_cmp_neq_f32_e32 vcc, s79, v40
	s_nop 1
	v_cndmask_b32_e32 v36, v211, v36, vcc
	v_cmp_ngt_f32_e32 vcc, -1.0, v40
	s_nop 1
	v_cndmask_b32_e32 v41, v212, v36, vcc
	ds_read_b128 v[36:39], v25 offset:27904
	v_cmp_neq_f32_e32 vcc, -1.0, v40
	s_nop 1
	v_cndmask_b32_e32 v41, v213, v41, vcc
	v_cmp_lt_f32_e64 vcc, |v40|, s2
	s_nop 1
	v_cndmask_b32_e32 v45, v41, v40, vcc
	ds_read_b128 v[40:43], v25 offset:27920
	s_waitcnt lgkmcnt(1)
	v_fma_f32 v46, v29, v36, v26
	v_fmac_f32_e32 v46, v30, v37
	v_fmac_f32_e32 v46, v31, v38
	v_fmac_f32_e32 v46, v32, v39
	ds_read_b128 v[36:39], v25 offset:27936
	s_waitcnt lgkmcnt(1)
	v_fmac_f32_e32 v46, v28, v40
	v_fmac_f32_e32 v46, v27, v41
	v_pk_mul_f32 v[40:41], v[12:13], v[42:43]
	s_nop 0
	v_add_f32_e32 v40, v46, v40
	v_add_f32_e32 v46, v40, v41
	ds_read_b128 v[40:43], v25 offset:27952
	s_waitcnt lgkmcnt(1)
	v_pk_mul_f32 v[36:37], v[6:7], v[36:37]
	s_nop 0
	v_add_f32_e32 v36, v46, v36
	v_add_f32_e32 v46, v36, v37
	v_pk_mul_f32 v[36:37], v[4:5], v[38:39]
	s_nop 0
	v_add_f32_e32 v36, v46, v36
	v_add_f32_e32 v38, v36, v37
	s_waitcnt lgkmcnt(0)
	v_pk_mul_f32 v[36:37], v[8:9], v[40:41]
	s_nop 0
	v_add_f32_e32 v36, v38, v36
	v_add_f32_e32 v38, v36, v37
	v_pk_mul_f32 v[36:37], v[10:11], v[42:43]
	s_nop 0
	v_add_f32_e32 v36, v38, v36
	v_add_f32_e32 v37, v36, v37
	v_mul_f32_e64 v36, |v37|, s90
	v_exp_f32_e32 v42, v36
	v_sub_f32_e32 v36, v44, v45
	v_min_f32_e32 v37, 0, v37
	v_fmamk_f32 v36, v36, 0x3d800000, v35
	v_add_f32_e32 v40, 1.0, v42
	v_add_f32_e32 v38, -1.0, v40
	v_sub_f32_e32 v39, v38, v40
	v_add_f32_e32 v39, 1.0, v39
	v_sub_f32_e32 v38, v42, v38
	v_add_f32_e32 v41, v38, v39
	v_frexp_mant_f32_e32 v43, v40
	v_cvt_f64_f32_e32 v[38:39], v40
	v_frexp_exp_i32_f64_e32 v38, v[38:39]
	v_cmp_gt_f32_e32 vcc, s36, v43
	s_nop 1
	v_subbrev_co_u32_e32 v38, vcc, 0, v38, vcc
	v_sub_u32_e32 v39, 0, v38
	v_ldexp_f32 v40, v40, v39
	v_ldexp_f32 v39, v41, v39
	v_add_f32_e32 v41, -1.0, v40
	v_add_f32_e32 v45, 1.0, v40
	v_add_f32_e32 v43, 1.0, v41
	v_add_f32_e32 v46, -1.0, v45
	v_sub_f32_e32 v43, v40, v43
	v_sub_f32_e32 v40, v40, v46
	v_add_f32_e32 v43, v39, v43
	v_add_f32_e32 v39, v39, v40
	v_add_f32_e32 v40, v45, v39
	v_rcp_f32_e32 v46, v40
	v_add_f32_e32 v44, v41, v43
	v_sub_f32_e32 v41, v44, v41
	v_sub_f32_e32 v41, v43, v41
	v_sub_f32_e32 v43, v40, v45
	v_sub_f32_e32 v39, v39, v43
	v_mul_f32_e32 v43, v44, v46
	v_mul_f32_e32 v45, v40, v43
	v_fma_f32 v47, v43, v40, -v45
	v_fmac_f32_e32 v47, v43, v39
	v_add_f32_e32 v48, v45, v47
	v_sub_f32_e32 v49, v44, v48
	v_sub_f32_e32 v44, v44, v49
	v_sub_f32_e32 v45, v48, v45
	v_sub_f32_e32 v44, v44, v48
	v_add_f32_e32 v41, v41, v44
	v_sub_f32_e32 v44, v45, v47
	v_add_f32_e32 v41, v44, v41
	v_add_f32_e32 v44, v49, v41
	v_mul_f32_e32 v45, v46, v44
	v_mul_f32_e32 v47, v40, v45
	v_fma_f32 v40, v45, v40, -v47
	v_fmac_f32_e32 v40, v45, v39
	v_sub_f32_e32 v39, v49, v44
	v_add_f32_e32 v39, v41, v39
	v_add_f32_e32 v41, v47, v40
	v_sub_f32_e32 v48, v44, v41
	v_sub_f32_e32 v44, v44, v48
	v_sub_f32_e32 v47, v41, v47
	v_sub_f32_e32 v41, v44, v41
	v_add_f32_e32 v39, v39, v41
	v_sub_f32_e32 v40, v47, v40
	v_cvt_f32_i32_e32 v38, v38
	v_add_f32_e32 v39, v40, v39
	v_add_f32_e32 v40, v43, v45
	v_add_f32_e32 v39, v48, v39
	v_sub_f32_e32 v41, v40, v43
	v_mul_f32_e32 v39, v46, v39
	v_sub_f32_e32 v41, v45, v41
	v_add_f32_e32 v39, v41, v39
	v_mul_f32_e32 v45, 0x3f317218, v38
	v_add_f32_e32 v41, v40, v39
	v_fma_f32 v46, v38, s78, -v45
	v_mul_f32_e32 v43, v41, v41
	v_fmac_f32_e32 v46, 0xb102e308, v38
	v_sub_f32_e32 v38, v41, v40
	v_fmamk_f32 v44, v43, 0x3e9b6dac, v204
	v_sub_f32_e32 v38, v39, v38
	v_add_f32_e32 v39, v45, v46
	v_fmaak_f32 v44, v43, v44, 0x3f2aaada
	v_sub_f32_e32 v40, v39, v45
	v_ldexp_f32 v45, v41, 1
	v_mul_f32_e32 v41, v41, v43
	v_mul_f32_e32 v41, v41, v44
	v_add_f32_e32 v43, v45, v41
	v_sub_f32_e32 v44, v43, v45
	v_ldexp_f32 v38, v38, 1
	v_sub_f32_e32 v41, v41, v44
	v_add_f32_e32 v38, v38, v41
	v_add_f32_e32 v41, v43, v38
	v_sub_f32_e32 v43, v41, v43
	v_sub_f32_e32 v38, v38, v43
	v_add_f32_e32 v43, v39, v41
	v_sub_f32_e32 v44, v43, v39
	v_sub_f32_e32 v45, v43, v44
	v_sub_f32_e32 v40, v46, v40
	v_sub_f32_e32 v39, v39, v45
	v_sub_f32_e32 v41, v41, v44
	v_add_f32_e32 v39, v41, v39
	v_add_f32_e32 v41, v40, v38
	v_sub_f32_e32 v44, v41, v40
	v_sub_f32_e32 v45, v41, v44
	v_sub_f32_e32 v40, v40, v45
	v_sub_f32_e32 v38, v38, v44
	v_add_f32_e32 v39, v41, v39
	v_add_f32_e32 v38, v38, v40
	v_add_f32_e32 v40, v43, v39
	v_sub_f32_e32 v41, v40, v43
	v_sub_f32_e32 v39, v39, v41
	v_add_f32_e32 v38, v38, v39
	v_add_f32_e32 v38, v40, v38
	v_cmp_neq_f32_e32 vcc, s79, v42
	s_nop 1
	v_cndmask_b32_e32 v38, v211, v38, vcc
	v_cmp_ngt_f32_e32 vcc, -1.0, v42
	s_nop 1
	v_cndmask_b32_e32 v43, v212, v38, vcc
	ds_read_b128 v[38:41], v25 offset:27968
	v_cmp_neq_f32_e32 vcc, -1.0, v42
	s_nop 1
	v_cndmask_b32_e32 v43, v213, v43, vcc
	v_cmp_lt_f32_e64 vcc, |v42|, s2
	s_nop 1
	v_cndmask_b32_e32 v46, v43, v42, vcc
	ds_read_b128 v[42:45], v25 offset:27984
	s_waitcnt lgkmcnt(1)
	v_fma_f32 v47, v29, v38, v26
	v_fmac_f32_e32 v47, v30, v39
	v_fmac_f32_e32 v47, v31, v40
	v_fmac_f32_e32 v47, v32, v41
	ds_read_b128 v[38:41], v25 offset:28000
	s_waitcnt lgkmcnt(1)
	v_fmac_f32_e32 v47, v28, v42
	v_fmac_f32_e32 v47, v27, v43
	v_pk_mul_f32 v[42:43], v[12:13], v[44:45]
	v_sub_f32_e32 v37, v37, v46
	v_add_f32_e32 v42, v47, v42
	v_add_f32_e32 v47, v42, v43
	ds_read_b128 v[42:45], v25 offset:28016
	s_waitcnt lgkmcnt(1)
	v_pk_mul_f32 v[38:39], v[6:7], v[38:39]
	v_fmamk_f32 v37, v37, 0x3d800000, v36
	v_add_f32_e32 v38, v47, v38
	v_add_f32_e32 v47, v38, v39
	v_pk_mul_f32 v[38:39], v[4:5], v[40:41]
	s_nop 0
	v_add_f32_e32 v38, v47, v38
	v_add_f32_e32 v40, v38, v39
	s_waitcnt lgkmcnt(0)
	v_pk_mul_f32 v[38:39], v[8:9], v[42:43]
	s_nop 0
	v_add_f32_e32 v38, v40, v38
	v_add_f32_e32 v40, v38, v39
	v_pk_mul_f32 v[38:39], v[10:11], v[44:45]
	s_nop 0
	v_add_f32_e32 v38, v40, v38
	v_add_f32_e32 v38, v38, v39
	v_mul_f32_e64 v39, |v38|, s90
	v_exp_f32_e32 v52, v39
	v_min_f32_e32 v53, 0, v38
	v_add_f32_e32 v40, 1.0, v52
	v_add_f32_e32 v38, -1.0, v40
	v_sub_f32_e32 v39, v38, v40
	v_add_f32_e32 v39, 1.0, v39
	v_sub_f32_e32 v38, v52, v38
	v_add_f32_e32 v41, v38, v39
	v_frexp_mant_f32_e32 v42, v40
	v_cvt_f64_f32_e32 v[38:39], v40
	v_frexp_exp_i32_f64_e32 v38, v[38:39]
	v_cmp_gt_f32_e32 vcc, s36, v42
	s_nop 1
	v_subbrev_co_u32_e32 v46, vcc, 0, v38, vcc
	v_sub_u32_e32 v38, 0, v46
	v_ldexp_f32 v39, v40, v38
	v_add_f32_e32 v40, -1.0, v39
	v_add_f32_e32 v42, 1.0, v39
	v_ldexp_f32 v38, v41, v38
	v_add_f32_e32 v41, 1.0, v40
	v_add_f32_e32 v43, -1.0, v42
	v_sub_f32_e32 v41, v39, v41
	v_sub_f32_e32 v39, v39, v43
	v_add_f32_e32 v41, v38, v41
	v_add_f32_e32 v38, v38, v39
	v_add_f32_e32 v47, v42, v38
	v_rcp_f32_e32 v49, v47
	v_sub_f32_e32 v39, v47, v42
	v_sub_f32_e32 v48, v38, v39
	v_add_f32_e32 v39, v40, v41
	v_mul_f32_e32 v51, v39, v49
	v_sub_f32_e32 v38, v39, v40
	v_mul_f32_e32 v40, v47, v51
	v_fma_f32 v42, v51, v47, -v40
	v_fmac_f32_e32 v42, v51, v48
	v_sub_f32_e32 v50, v41, v38
	v_add_f32_e32 v38, v40, v42
	v_sub_f32_e32 v41, v39, v38
	v_pk_add_f32 v[44:45], v[38:39], v[40:41] neg_lo:[0,1] neg_hi:[0,1]
	v_mov_b32_e32 v43, v38
	v_pk_add_f32 v[38:39], v[44:45], v[42:43] neg_lo:[0,1] neg_hi:[0,1]
	v_cmp_neq_f32_e32 vcc, s79, v52
	v_add_f32_e32 v39, v50, v39
	v_add_f32_e32 v38, v38, v39
	v_add_f32_e32 v39, v41, v38
	v_mul_f32_e32 v50, v49, v39
	v_mul_f32_e32 v40, v47, v50
	v_fma_f32 v42, v50, v47, -v40
	v_fmac_f32_e32 v42, v50, v48
	v_sub_f32_e32 v41, v41, v39
	v_add_f32_e32 v47, v38, v41
	v_add_f32_e32 v38, v40, v42
	v_sub_f32_e32 v41, v39, v38
	v_pk_add_f32 v[44:45], v[38:39], v[40:41] neg_lo:[0,1] neg_hi:[0,1]
	v_mov_b32_e32 v43, v38
	v_pk_add_f32 v[38:39], v[44:45], v[42:43] neg_lo:[0,1] neg_hi:[0,1]
	s_nop 0
	v_add_f32_e32 v39, v47, v39
	v_add_f32_e32 v38, v38, v39
	v_add_f32_e32 v39, v51, v50
	v_add_f32_e32 v38, v41, v38
	v_sub_f32_e32 v40, v39, v51
	v_mul_f32_e32 v38, v49, v38
	v_sub_f32_e32 v40, v50, v40
	v_add_f32_e32 v40, v40, v38
	v_add_f32_e32 v42, v39, v40
	v_mul_f32_e32 v43, v42, v42
	v_fmamk_f32 v38, v43, 0x3e9b6dac, v204
	v_fmaak_f32 v175, v43, v38, 0x3f2aaada
	v_cvt_f32_i32_e32 v38, v46
	v_sub_f32_e32 v39, v42, v39
	v_sub_f32_e32 v39, v40, v39
	v_ldexp_f32 v44, v39, 1
	v_mul_f32_e32 v39, v42, v43
	v_ldexp_f32 v41, v42, 1
	v_pk_mul_f32 v[42:43], v[38:39], v[174:175]
	s_nop 0
	v_fma_f32 v40, v38, s78, -v42
	v_fmac_f32_e32 v40, 0xb102e308, v38
	v_pk_add_f32 v[38:39], v[42:43], v[40:41]
	s_nop 0
	v_sub_f32_e32 v41, v39, v41
	v_sub_f32_e32 v41, v43, v41
	v_add_f32_e32 v45, v44, v41
	v_mov_b32_e32 v44, v42
	v_pk_add_f32 v[42:43], v[38:39], v[42:43] neg_lo:[0,1] neg_hi:[0,1]
	v_pk_add_f32 v[46:47], v[38:39], v[44:45]
	v_mov_b32_e32 v41, v38
	v_mov_b32_e32 v43, v47
	v_pk_add_f32 v[48:49], v[40:41], v[42:43] neg_lo:[0,1] neg_hi:[0,1]
	v_pk_add_f32 v[40:41], v[40:41], v[42:43]
	v_mov_b32_e32 v44, v45
	v_pk_add_f32 v[42:43], v[40:41], v[38:39] op_sel:[1,0] op_sel_hi:[0,1] neg_lo:[0,1] neg_hi:[0,1]
	v_pk_add_f32 v[50:51], v[46:47], v[42:43] op_sel_hi:[1,0] neg_lo:[0,1] neg_hi:[0,1]
	v_mov_b32_e32 v46, v47
	v_mov_b32_e32 v47, v41
	v_pk_mov_b32 v[42:43], v[38:39], v[42:43] op_sel:[1,0]
	v_mov_b32_e32 v45, v38
	v_pk_add_f32 v[42:43], v[46:47], v[42:43] neg_lo:[0,1] neg_hi:[0,1]
	v_mov_b32_e32 v50, v48
	v_pk_add_f32 v[38:39], v[44:45], v[42:43] neg_lo:[0,1] neg_hi:[0,1]
	v_mov_b32_e32 v49, v41
	v_pk_add_f32 v[42:43], v[50:51], v[38:39]
	s_nop 0
	v_pk_add_f32 v[44:45], v[42:43], v[42:43] op_sel:[0,1] op_sel_hi:[1,0]
	s_nop 0
	v_pk_add_f32 v[40:41], v[40:41], v[44:45] op_sel:[1,0] op_sel_hi:[0,1]
	v_mov_b32_e32 v43, v40
	v_pk_add_f32 v[46:47], v[42:43], v[48:49] neg_lo:[0,1] neg_hi:[0,1]
	v_mov_b32_e32 v39, v44
	v_sub_f32_e32 v41, v42, v46
	v_pk_add_f32 v[38:39], v[38:39], v[46:47] neg_lo:[0,1] neg_hi:[0,1]
	v_sub_f32_e32 v41, v48, v41
	v_add_f32_e32 v38, v38, v41
	v_add_f32_e32 v38, v38, v39
	v_add_f32_e32 v38, v40, v38
	v_cndmask_b32_e32 v38, v211, v38, vcc
	v_cmp_ngt_f32_e32 vcc, -1.0, v52
	s_nop 1
	v_cndmask_b32_e32 v42, v212, v38, vcc
	ds_read_b128 v[38:41], v25 offset:28032
	v_cmp_neq_f32_e32 vcc, -1.0, v52
	s_nop 1
	v_cndmask_b32_e32 v42, v213, v42, vcc
	v_cmp_lt_f32_e64 vcc, |v52|, s2
	s_nop 1
	v_cndmask_b32_e32 v46, v42, v52, vcc
	ds_read_b128 v[42:45], v25 offset:28048
	s_waitcnt lgkmcnt(1)
	v_fma_f32 v47, v29, v38, v26
	v_fmac_f32_e32 v47, v30, v39
	v_fmac_f32_e32 v47, v31, v40
	v_fmac_f32_e32 v47, v32, v41
	ds_read_b128 v[38:41], v25 offset:28064
	s_waitcnt lgkmcnt(1)
	v_fmac_f32_e32 v47, v28, v42
	v_fmac_f32_e32 v47, v27, v43
	v_pk_mul_f32 v[42:43], v[12:13], v[44:45]
	s_nop 0
	v_add_f32_e32 v42, v47, v42
	v_add_f32_e32 v47, v42, v43
	ds_read_b128 v[42:45], v25 offset:28080
	s_waitcnt lgkmcnt(1)
	v_pk_mul_f32 v[38:39], v[6:7], v[38:39]
	s_nop 0
	v_add_f32_e32 v38, v47, v38
	v_add_f32_e32 v47, v38, v39
	v_pk_mul_f32 v[38:39], v[4:5], v[40:41]
	s_nop 0
	v_add_f32_e32 v38, v47, v38
	v_add_f32_e32 v40, v38, v39
	s_waitcnt lgkmcnt(0)
	v_pk_mul_f32 v[38:39], v[8:9], v[42:43]
	s_nop 0
	v_add_f32_e32 v38, v40, v38
	v_add_f32_e32 v40, v38, v39
	v_pk_mul_f32 v[38:39], v[10:11], v[44:45]
	s_nop 0
	v_add_f32_e32 v38, v40, v38
	v_add_f32_e32 v38, v38, v39
	v_mul_f32_e64 v39, |v38|, s90
	v_exp_f32_e32 v52, v39
	v_sub_f32_e32 v39, v53, v46
	v_min_f32_e32 v54, 0, v38
	v_fmamk_f32 v53, v39, 0x3d800000, v37
	v_add_f32_e32 v40, 1.0, v52
	v_add_f32_e32 v38, -1.0, v40
	v_sub_f32_e32 v39, v38, v40
	v_add_f32_e32 v39, 1.0, v39
	v_sub_f32_e32 v38, v52, v38
	v_add_f32_e32 v41, v38, v39
	v_frexp_mant_f32_e32 v42, v40
	v_cvt_f64_f32_e32 v[38:39], v40
	v_frexp_exp_i32_f64_e32 v38, v[38:39]
	v_cmp_gt_f32_e32 vcc, s36, v42
	s_nop 1
	v_subbrev_co_u32_e32 v46, vcc, 0, v38, vcc
	v_sub_u32_e32 v38, 0, v46
	v_ldexp_f32 v39, v40, v38
	v_add_f32_e32 v40, -1.0, v39
	v_add_f32_e32 v42, 1.0, v39
	v_ldexp_f32 v38, v41, v38
	v_add_f32_e32 v41, 1.0, v40
	v_add_f32_e32 v43, -1.0, v42
	v_sub_f32_e32 v41, v39, v41
	v_sub_f32_e32 v39, v39, v43
	v_add_f32_e32 v41, v38, v41
	v_add_f32_e32 v38, v38, v39
	v_add_f32_e32 v47, v42, v38
	v_rcp_f32_e32 v49, v47
	v_sub_f32_e32 v39, v47, v42
	v_sub_f32_e32 v48, v38, v39
	v_add_f32_e32 v39, v40, v41
	v_mul_f32_e32 v51, v39, v49
	v_sub_f32_e32 v38, v39, v40
	v_mul_f32_e32 v40, v47, v51
	v_fma_f32 v42, v51, v47, -v40
	v_fmac_f32_e32 v42, v51, v48
	v_sub_f32_e32 v50, v41, v38
	v_add_f32_e32 v38, v40, v42
	v_sub_f32_e32 v41, v39, v38
	v_pk_add_f32 v[44:45], v[38:39], v[40:41] neg_lo:[0,1] neg_hi:[0,1]
	v_mov_b32_e32 v43, v38
	v_pk_add_f32 v[38:39], v[44:45], v[42:43] neg_lo:[0,1] neg_hi:[0,1]
	v_cmp_neq_f32_e32 vcc, s79, v52
	v_add_f32_e32 v39, v50, v39
	v_add_f32_e32 v38, v38, v39
	v_add_f32_e32 v39, v41, v38
	v_mul_f32_e32 v50, v49, v39
	v_mul_f32_e32 v40, v47, v50
	v_fma_f32 v42, v50, v47, -v40
	v_fmac_f32_e32 v42, v50, v48
	v_sub_f32_e32 v41, v41, v39
	v_add_f32_e32 v47, v38, v41
	v_add_f32_e32 v38, v40, v42
	v_sub_f32_e32 v41, v39, v38
	v_pk_add_f32 v[44:45], v[38:39], v[40:41] neg_lo:[0,1] neg_hi:[0,1]
	v_mov_b32_e32 v43, v38
	v_pk_add_f32 v[38:39], v[44:45], v[42:43] neg_lo:[0,1] neg_hi:[0,1]
	s_nop 0
	v_add_f32_e32 v39, v47, v39
	v_add_f32_e32 v38, v38, v39
	v_add_f32_e32 v39, v51, v50
	v_add_f32_e32 v38, v41, v38
	v_sub_f32_e32 v40, v39, v51
	v_mul_f32_e32 v38, v49, v38
	v_sub_f32_e32 v40, v50, v40
	v_add_f32_e32 v40, v40, v38
	v_add_f32_e32 v42, v39, v40
	v_mul_f32_e32 v43, v42, v42
	v_fmamk_f32 v38, v43, 0x3e9b6dac, v204
	v_fmaak_f32 v175, v43, v38, 0x3f2aaada
	v_cvt_f32_i32_e32 v38, v46
	v_sub_f32_e32 v39, v42, v39
	v_sub_f32_e32 v39, v40, v39
	v_ldexp_f32 v44, v39, 1
	v_mul_f32_e32 v39, v42, v43
	v_ldexp_f32 v41, v42, 1
	v_pk_mul_f32 v[42:43], v[38:39], v[174:175]
	s_nop 0
	v_fma_f32 v40, v38, s78, -v42
	v_fmac_f32_e32 v40, 0xb102e308, v38
	v_pk_add_f32 v[38:39], v[42:43], v[40:41]
	s_nop 0
	v_sub_f32_e32 v41, v39, v41
	v_sub_f32_e32 v41, v43, v41
	v_add_f32_e32 v45, v44, v41
	v_mov_b32_e32 v44, v42
	v_pk_add_f32 v[42:43], v[38:39], v[42:43] neg_lo:[0,1] neg_hi:[0,1]
	v_pk_add_f32 v[46:47], v[38:39], v[44:45]
	v_mov_b32_e32 v41, v38
	v_mov_b32_e32 v43, v47
	v_pk_add_f32 v[48:49], v[40:41], v[42:43] neg_lo:[0,1] neg_hi:[0,1]
	v_pk_add_f32 v[40:41], v[40:41], v[42:43]
	v_mov_b32_e32 v44, v45
	v_pk_add_f32 v[42:43], v[40:41], v[38:39] op_sel:[1,0] op_sel_hi:[0,1] neg_lo:[0,1] neg_hi:[0,1]
	v_pk_add_f32 v[50:51], v[46:47], v[42:43] op_sel_hi:[1,0] neg_lo:[0,1] neg_hi:[0,1]
	v_mov_b32_e32 v46, v47
	v_mov_b32_e32 v47, v41
	v_pk_mov_b32 v[42:43], v[38:39], v[42:43] op_sel:[1,0]
	v_mov_b32_e32 v45, v38
	v_pk_add_f32 v[42:43], v[46:47], v[42:43] neg_lo:[0,1] neg_hi:[0,1]
	v_mov_b32_e32 v50, v48
	v_pk_add_f32 v[38:39], v[44:45], v[42:43] neg_lo:[0,1] neg_hi:[0,1]
	v_mov_b32_e32 v49, v41
	v_pk_add_f32 v[42:43], v[50:51], v[38:39]
	s_nop 0
	v_pk_add_f32 v[44:45], v[42:43], v[42:43] op_sel:[0,1] op_sel_hi:[1,0]
	s_nop 0
	v_pk_add_f32 v[40:41], v[40:41], v[44:45] op_sel:[1,0] op_sel_hi:[0,1]
	v_mov_b32_e32 v43, v40
	v_pk_add_f32 v[46:47], v[42:43], v[48:49] neg_lo:[0,1] neg_hi:[0,1]
	v_mov_b32_e32 v39, v44
	v_sub_f32_e32 v41, v42, v46
	v_pk_add_f32 v[38:39], v[38:39], v[46:47] neg_lo:[0,1] neg_hi:[0,1]
	v_sub_f32_e32 v41, v48, v41
	v_add_f32_e32 v38, v38, v41
	v_add_f32_e32 v38, v38, v39
	v_add_f32_e32 v38, v40, v38
	v_cndmask_b32_e32 v38, v211, v38, vcc
	v_cmp_ngt_f32_e32 vcc, -1.0, v52
	s_nop 1
	v_cndmask_b32_e32 v42, v212, v38, vcc
	ds_read_b128 v[38:41], v25 offset:28096
	v_cmp_neq_f32_e32 vcc, -1.0, v52
	s_nop 1
	v_cndmask_b32_e32 v42, v213, v42, vcc
	v_cmp_lt_f32_e64 vcc, |v52|, s2
	s_nop 1
	v_cndmask_b32_e32 v46, v42, v52, vcc
	ds_read_b128 v[42:45], v25 offset:28112
	s_waitcnt lgkmcnt(1)
	v_fmac_f32_e32 v26, v29, v38
	v_fmac_f32_e32 v26, v30, v39
	v_fmac_f32_e32 v26, v31, v40
	v_fmac_f32_e32 v26, v32, v41
	s_waitcnt lgkmcnt(0)
	v_fmac_f32_e32 v26, v28, v42
	ds_read_b128 v[28:31], v25 offset:28128
	ds_read_b128 v[38:41], v25 offset:28144
	v_fmac_f32_e32 v26, v27, v43
	v_pk_mul_f32 v[12:13], v[12:13], v[44:45]
	s_waitcnt lgkmcnt(1)
	v_pk_mul_f32 v[6:7], v[6:7], v[28:29]
	v_add_f32_e32 v12, v26, v12
	v_add_f32_e32 v12, v12, v13
	v_add_f32_e32 v6, v12, v6
	v_add_f32_e32 v6, v6, v7
	v_pk_mul_f32 v[4:5], v[4:5], v[30:31]
	s_nop 0
	v_add_f32_e32 v4, v6, v4
	v_add_f32_e32 v6, v4, v5
	s_waitcnt lgkmcnt(0)
	v_pk_mul_f32 v[4:5], v[8:9], v[38:39]
	s_nop 0
	v_add_f32_e32 v4, v6, v4
	v_add_f32_e32 v6, v4, v5
	v_pk_mul_f32 v[4:5], v[10:11], v[40:41]
	s_nop 0
	v_add_f32_e32 v4, v6, v4
	v_add_f32_e32 v4, v4, v5
	v_mul_f32_e64 v5, |v4|, s90
	v_exp_f32_e32 v25, v5
	v_sub_f32_e32 v5, v54, v46
	v_min_f32_e32 v31, 0, v4
	v_fmamk_f32 v30, v5, 0x3d800000, v53
	v_add_f32_e32 v6, 1.0, v25
	v_add_f32_e32 v4, -1.0, v6
	v_sub_f32_e32 v5, v4, v6
	v_add_f32_e32 v5, 1.0, v5
	v_sub_f32_e32 v4, v25, v4
	v_add_f32_e32 v7, v4, v5
	v_frexp_mant_f32_e32 v8, v6
	v_cvt_f64_f32_e32 v[4:5], v6
	v_frexp_exp_i32_f64_e32 v4, v[4:5]
	v_cmp_gt_f32_e32 vcc, s36, v8
	s_nop 1
	v_subbrev_co_u32_e32 v12, vcc, 0, v4, vcc
	v_sub_u32_e32 v4, 0, v12
	v_ldexp_f32 v5, v6, v4
	v_add_f32_e32 v6, -1.0, v5
	v_add_f32_e32 v8, 1.0, v5
	v_ldexp_f32 v4, v7, v4
	v_add_f32_e32 v7, 1.0, v6
	v_add_f32_e32 v9, -1.0, v8
	v_sub_f32_e32 v7, v5, v7
	v_sub_f32_e32 v5, v5, v9
	v_add_f32_e32 v7, v4, v7
	v_add_f32_e32 v4, v4, v5
	v_add_f32_e32 v13, v8, v4
	v_rcp_f32_e32 v27, v13
	v_sub_f32_e32 v5, v13, v8
	v_sub_f32_e32 v26, v4, v5
	v_add_f32_e32 v5, v6, v7
	v_mul_f32_e32 v29, v5, v27
	v_sub_f32_e32 v4, v5, v6
	v_mul_f32_e32 v6, v13, v29
	v_fma_f32 v8, v29, v13, -v6
	v_fmac_f32_e32 v8, v29, v26
	v_sub_f32_e32 v28, v7, v4
	v_add_f32_e32 v4, v6, v8
	v_sub_f32_e32 v7, v5, v4
	v_pk_add_f32 v[10:11], v[4:5], v[6:7] neg_lo:[0,1] neg_hi:[0,1]
	v_mov_b32_e32 v9, v4
	v_pk_add_f32 v[4:5], v[10:11], v[8:9] neg_lo:[0,1] neg_hi:[0,1]
	v_cmp_neq_f32_e32 vcc, s79, v25
	v_add_f32_e32 v5, v28, v5
	v_add_f32_e32 v4, v4, v5
	v_add_f32_e32 v5, v7, v4
	v_mul_f32_e32 v28, v27, v5
	v_mul_f32_e32 v6, v13, v28
	v_fma_f32 v8, v28, v13, -v6
	v_fmac_f32_e32 v8, v28, v26
	v_sub_f32_e32 v7, v7, v5
	v_add_f32_e32 v13, v4, v7
	v_add_f32_e32 v4, v6, v8
	v_sub_f32_e32 v7, v5, v4
	v_pk_add_f32 v[10:11], v[4:5], v[6:7] neg_lo:[0,1] neg_hi:[0,1]
	v_mov_b32_e32 v9, v4
	v_pk_add_f32 v[4:5], v[10:11], v[8:9] neg_lo:[0,1] neg_hi:[0,1]
	s_nop 0
	v_add_f32_e32 v5, v13, v5
	v_add_f32_e32 v4, v4, v5
	v_add_f32_e32 v5, v29, v28
	v_add_f32_e32 v4, v7, v4
	v_sub_f32_e32 v6, v5, v29
	v_mul_f32_e32 v4, v27, v4
	v_sub_f32_e32 v6, v28, v6
	v_add_f32_e32 v6, v6, v4
	v_add_f32_e32 v8, v5, v6
	v_mul_f32_e32 v9, v8, v8
	v_fmamk_f32 v4, v9, 0x3e9b6dac, v204
	v_fmaak_f32 v175, v9, v4, 0x3f2aaada
	v_cvt_f32_i32_e32 v4, v12
	v_sub_f32_e32 v5, v8, v5
	v_sub_f32_e32 v5, v6, v5
	v_ldexp_f32 v10, v5, 1
	v_mul_f32_e32 v5, v8, v9
	v_ldexp_f32 v7, v8, 1
	v_pk_mul_f32 v[8:9], v[4:5], v[174:175]
	s_nop 0
	v_fma_f32 v6, v4, s78, -v8
	v_fmac_f32_e32 v6, 0xb102e308, v4
	v_pk_add_f32 v[4:5], v[8:9], v[6:7]
	s_nop 0
	v_sub_f32_e32 v7, v5, v7
	v_sub_f32_e32 v7, v9, v7
	v_add_f32_e32 v11, v10, v7
	v_mov_b32_e32 v10, v8
	v_pk_add_f32 v[8:9], v[4:5], v[8:9] neg_lo:[0,1] neg_hi:[0,1]
	v_pk_add_f32 v[12:13], v[4:5], v[10:11]
	v_mov_b32_e32 v7, v4
	v_mov_b32_e32 v9, v13
	v_pk_add_f32 v[26:27], v[6:7], v[8:9] neg_lo:[0,1] neg_hi:[0,1]
	v_pk_add_f32 v[6:7], v[6:7], v[8:9]
	v_mov_b32_e32 v10, v11
	v_pk_add_f32 v[8:9], v[6:7], v[4:5] op_sel:[1,0] op_sel_hi:[0,1] neg_lo:[0,1] neg_hi:[0,1]
	v_pk_add_f32 v[28:29], v[12:13], v[8:9] op_sel_hi:[1,0] neg_lo:[0,1] neg_hi:[0,1]
	v_mov_b32_e32 v12, v13
	v_mov_b32_e32 v13, v7
	v_pk_mov_b32 v[8:9], v[4:5], v[8:9] op_sel:[1,0]
	v_mov_b32_e32 v11, v4
	v_pk_add_f32 v[8:9], v[12:13], v[8:9] neg_lo:[0,1] neg_hi:[0,1]
	v_mov_b32_e32 v28, v26
	v_pk_add_f32 v[4:5], v[10:11], v[8:9] neg_lo:[0,1] neg_hi:[0,1]
	v_mov_b32_e32 v27, v7
	v_pk_add_f32 v[8:9], v[28:29], v[4:5]
	s_nop 0
	v_pk_add_f32 v[10:11], v[8:9], v[8:9] op_sel:[0,1] op_sel_hi:[1,0]
	s_nop 0
	v_pk_add_f32 v[6:7], v[6:7], v[10:11] op_sel:[1,0] op_sel_hi:[0,1]
	v_mov_b32_e32 v9, v6
	v_pk_add_f32 v[12:13], v[8:9], v[26:27] neg_lo:[0,1] neg_hi:[0,1]
	v_mov_b32_e32 v5, v10
	v_sub_f32_e32 v7, v8, v12
	v_pk_add_f32 v[4:5], v[4:5], v[12:13] neg_lo:[0,1] neg_hi:[0,1]
	v_sub_f32_e32 v7, v26, v7
	v_add_f32_e32 v4, v4, v7
	v_add_f32_e32 v4, v4, v5
	v_add_f32_e32 v4, v6, v4
	v_cndmask_b32_e32 v4, v211, v4, vcc
	v_cmp_ngt_f32_e32 vcc, -1.0, v25
	s_nop 1
	v_cndmask_b32_e32 v4, v212, v4, vcc
	v_cmp_neq_f32_e32 vcc, -1.0, v25
	s_nop 1
	v_cndmask_b32_e32 v4, v213, v4, vcc
	v_cmp_lt_f32_e64 vcc, |v25|, s2
	s_nop 1
	v_cndmask_b32_e32 v4, v4, v25, vcc
	v_sub_f32_e32 v4, v31, v4
	v_fmamk_f32 v5, v4, 0x3d800000, v30
	ds_write_b32 v2, v5 offset:31744
	s_waitcnt lgkmcnt(0)
	s_barrier
	ds_read2st64_b32 v[6:7], v0 offset0:124 offset1:125
	ds_read2st64_b32 v[8:9], v0 offset0:126 offset1:127
	ds_read2st64_b32 v[10:11], v0 offset0:128 offset1:129
	ds_read2st64_b32 v[12:13], v0 offset0:130 offset1:131
	v_cmp_lt_i32_e32 vcc, 0, v3
	s_waitcnt lgkmcnt(3)
	v_add_f32_e32 v0, 0, v6
	s_waitcnt lgkmcnt(0)
	v_cndmask_b32_e32 v2, 0, v0, vcc
	v_add_f32_e32 v4, v7, v2
	v_cmp_lt_i32_e32 vcc, 1, v3
	v_add_f32_e32 v0, v0, v7
	v_add_f32_e32 v0, v0, v8
	v_cndmask_b32_e32 v2, v2, v4, vcc
	v_add_f32_e32 v4, v8, v2
	v_cmp_lt_i32_e32 vcc, 2, v3
	v_add_f32_e32 v0, v0, v9
	v_add_f32_e32 v0, v0, v10
	v_cndmask_b32_e32 v2, v2, v4, vcc
	v_add_f32_e32 v4, v9, v2
	v_cmp_lt_i32_e32 vcc, 3, v3
	v_add_f32_e32 v0, v0, v11
	v_lshlrev_b32_e32 v7, 16, v21
	v_cndmask_b32_e32 v2, v2, v4, vcc
	v_add_f32_e32 v4, v10, v2
	v_cmp_lt_i32_e32 vcc, 4, v3
	v_lshlrev_b32_e32 v9, 16, v22
	v_lshlrev_b32_e32 v8, 16, v17
	v_cndmask_b32_e32 v2, v2, v4, vcc
	v_add_f32_e32 v4, v11, v2
	v_cmp_lt_i32_e32 vcc, 5, v3
	v_lshlrev_b32_e32 v11, 16, v24
	v_lshlrev_b32_e32 v10, 16, v20
	v_cndmask_b32_e32 v2, v2, v4, vcc
	v_add_f32_e32 v4, v12, v2
	v_cmp_lt_i32_e32 vcc, 6, v3
	s_barrier
	s_nop 0
	v_cndmask_b32_e32 v2, v2, v4, vcc
	v_add_f32_e32 v4, v13, v2
	v_cmp_lt_i32_e32 vcc, 7, v3
	s_nop 1
	v_cndmask_b32_e32 v3, v2, v4, vcc
	v_add_f32_e32 v4, v0, v12
	v_mov_b32_e32 v2, v13
	v_add_f32_e32 v6, v33, v3
	v_add_f32_e32 v25, v34, v3
	v_add_f32_e32 v26, v35, v3
	v_add_f32_e32 v27, v36, v3
	v_add_f32_e32 v28, v3, v37
	v_add_f32_e32 v29, v3, v53
	v_add_f32_e32 v30, v3, v30
	v_pk_add_f32 v[2:3], v[4:5], v[2:3]
	v_mov_b32_e32 v80, v6
	v_mov_b32_e32 v81, v25
	v_mov_b32_e32 v82, v26
	v_mov_b32_e32 v83, v27
	v_mov_b32_e32 v84, v28
	v_mov_b32_e32 v85, v29
	v_mov_b32_e32 v86, v30
	v_mov_b32_e32 v87, v3
	v_lshlrev_b32_e32 v88, 5, v202
	s_lshl_b32 s98, s30, 14
	s_add_u32 s98, s98, 0x4f28000
	s_add_u32 s98, s100, s98
	s_addc_u32 s99, s101, 0
	global_store_dwordx4 v88, v[80:83], s[98:99]
	global_store_dwordx4 v88, v[84:87], s[98:99] offset:16
	v_cmp_gt_i32_e32 vcc, 64, v18
	v_sub_f32_e32 v0, v2, v6
	v_mul_f32_e32 v0, 0x3fb8aa3b, v0
	v_exp_f32_e32 v4, v0
	v_sub_f32_e32 v0, v2, v25
	v_mul_f32_e32 v0, 0x3fb8aa3b, v0
	v_exp_f32_e32 v5, v0
	v_sub_f32_e32 v0, v2, v26
	v_lshlrev_b32_e32 v6, 16, v16
	v_mul_f32_e32 v0, 0x3fb8aa3b, v0
	v_pk_mul_f32 v[4:5], v[4:5], v[6:7]
	v_exp_f32_e32 v6, v0
	v_sub_f32_e32 v0, v2, v27
	v_mul_f32_e32 v0, 0x3fb8aa3b, v0
	v_exp_f32_e32 v7, v0
	v_sub_f32_e32 v0, v2, v28
	v_mul_f32_e32 v0, 0x3fb8aa3b, v0
	v_cvt_pk_bf16_f32 v4, v4, v5
	v_pk_mul_f32 v[6:7], v[6:7], v[8:9]
	v_exp_f32_e32 v8, v0
	v_sub_f32_e32 v0, v2, v29
	v_mul_f32_e32 v0, 0x3fb8aa3b, v0
	v_exp_f32_e32 v9, v0
	v_sub_f32_e32 v0, v2, v30
	v_cvt_pk_bf16_f32 v5, v6, v7
	v_lshlrev_b32_e32 v7, 16, v23
	v_lshlrev_b32_e32 v6, 16, v19
	v_mul_f32_e32 v0, 0x3fb8aa3b, v0
	v_pk_mul_f32 v[6:7], v[8:9], v[6:7]
	v_exp_f32_e32 v8, v0
	v_sub_f32_e32 v0, v2, v3
	v_mul_f32_e32 v0, 0x3fb8aa3b, v0
	v_exp_f32_e32 v9, v0
	v_mul_u32_u24_e32 v0, 0x90, v15
	v_lshlrev_b32_e32 v3, 4, v14
	v_cvt_pk_bf16_f32 v6, v6, v7
	v_pk_mul_f32 v[8:9], v[8:9], v[10:11]
	v_add3_u32 v0, 0, v0, v3
	v_cvt_pk_bf16_f32 v7, v8, v9
	ds_write_b128 v0, v[4:7]
	s_and_saveexec_b64 s[14:15], vcc
	s_cbranch_execz .LBB0_677
	v_mul_f32_e32 v0, 0x3fb8aa3b, v2
	s_lshl_b64 s[6:7], s[30:31], 8
	v_readlane_b32 s4, v254, 53
	v_exp_f32_e32 v0, v0
	v_readlane_b32 s5, v254, 54
	s_add_u32 s6, s4, s6
	s_addc_u32 s7, s5, s7
	v_ashrrev_i32_e32 v19, 31, v18
	v_lshl_add_u64 v[2:3], v[18:19], 2, s[6:7]
	global_store_dword v[2:3], v0, off

.LBB0_1222:
	v_add_co_u32_e32 v184, vcc, 0xfffd6000, v4
	s_nop 1
	v_addc_co_u32_e32 v185, vcc, -1, v5, vcc
	v_add_u32_e32 v186, 0x14000, v62
	global_load_dword v112, v[184:185], off
	v_add_co_u32_e32 v184, vcc, 0x6000, v184
	s_nop 1
	v_addc_co_u32_e32 v185, vcc, 0, v185, vcc
	global_load_dword v113, v[184:185], off
	v_add_co_u32_e32 v184, vcc, 0x6000, v184
	s_nop 1
	v_addc_co_u32_e32 v185, vcc, 0, v185, vcc
	global_load_dword v114, v[184:185], off
	v_add_co_u32_e32 v184, vcc, 0x6000, v184
	s_nop 1
	v_addc_co_u32_e32 v185, vcc, 0, v185, vcc
	global_load_dword v115, v[184:185], off
	v_add_co_u32_e32 v184, vcc, 0x6000, v184
	s_nop 1
	v_addc_co_u32_e32 v185, vcc, 0, v185, vcc
	global_load_dword v116, v[184:185], off
	v_add_co_u32_e32 v184, vcc, 0x6000, v184
	s_nop 1
	v_addc_co_u32_e32 v185, vcc, 0, v185, vcc
	global_load_dword v117, v[184:185], off
	v_add_co_u32_e32 v184, vcc, 0x6000, v184
	s_nop 1
	v_addc_co_u32_e32 v185, vcc, 0, v185, vcc
	global_load_dword v118, v[184:185], off
	v_add_co_u32_e32 v184, vcc, 0x6000, v184
	s_nop 1
	v_addc_co_u32_e32 v185, vcc, 0, v185, vcc
	global_load_dword v119, v[184:185], off
	v_add_co_u32_e32 v184, vcc, 0x6000, v184
	s_nop 1
	v_addc_co_u32_e32 v185, vcc, 0, v185, vcc
	global_load_dword v120, v[184:185], off
	v_add_co_u32_e32 v184, vcc, 0x6000, v184
	s_nop 1
	v_addc_co_u32_e32 v185, vcc, 0, v185, vcc
	global_load_dword v121, v[184:185], off
	v_add_co_u32_e32 v184, vcc, 0x6000, v184
	s_nop 1
	v_addc_co_u32_e32 v185, vcc, 0, v185, vcc
	global_load_dword v122, v[184:185], off
	v_add_co_u32_e32 v184, vcc, 0x6000, v184
	s_nop 1
	v_addc_co_u32_e32 v185, vcc, 0, v185, vcc
	global_load_dword v123, v[184:185], off
	v_add_co_u32_e32 v184, vcc, 0x6000, v184
	s_nop 1
	v_addc_co_u32_e32 v185, vcc, 0, v185, vcc
	global_load_dword v124, v[184:185], off
	v_add_co_u32_e32 v184, vcc, 0x6000, v184
	s_nop 1
	v_addc_co_u32_e32 v185, vcc, 0, v185, vcc
	global_load_dword v125, v[184:185], off
	v_add_co_u32_e32 v184, vcc, 0x6000, v184
	s_nop 1
	v_addc_co_u32_e32 v185, vcc, 0, v185, vcc
	global_load_dword v126, v[184:185], off
	v_add_co_u32_e32 v184, vcc, 0x6000, v184
	s_nop 1
	v_addc_co_u32_e32 v185, vcc, 0, v185, vcc
	global_load_dword v127, v[184:185], off
	v_add_co_u32_e32 v184, vcc, 0x6000, v184
	s_nop 1
	v_addc_co_u32_e32 v185, vcc, 0, v185, vcc
	global_load_dword v128, v[184:185], off
	v_add_co_u32_e32 v184, vcc, 0x6000, v184
	s_nop 1
	v_addc_co_u32_e32 v185, vcc, 0, v185, vcc
	global_load_dword v129, v[184:185], off
	v_add_co_u32_e32 v184, vcc, 0x6000, v184
	s_nop 1
	v_addc_co_u32_e32 v185, vcc, 0, v185, vcc
	global_load_dword v130, v[184:185], off
	v_add_co_u32_e32 v184, vcc, 0x6000, v184
	s_nop 1
	v_addc_co_u32_e32 v185, vcc, 0, v185, vcc
	global_load_dword v131, v[184:185], off
	v_add_co_u32_e32 v184, vcc, 0x6000, v184
	s_nop 1
	v_addc_co_u32_e32 v185, vcc, 0, v185, vcc
	global_load_dword v132, v[184:185], off
	v_add_co_u32_e32 v184, vcc, 0x6000, v184
	s_nop 1
	v_addc_co_u32_e32 v185, vcc, 0, v185, vcc
	global_load_dword v133, v[184:185], off
	v_add_co_u32_e32 v184, vcc, 0x6000, v184
	s_nop 1
	v_addc_co_u32_e32 v185, vcc, 0, v185, vcc
	global_load_dword v134, v[184:185], off
	v_add_co_u32_e32 v184, vcc, 0x6000, v184
	s_nop 1
	v_addc_co_u32_e32 v185, vcc, 0, v185, vcc
	global_load_dword v135, v[184:185], off
	v_add_co_u32_e32 v184, vcc, 0x6000, v184
	s_nop 1
	v_addc_co_u32_e32 v185, vcc, 0, v185, vcc
	global_load_dword v136, v[184:185], off
	v_add_co_u32_e32 v184, vcc, 0x6000, v184
	s_nop 1
	v_addc_co_u32_e32 v185, vcc, 0, v185, vcc
	global_load_dword v137, v[184:185], off
	v_add_co_u32_e32 v184, vcc, 0x6000, v184
	s_nop 1
	v_addc_co_u32_e32 v185, vcc, 0, v185, vcc
	global_load_dword v138, v[184:185], off
	v_add_co_u32_e32 v184, vcc, 0x6000, v184
	s_nop 1
	v_addc_co_u32_e32 v185, vcc, 0, v185, vcc
	global_load_dword v139, v[184:185], off
	v_add_co_u32_e32 v184, vcc, 0x6000, v184
	s_nop 1
	v_addc_co_u32_e32 v185, vcc, 0, v185, vcc
	global_load_dword v140, v[184:185], off
	v_add_co_u32_e32 v184, vcc, 0x6000, v184
	s_nop 1
	v_addc_co_u32_e32 v185, vcc, 0, v185, vcc
	global_load_dword v141, v[184:185], off
	v_add_co_u32_e32 v184, vcc, 0x6000, v184
	s_nop 1
	v_addc_co_u32_e32 v185, vcc, 0, v185, vcc
	global_load_dword v142, v[184:185], off
	v_add_co_u32_e32 v184, vcc, 0x6000, v184
	s_nop 1
	v_addc_co_u32_e32 v185, vcc, 0, v185, vcc
	global_load_dword v143, v[184:185], off
	v_add_co_u32_e32 v184, vcc, 0x6000, v184
	s_nop 1
	v_addc_co_u32_e32 v185, vcc, 0, v185, vcc
	global_load_dword v144, v[184:185], off
	v_add_co_u32_e32 v184, vcc, 0x6000, v184
	s_nop 1
	v_addc_co_u32_e32 v185, vcc, 0, v185, vcc
	global_load_dword v145, v[184:185], off
	v_add_co_u32_e32 v184, vcc, 0x6000, v184
	s_nop 1
	v_addc_co_u32_e32 v185, vcc, 0, v185, vcc
	global_load_dword v146, v[184:185], off
	v_add_co_u32_e32 v184, vcc, 0x6000, v184
	s_nop 1
	v_addc_co_u32_e32 v185, vcc, 0, v185, vcc
	global_load_dword v147, v[184:185], off
	v_add_co_u32_e32 v184, vcc, 0x6000, v184
	s_nop 1
	v_addc_co_u32_e32 v185, vcc, 0, v185, vcc
	global_load_dword v148, v[184:185], off
	v_add_co_u32_e32 v184, vcc, 0x6000, v184
	s_nop 1
	v_addc_co_u32_e32 v185, vcc, 0, v185, vcc
	global_load_dword v149, v[184:185], off
	v_add_co_u32_e32 v184, vcc, 0x6000, v184
	s_nop 1
	v_addc_co_u32_e32 v185, vcc, 0, v185, vcc
	global_load_dword v150, v[184:185], off
	v_add_co_u32_e32 v184, vcc, 0x6000, v184
	s_nop 1
	v_addc_co_u32_e32 v185, vcc, 0, v185, vcc
	global_load_dword v151, v[184:185], off
	v_add_co_u32_e32 v184, vcc, 0x6000, v184
	s_nop 1
	v_addc_co_u32_e32 v185, vcc, 0, v185, vcc
	global_load_dword v152, v[184:185], off
	v_add_co_u32_e32 v184, vcc, 0x6000, v184
	s_nop 1
	v_addc_co_u32_e32 v185, vcc, 0, v185, vcc
	global_load_dword v153, v[184:185], off
	v_add_co_u32_e32 v184, vcc, 0x6000, v184
	s_nop 1
	v_addc_co_u32_e32 v185, vcc, 0, v185, vcc
	global_load_dword v154, v[184:185], off
	v_add_co_u32_e32 v184, vcc, 0x6000, v184
	s_nop 1
	v_addc_co_u32_e32 v185, vcc, 0, v185, vcc
	global_load_dword v155, v[184:185], off
	v_add_co_u32_e32 v184, vcc, 0x6000, v184
	s_nop 1
	v_addc_co_u32_e32 v185, vcc, 0, v185, vcc
	global_load_dword v156, v[184:185], off
	v_add_co_u32_e32 v184, vcc, 0x6000, v184
	s_nop 1
	v_addc_co_u32_e32 v185, vcc, 0, v185, vcc
	global_load_dword v157, v[184:185], off
	v_add_co_u32_e32 v184, vcc, 0x6000, v184
	s_nop 1
	v_addc_co_u32_e32 v185, vcc, 0, v185, vcc
	global_load_dword v158, v[184:185], off
	v_add_co_u32_e32 v184, vcc, 0x6000, v184
	s_nop 1
	v_addc_co_u32_e32 v185, vcc, 0, v185, vcc
	global_load_dword v159, v[184:185], off
	v_add_co_u32_e32 v184, vcc, 0x6000, v184
	s_nop 1
	v_addc_co_u32_e32 v185, vcc, 0, v185, vcc
	ds_read_b128 v[8:11], v186 offset:0
	ds_read_b128 v[12:15], v186 offset:4096
	ds_read_b128 v[16:19], v186 offset:8192
	ds_read_b128 v[20:23], v186 offset:16
	ds_read_b128 v[24:27], v186 offset:4112
	ds_read_b128 v[28:31], v186 offset:8208
	ds_read_b128 v[188:191], v186 offset:32
	ds_read_b128 v[192:195], v186 offset:4128
	ds_read_b128 v[196:199], v186 offset:8224
	ds_read_b128 v[228:231], v186 offset:48
	ds_read_b128 v[232:235], v186 offset:4144
	ds_read_b128 v[236:239], v186 offset:8240
	s_waitcnt vmcnt(32)
	s_waitcnt lgkmcnt(0)
	v_fmac_f32_e32 v6, v112, v8
	v_fmac_f32_e32 v7, v112, v12
	v_fmac_f32_e32 v3, v112, v16
	v_fmac_f32_e32 v6, v113, v9
	v_fmac_f32_e32 v7, v113, v13
	v_fmac_f32_e32 v3, v113, v17
	v_fmac_f32_e32 v6, v114, v10
	v_fmac_f32_e32 v7, v114, v14
	v_fmac_f32_e32 v3, v114, v18
	v_fmac_f32_e32 v6, v115, v11
	v_fmac_f32_e32 v7, v115, v15
	v_fmac_f32_e32 v3, v115, v19
	v_fmac_f32_e32 v6, v116, v20
	v_fmac_f32_e32 v7, v116, v24
	v_fmac_f32_e32 v3, v116, v28
	v_fmac_f32_e32 v6, v117, v21
	v_fmac_f32_e32 v7, v117, v25
	v_fmac_f32_e32 v3, v117, v29
	v_fmac_f32_e32 v6, v118, v22
	v_fmac_f32_e32 v7, v118, v26
	v_fmac_f32_e32 v3, v118, v30
	v_fmac_f32_e32 v6, v119, v23
	v_fmac_f32_e32 v7, v119, v27
	v_fmac_f32_e32 v3, v119, v31
	v_fmac_f32_e32 v6, v120, v188
	v_fmac_f32_e32 v7, v120, v192
	v_fmac_f32_e32 v3, v120, v196
	v_fmac_f32_e32 v6, v121, v189
	v_fmac_f32_e32 v7, v121, v193
	v_fmac_f32_e32 v3, v121, v197
	v_fmac_f32_e32 v6, v122, v190
	v_fmac_f32_e32 v7, v122, v194
	v_fmac_f32_e32 v3, v122, v198
	v_fmac_f32_e32 v6, v123, v191
	v_fmac_f32_e32 v7, v123, v195
	v_fmac_f32_e32 v3, v123, v199
	v_fmac_f32_e32 v6, v124, v228
	v_fmac_f32_e32 v7, v124, v232
	v_fmac_f32_e32 v3, v124, v236
	v_fmac_f32_e32 v6, v125, v229
	v_fmac_f32_e32 v7, v125, v233
	v_fmac_f32_e32 v3, v125, v237
	v_fmac_f32_e32 v6, v126, v230
	v_fmac_f32_e32 v7, v126, v234
	v_fmac_f32_e32 v3, v126, v238
	v_fmac_f32_e32 v6, v127, v231
	v_fmac_f32_e32 v7, v127, v235
	v_fmac_f32_e32 v3, v127, v239
	global_load_dword v112, v[184:185], off
	v_add_co_u32_e32 v184, vcc, 0x6000, v184
	s_nop 1
	v_addc_co_u32_e32 v185, vcc, 0, v185, vcc
	global_load_dword v113, v[184:185], off
	v_add_co_u32_e32 v184, vcc, 0x6000, v184
	s_nop 1
	v_addc_co_u32_e32 v185, vcc, 0, v185, vcc
	global_load_dword v114, v[184:185], off
	v_add_co_u32_e32 v184, vcc, 0x6000, v184
	s_nop 1
	v_addc_co_u32_e32 v185, vcc, 0, v185, vcc
	global_load_dword v115, v[184:185], off
	v_add_co_u32_e32 v184, vcc, 0x6000, v184
	s_nop 1
	v_addc_co_u32_e32 v185, vcc, 0, v185, vcc
	global_load_dword v116, v[184:185], off
	v_add_co_u32_e32 v184, vcc, 0x6000, v184
	s_nop 1
	v_addc_co_u32_e32 v185, vcc, 0, v185, vcc
	global_load_dword v117, v[184:185], off
	v_add_co_u32_e32 v184, vcc, 0x6000, v184
	s_nop 1
	v_addc_co_u32_e32 v185, vcc, 0, v185, vcc
	global_load_dword v118, v[184:185], off
	v_add_co_u32_e32 v184, vcc, 0x6000, v184
	s_nop 1
	v_addc_co_u32_e32 v185, vcc, 0, v185, vcc
	global_load_dword v119, v[184:185], off
	v_add_co_u32_e32 v184, vcc, 0x6000, v184
	s_nop 1
	v_addc_co_u32_e32 v185, vcc, 0, v185, vcc
	global_load_dword v120, v[184:185], off
	v_add_co_u32_e32 v184, vcc, 0x6000, v184
	s_nop 1
	v_addc_co_u32_e32 v185, vcc, 0, v185, vcc
	global_load_dword v121, v[184:185], off
	v_add_co_u32_e32 v184, vcc, 0x6000, v184
	s_nop 1
	v_addc_co_u32_e32 v185, vcc, 0, v185, vcc
	global_load_dword v122, v[184:185], off
	v_add_co_u32_e32 v184, vcc, 0x6000, v184
	s_nop 1
	v_addc_co_u32_e32 v185, vcc, 0, v185, vcc
	global_load_dword v123, v[184:185], off
	v_add_co_u32_e32 v184, vcc, 0x6000, v184
	s_nop 1
	v_addc_co_u32_e32 v185, vcc, 0, v185, vcc
	global_load_dword v124, v[184:185], off
	v_add_co_u32_e32 v184, vcc, 0x6000, v184
	s_nop 1
	v_addc_co_u32_e32 v185, vcc, 0, v185, vcc
	global_load_dword v125, v[184:185], off
	v_add_co_u32_e32 v184, vcc, 0x6000, v184
	s_nop 1
	v_addc_co_u32_e32 v185, vcc, 0, v185, vcc
	global_load_dword v126, v[184:185], off
	v_add_co_u32_e32 v184, vcc, 0x6000, v184
	s_nop 1
	v_addc_co_u32_e32 v185, vcc, 0, v185, vcc
	global_load_dword v127, v[184:185], off
	v_add_co_u32_e32 v184, vcc, 0x6000, v184
	s_nop 1
	v_addc_co_u32_e32 v185, vcc, 0, v185, vcc
	ds_read_b128 v[8:11], v186 offset:64
	ds_read_b128 v[12:15], v186 offset:4160
	ds_read_b128 v[16:19], v186 offset:8256
	ds_read_b128 v[20:23], v186 offset:80
	ds_read_b128 v[24:27], v186 offset:4176
	ds_read_b128 v[28:31], v186 offset:8272
	ds_read_b128 v[188:191], v186 offset:96
	ds_read_b128 v[192:195], v186 offset:4192
	ds_read_b128 v[196:199], v186 offset:8288
	ds_read_b128 v[228:231], v186 offset:112
	ds_read_b128 v[232:235], v186 offset:4208
	ds_read_b128 v[236:239], v186 offset:8304
	s_waitcnt vmcnt(32)
	s_waitcnt lgkmcnt(0)
	v_fmac_f32_e32 v6, v128, v8
	v_fmac_f32_e32 v7, v128, v12
	v_fmac_f32_e32 v3, v128, v16
	v_fmac_f32_e32 v6, v129, v9
	v_fmac_f32_e32 v7, v129, v13
	v_fmac_f32_e32 v3, v129, v17
	v_fmac_f32_e32 v6, v130, v10
	v_fmac_f32_e32 v7, v130, v14
	v_fmac_f32_e32 v3, v130, v18
	v_fmac_f32_e32 v6, v131, v11
	v_fmac_f32_e32 v7, v131, v15
	v_fmac_f32_e32 v3, v131, v19
	v_fmac_f32_e32 v6, v132, v20
	v_fmac_f32_e32 v7, v132, v24
	v_fmac_f32_e32 v3, v132, v28
	v_fmac_f32_e32 v6, v133, v21
	v_fmac_f32_e32 v7, v133, v25
	v_fmac_f32_e32 v3, v133, v29
	v_fmac_f32_e32 v6, v134, v22
	v_fmac_f32_e32 v7, v134, v26
	v_fmac_f32_e32 v3, v134, v30
	v_fmac_f32_e32 v6, v135, v23
	v_fmac_f32_e32 v7, v135, v27
	v_fmac_f32_e32 v3, v135, v31
	v_fmac_f32_e32 v6, v136, v188
	v_fmac_f32_e32 v7, v136, v192
	v_fmac_f32_e32 v3, v136, v196
	v_fmac_f32_e32 v6, v137, v189
	v_fmac_f32_e32 v7, v137, v193
	v_fmac_f32_e32 v3, v137, v197
	v_fmac_f32_e32 v6, v138, v190
	v_fmac_f32_e32 v7, v138, v194
	v_fmac_f32_e32 v3, v138, v198
	v_fmac_f32_e32 v6, v139, v191
	v_fmac_f32_e32 v7, v139, v195
	v_fmac_f32_e32 v3, v139, v199
	v_fmac_f32_e32 v6, v140, v228
	v_fmac_f32_e32 v7, v140, v232
	v_fmac_f32_e32 v3, v140, v236
	v_fmac_f32_e32 v6, v141, v229
	v_fmac_f32_e32 v7, v141, v233
	v_fmac_f32_e32 v3, v141, v237
	v_fmac_f32_e32 v6, v142, v230
	v_fmac_f32_e32 v7, v142, v234
	v_fmac_f32_e32 v3, v142, v238
	v_fmac_f32_e32 v6, v143, v231
	v_fmac_f32_e32 v7, v143, v235
	v_fmac_f32_e32 v3, v143, v239
	global_load_dword v128, v[184:185], off
	v_add_co_u32_e32 v184, vcc, 0x6000, v184
	s_nop 1
	v_addc_co_u32_e32 v185, vcc, 0, v185, vcc
	global_load_dword v129, v[184:185], off
	v_add_co_u32_e32 v184, vcc, 0x6000, v184
	s_nop 1
	v_addc_co_u32_e32 v185, vcc, 0, v185, vcc
	global_load_dword v130, v[184:185], off
	v_add_co_u32_e32 v184, vcc, 0x6000, v184
	s_nop 1
	v_addc_co_u32_e32 v185, vcc, 0, v185, vcc
	global_load_dword v131, v[184:185], off
	v_add_co_u32_e32 v184, vcc, 0x6000, v184
	s_nop 1
	v_addc_co_u32_e32 v185, vcc, 0, v185, vcc
	global_load_dword v132, v[184:185], off
	v_add_co_u32_e32 v184, vcc, 0x6000, v184
	s_nop 1
	v_addc_co_u32_e32 v185, vcc, 0, v185, vcc
	global_load_dword v133, v[184:185], off
	v_add_co_u32_e32 v184, vcc, 0x6000, v184
	s_nop 1
	v_addc_co_u32_e32 v185, vcc, 0, v185, vcc
	global_load_dword v134, v[184:185], off
	v_add_co_u32_e32 v184, vcc, 0x6000, v184
	s_nop 1
	v_addc_co_u32_e32 v185, vcc, 0, v185, vcc
	global_load_dword v135, v[184:185], off
	v_add_co_u32_e32 v184, vcc, 0x6000, v184
	s_nop 1
	v_addc_co_u32_e32 v185, vcc, 0, v185, vcc
	global_load_dword v136, v[184:185], off
	v_add_co_u32_e32 v184, vcc, 0x6000, v184
	s_nop 1
	v_addc_co_u32_e32 v185, vcc, 0, v185, vcc
	global_load_dword v137, v[184:185], off
	v_add_co_u32_e32 v184, vcc, 0x6000, v184
	s_nop 1
	v_addc_co_u32_e32 v185, vcc, 0, v185, vcc
	global_load_dword v138, v[184:185], off
	v_add_co_u32_e32 v184, vcc, 0x6000, v184
	s_nop 1
	v_addc_co_u32_e32 v185, vcc, 0, v185, vcc
	global_load_dword v139, v[184:185], off
	v_add_co_u32_e32 v184, vcc, 0x6000, v184
	s_nop 1
	v_addc_co_u32_e32 v185, vcc, 0, v185, vcc
	global_load_dword v140, v[184:185], off
	v_add_co_u32_e32 v184, vcc, 0x6000, v184
	s_nop 1
	v_addc_co_u32_e32 v185, vcc, 0, v185, vcc
	global_load_dword v141, v[184:185], off
	v_add_co_u32_e32 v184, vcc, 0x6000, v184
	s_nop 1
	v_addc_co_u32_e32 v185, vcc, 0, v185, vcc
	global_load_dword v142, v[184:185], off
	v_add_co_u32_e32 v184, vcc, 0x6000, v184
	s_nop 1
	v_addc_co_u32_e32 v185, vcc, 0, v185, vcc
	global_load_dword v143, v[184:185], off
	v_add_co_u32_e32 v184, vcc, 0x6000, v184
	s_nop 1
	v_addc_co_u32_e32 v185, vcc, 0, v185, vcc
	ds_read_b128 v[8:11], v186 offset:128
	ds_read_b128 v[12:15], v186 offset:4224
	ds_read_b128 v[16:19], v186 offset:8320
	ds_read_b128 v[20:23], v186 offset:144
	ds_read_b128 v[24:27], v186 offset:4240
	ds_read_b128 v[28:31], v186 offset:8336
	ds_read_b128 v[188:191], v186 offset:160
	ds_read_b128 v[192:195], v186 offset:4256
	ds_read_b128 v[196:199], v186 offset:8352
	ds_read_b128 v[228:231], v186 offset:176
	ds_read_b128 v[232:235], v186 offset:4272
	ds_read_b128 v[236:239], v186 offset:8368
	s_waitcnt vmcnt(32)
	s_waitcnt lgkmcnt(0)
	v_fmac_f32_e32 v6, v144, v8
	v_fmac_f32_e32 v7, v144, v12
	v_fmac_f32_e32 v3, v144, v16
	v_fmac_f32_e32 v6, v145, v9
	v_fmac_f32_e32 v7, v145, v13
	v_fmac_f32_e32 v3, v145, v17
	v_fmac_f32_e32 v6, v146, v10
	v_fmac_f32_e32 v7, v146, v14
	v_fmac_f32_e32 v3, v146, v18
	v_fmac_f32_e32 v6, v147, v11
	v_fmac_f32_e32 v7, v147, v15
	v_fmac_f32_e32 v3, v147, v19
	v_fmac_f32_e32 v6, v148, v20
	v_fmac_f32_e32 v7, v148, v24
	v_fmac_f32_e32 v3, v148, v28
	v_fmac_f32_e32 v6, v149, v21
	v_fmac_f32_e32 v7, v149, v25
	v_fmac_f32_e32 v3, v149, v29
	v_fmac_f32_e32 v6, v150, v22
	v_fmac_f32_e32 v7, v150, v26
	v_fmac_f32_e32 v3, v150, v30
	v_fmac_f32_e32 v6, v151, v23
	v_fmac_f32_e32 v7, v151, v27
	v_fmac_f32_e32 v3, v151, v31
	v_fmac_f32_e32 v6, v152, v188
	v_fmac_f32_e32 v7, v152, v192
	v_fmac_f32_e32 v3, v152, v196
	v_fmac_f32_e32 v6, v153, v189
	v_fmac_f32_e32 v7, v153, v193
	v_fmac_f32_e32 v3, v153, v197
	v_fmac_f32_e32 v6, v154, v190
	v_fmac_f32_e32 v7, v154, v194
	v_fmac_f32_e32 v3, v154, v198
	v_fmac_f32_e32 v6, v155, v191
	v_fmac_f32_e32 v7, v155, v195
	v_fmac_f32_e32 v3, v155, v199
	v_fmac_f32_e32 v6, v156, v228
	v_fmac_f32_e32 v7, v156, v232
	v_fmac_f32_e32 v3, v156, v236
	v_fmac_f32_e32 v6, v157, v229
	v_fmac_f32_e32 v7, v157, v233
	v_fmac_f32_e32 v3, v157, v237
	v_fmac_f32_e32 v6, v158, v230
	v_fmac_f32_e32 v7, v158, v234
	v_fmac_f32_e32 v3, v158, v238
	v_fmac_f32_e32 v6, v159, v231
	v_fmac_f32_e32 v7, v159, v235
	v_fmac_f32_e32 v3, v159, v239
	global_load_dword v144, v[184:185], off
	v_add_co_u32_e32 v184, vcc, 0x6000, v184
	s_nop 1
	v_addc_co_u32_e32 v185, vcc, 0, v185, vcc
	global_load_dword v145, v[184:185], off
	v_add_co_u32_e32 v184, vcc, 0x6000, v184
	s_nop 1
	v_addc_co_u32_e32 v185, vcc, 0, v185, vcc
	global_load_dword v146, v[184:185], off
	v_add_co_u32_e32 v184, vcc, 0x6000, v184
	s_nop 1
	v_addc_co_u32_e32 v185, vcc, 0, v185, vcc
	global_load_dword v147, v[184:185], off
	v_add_co_u32_e32 v184, vcc, 0x6000, v184
	s_nop 1
	v_addc_co_u32_e32 v185, vcc, 0, v185, vcc
	global_load_dword v148, v[184:185], off
	v_add_co_u32_e32 v184, vcc, 0x6000, v184
	s_nop 1
	v_addc_co_u32_e32 v185, vcc, 0, v185, vcc
	global_load_dword v149, v[184:185], off
	v_add_co_u32_e32 v184, vcc, 0x6000, v184
	s_nop 1
	v_addc_co_u32_e32 v185, vcc, 0, v185, vcc
	global_load_dword v150, v[184:185], off
	v_add_co_u32_e32 v184, vcc, 0x6000, v184
	s_nop 1
	v_addc_co_u32_e32 v185, vcc, 0, v185, vcc
	global_load_dword v151, v[184:185], off
	v_add_co_u32_e32 v184, vcc, 0x6000, v184
	s_nop 1
	v_addc_co_u32_e32 v185, vcc, 0, v185, vcc
	global_load_dword v152, v[184:185], off
	v_add_co_u32_e32 v184, vcc, 0x6000, v184
	s_nop 1
	v_addc_co_u32_e32 v185, vcc, 0, v185, vcc
	global_load_dword v153, v[184:185], off
	v_add_co_u32_e32 v184, vcc, 0x6000, v184
	s_nop 1
	v_addc_co_u32_e32 v185, vcc, 0, v185, vcc
	global_load_dword v154, v[184:185], off
	v_add_co_u32_e32 v184, vcc, 0x6000, v184
	s_nop 1
	v_addc_co_u32_e32 v185, vcc, 0, v185, vcc
	global_load_dword v155, v[184:185], off
	v_add_co_u32_e32 v184, vcc, 0x6000, v184
	s_nop 1
	v_addc_co_u32_e32 v185, vcc, 0, v185, vcc
	global_load_dword v156, v[184:185], off
	v_add_co_u32_e32 v184, vcc, 0x6000, v184
	s_nop 1
	v_addc_co_u32_e32 v185, vcc, 0, v185, vcc
	global_load_dword v157, v[184:185], off
	v_add_co_u32_e32 v184, vcc, 0x6000, v184
	s_nop 1
	v_addc_co_u32_e32 v185, vcc, 0, v185, vcc
	global_load_dword v158, v[184:185], off
	v_add_co_u32_e32 v184, vcc, 0x6000, v184
	s_nop 1
	v_addc_co_u32_e32 v185, vcc, 0, v185, vcc
	global_load_dword v159, v[184:185], off
	v_add_co_u32_e32 v184, vcc, 0x6000, v184
	s_nop 1
	v_addc_co_u32_e32 v185, vcc, 0, v185, vcc
	ds_read_b128 v[8:11], v186 offset:192
	ds_read_b128 v[12:15], v186 offset:4288
	ds_read_b128 v[16:19], v186 offset:8384
	ds_read_b128 v[20:23], v186 offset:208
	ds_read_b128 v[24:27], v186 offset:4304
	ds_read_b128 v[28:31], v186 offset:8400
	ds_read_b128 v[188:191], v186 offset:224
	ds_read_b128 v[192:195], v186 offset:4320
	ds_read_b128 v[196:199], v186 offset:8416
	ds_read_b128 v[228:231], v186 offset:240
	ds_read_b128 v[232:235], v186 offset:4336
	ds_read_b128 v[236:239], v186 offset:8432
	s_waitcnt vmcnt(32)
	s_waitcnt lgkmcnt(0)
	v_fmac_f32_e32 v6, v112, v8
	v_fmac_f32_e32 v7, v112, v12
	v_fmac_f32_e32 v3, v112, v16
	v_fmac_f32_e32 v6, v113, v9
	v_fmac_f32_e32 v7, v113, v13
	v_fmac_f32_e32 v3, v113, v17
	v_fmac_f32_e32 v6, v114, v10
	v_fmac_f32_e32 v7, v114, v14
	v_fmac_f32_e32 v3, v114, v18
	v_fmac_f32_e32 v6, v115, v11
	v_fmac_f32_e32 v7, v115, v15
	v_fmac_f32_e32 v3, v115, v19
	v_fmac_f32_e32 v6, v116, v20
	v_fmac_f32_e32 v7, v116, v24
	v_fmac_f32_e32 v3, v116, v28
	v_fmac_f32_e32 v6, v117, v21
	v_fmac_f32_e32 v7, v117, v25
	v_fmac_f32_e32 v3, v117, v29
	v_fmac_f32_e32 v6, v118, v22
	v_fmac_f32_e32 v7, v118, v26
	v_fmac_f32_e32 v3, v118, v30
	v_fmac_f32_e32 v6, v119, v23
	v_fmac_f32_e32 v7, v119, v27
	v_fmac_f32_e32 v3, v119, v31
	v_fmac_f32_e32 v6, v120, v188
	v_fmac_f32_e32 v7, v120, v192
	v_fmac_f32_e32 v3, v120, v196
	v_fmac_f32_e32 v6, v121, v189
	v_fmac_f32_e32 v7, v121, v193
	v_fmac_f32_e32 v3, v121, v197
	v_fmac_f32_e32 v6, v122, v190
	v_fmac_f32_e32 v7, v122, v194
	v_fmac_f32_e32 v3, v122, v198
	v_fmac_f32_e32 v6, v123, v191
	v_fmac_f32_e32 v7, v123, v195
	v_fmac_f32_e32 v3, v123, v199
	v_fmac_f32_e32 v6, v124, v228
	v_fmac_f32_e32 v7, v124, v232
	v_fmac_f32_e32 v3, v124, v236
	v_fmac_f32_e32 v6, v125, v229
	v_fmac_f32_e32 v7, v125, v233
	v_fmac_f32_e32 v3, v125, v237
	v_fmac_f32_e32 v6, v126, v230
	v_fmac_f32_e32 v7, v126, v234
	v_fmac_f32_e32 v3, v126, v238
	v_fmac_f32_e32 v6, v127, v231
	v_fmac_f32_e32 v7, v127, v235
	v_fmac_f32_e32 v3, v127, v239
	global_load_dword v112, v[184:185], off
	v_add_co_u32_e32 v184, vcc, 0x6000, v184
	s_nop 1
	v_addc_co_u32_e32 v185, vcc, 0, v185, vcc
	global_load_dword v113, v[184:185], off
	v_add_co_u32_e32 v184, vcc, 0x6000, v184
	s_nop 1
	v_addc_co_u32_e32 v185, vcc, 0, v185, vcc
	global_load_dword v114, v[184:185], off
	v_add_co_u32_e32 v184, vcc, 0x6000, v184
	s_nop 1
	v_addc_co_u32_e32 v185, vcc, 0, v185, vcc
	global_load_dword v115, v[184:185], off
	v_add_co_u32_e32 v184, vcc, 0x6000, v184
	s_nop 1
	v_addc_co_u32_e32 v185, vcc, 0, v185, vcc
	global_load_dword v116, v[184:185], off
	v_add_co_u32_e32 v184, vcc, 0x6000, v184
	s_nop 1
	v_addc_co_u32_e32 v185, vcc, 0, v185, vcc
	global_load_dword v117, v[184:185], off
	v_add_co_u32_e32 v184, vcc, 0x6000, v184
	s_nop 1
	v_addc_co_u32_e32 v185, vcc, 0, v185, vcc
	global_load_dword v118, v[184:185], off
	v_add_co_u32_e32 v184, vcc, 0x6000, v184
	s_nop 1
	v_addc_co_u32_e32 v185, vcc, 0, v185, vcc
	global_load_dword v119, v[184:185], off
	v_add_co_u32_e32 v184, vcc, 0x6000, v184
	s_nop 1
	v_addc_co_u32_e32 v185, vcc, 0, v185, vcc
	global_load_dword v120, v[184:185], off
	v_add_co_u32_e32 v184, vcc, 0x6000, v184
	s_nop 1
	v_addc_co_u32_e32 v185, vcc, 0, v185, vcc
	global_load_dword v121, v[184:185], off
	v_add_co_u32_e32 v184, vcc, 0x6000, v184
	s_nop 1
	v_addc_co_u32_e32 v185, vcc, 0, v185, vcc
	global_load_dword v122, v[184:185], off
	v_add_co_u32_e32 v184, vcc, 0x6000, v184
	s_nop 1
	v_addc_co_u32_e32 v185, vcc, 0, v185, vcc
	global_load_dword v123, v[184:185], off
	v_add_co_u32_e32 v184, vcc, 0x6000, v184
	s_nop 1
	v_addc_co_u32_e32 v185, vcc, 0, v185, vcc
	global_load_dword v124, v[184:185], off
	v_add_co_u32_e32 v184, vcc, 0x6000, v184
	s_nop 1
	v_addc_co_u32_e32 v185, vcc, 0, v185, vcc
	global_load_dword v125, v[184:185], off
	v_add_co_u32_e32 v184, vcc, 0x6000, v184
	s_nop 1
	v_addc_co_u32_e32 v185, vcc, 0, v185, vcc
	global_load_dword v126, v[184:185], off
	v_add_co_u32_e32 v184, vcc, 0x6000, v184
	s_nop 1
	v_addc_co_u32_e32 v185, vcc, 0, v185, vcc
	global_load_dword v127, v[184:185], off
	v_add_co_u32_e32 v184, vcc, 0x6000, v184
	s_nop 1
	v_addc_co_u32_e32 v185, vcc, 0, v185, vcc
	ds_read_b128 v[8:11], v186 offset:256
	ds_read_b128 v[12:15], v186 offset:4352
	ds_read_b128 v[16:19], v186 offset:8448
	ds_read_b128 v[20:23], v186 offset:272
	ds_read_b128 v[24:27], v186 offset:4368
	ds_read_b128 v[28:31], v186 offset:8464
	ds_read_b128 v[188:191], v186 offset:288
	ds_read_b128 v[192:195], v186 offset:4384
	ds_read_b128 v[196:199], v186 offset:8480
	ds_read_b128 v[228:231], v186 offset:304
	ds_read_b128 v[232:235], v186 offset:4400
	ds_read_b128 v[236:239], v186 offset:8496
	s_waitcnt vmcnt(32)
	s_waitcnt lgkmcnt(0)
	v_fmac_f32_e32 v6, v128, v8
	v_fmac_f32_e32 v7, v128, v12
	v_fmac_f32_e32 v3, v128, v16
	v_fmac_f32_e32 v6, v129, v9
	v_fmac_f32_e32 v7, v129, v13
	v_fmac_f32_e32 v3, v129, v17
	v_fmac_f32_e32 v6, v130, v10
	v_fmac_f32_e32 v7, v130, v14
	v_fmac_f32_e32 v3, v130, v18
	v_fmac_f32_e32 v6, v131, v11
	v_fmac_f32_e32 v7, v131, v15
	v_fmac_f32_e32 v3, v131, v19
	v_fmac_f32_e32 v6, v132, v20
	v_fmac_f32_e32 v7, v132, v24
	v_fmac_f32_e32 v3, v132, v28
	v_fmac_f32_e32 v6, v133, v21
	v_fmac_f32_e32 v7, v133, v25
	v_fmac_f32_e32 v3, v133, v29
	v_fmac_f32_e32 v6, v134, v22
	v_fmac_f32_e32 v7, v134, v26
	v_fmac_f32_e32 v3, v134, v30
	v_fmac_f32_e32 v6, v135, v23
	v_fmac_f32_e32 v7, v135, v27
	v_fmac_f32_e32 v3, v135, v31
	v_fmac_f32_e32 v6, v136, v188
	v_fmac_f32_e32 v7, v136, v192
	v_fmac_f32_e32 v3, v136, v196
	v_fmac_f32_e32 v6, v137, v189
	v_fmac_f32_e32 v7, v137, v193
	v_fmac_f32_e32 v3, v137, v197
	v_fmac_f32_e32 v6, v138, v190
	v_fmac_f32_e32 v7, v138, v194
	v_fmac_f32_e32 v3, v138, v198
	v_fmac_f32_e32 v6, v139, v191
	v_fmac_f32_e32 v7, v139, v195
	v_fmac_f32_e32 v3, v139, v199
	v_fmac_f32_e32 v6, v140, v228
	v_fmac_f32_e32 v7, v140, v232
	v_fmac_f32_e32 v3, v140, v236
	v_fmac_f32_e32 v6, v141, v229
	v_fmac_f32_e32 v7, v141, v233
	v_fmac_f32_e32 v3, v141, v237
	v_fmac_f32_e32 v6, v142, v230
	v_fmac_f32_e32 v7, v142, v234
	v_fmac_f32_e32 v3, v142, v238
	v_fmac_f32_e32 v6, v143, v231
	v_fmac_f32_e32 v7, v143, v235
	v_fmac_f32_e32 v3, v143, v239
	global_load_dword v128, v[184:185], off
	v_add_co_u32_e32 v184, vcc, 0x6000, v184
	s_nop 1
	v_addc_co_u32_e32 v185, vcc, 0, v185, vcc
	global_load_dword v129, v[184:185], off
	v_add_co_u32_e32 v184, vcc, 0x6000, v184
	s_nop 1
	v_addc_co_u32_e32 v185, vcc, 0, v185, vcc
	global_load_dword v130, v[184:185], off
	v_add_co_u32_e32 v184, vcc, 0x6000, v184
	s_nop 1
	v_addc_co_u32_e32 v185, vcc, 0, v185, vcc
	global_load_dword v131, v[184:185], off
	v_add_co_u32_e32 v184, vcc, 0x6000, v184
	s_nop 1
	v_addc_co_u32_e32 v185, vcc, 0, v185, vcc
	global_load_dword v132, v[184:185], off
	v_add_co_u32_e32 v184, vcc, 0x6000, v184
	s_nop 1
	v_addc_co_u32_e32 v185, vcc, 0, v185, vcc
	global_load_dword v133, v[184:185], off
	v_add_co_u32_e32 v184, vcc, 0x6000, v184
	s_nop 1
	v_addc_co_u32_e32 v185, vcc, 0, v185, vcc
	global_load_dword v134, v[184:185], off
	v_add_co_u32_e32 v184, vcc, 0x6000, v184
	s_nop 1
	v_addc_co_u32_e32 v185, vcc, 0, v185, vcc
	global_load_dword v135, v[184:185], off
	v_add_co_u32_e32 v184, vcc, 0x6000, v184
	s_nop 1
	v_addc_co_u32_e32 v185, vcc, 0, v185, vcc
	global_load_dword v136, v[184:185], off
	v_add_co_u32_e32 v184, vcc, 0x6000, v184
	s_nop 1
	v_addc_co_u32_e32 v185, vcc, 0, v185, vcc
	global_load_dword v137, v[184:185], off
	v_add_co_u32_e32 v184, vcc, 0x6000, v184
	s_nop 1
	v_addc_co_u32_e32 v185, vcc, 0, v185, vcc
	global_load_dword v138, v[184:185], off
	v_add_co_u32_e32 v184, vcc, 0x6000, v184
	s_nop 1
	v_addc_co_u32_e32 v185, vcc, 0, v185, vcc
	global_load_dword v139, v[184:185], off
	v_add_co_u32_e32 v184, vcc, 0x6000, v184
	s_nop 1
	v_addc_co_u32_e32 v185, vcc, 0, v185, vcc
	global_load_dword v140, v[184:185], off
	v_add_co_u32_e32 v184, vcc, 0x6000, v184
	s_nop 1
	v_addc_co_u32_e32 v185, vcc, 0, v185, vcc
	global_load_dword v141, v[184:185], off
	v_add_co_u32_e32 v184, vcc, 0x6000, v184
	s_nop 1
	v_addc_co_u32_e32 v185, vcc, 0, v185, vcc
	global_load_dword v142, v[184:185], off
	v_add_co_u32_e32 v184, vcc, 0x6000, v184
	s_nop 1
	v_addc_co_u32_e32 v185, vcc, 0, v185, vcc
	global_load_dword v143, v[184:185], off
	v_add_co_u32_e32 v184, vcc, 0x6000, v184
	s_nop 1
	v_addc_co_u32_e32 v185, vcc, 0, v185, vcc
	ds_read_b128 v[8:11], v186 offset:320
	ds_read_b128 v[12:15], v186 offset:4416
	ds_read_b128 v[16:19], v186 offset:8512
	ds_read_b128 v[20:23], v186 offset:336
	ds_read_b128 v[24:27], v186 offset:4432
	ds_read_b128 v[28:31], v186 offset:8528
	ds_read_b128 v[188:191], v186 offset:352
	ds_read_b128 v[192:195], v186 offset:4448
	ds_read_b128 v[196:199], v186 offset:8544
	ds_read_b128 v[228:231], v186 offset:368
	ds_read_b128 v[232:235], v186 offset:4464
	ds_read_b128 v[236:239], v186 offset:8560
	s_waitcnt vmcnt(32)
	s_waitcnt lgkmcnt(0)
	v_fmac_f32_e32 v6, v144, v8
	v_fmac_f32_e32 v7, v144, v12
	v_fmac_f32_e32 v3, v144, v16
	v_fmac_f32_e32 v6, v145, v9
	v_fmac_f32_e32 v7, v145, v13
	v_fmac_f32_e32 v3, v145, v17
	v_fmac_f32_e32 v6, v146, v10
	v_fmac_f32_e32 v7, v146, v14
	v_fmac_f32_e32 v3, v146, v18
	v_fmac_f32_e32 v6, v147, v11
	v_fmac_f32_e32 v7, v147, v15
	v_fmac_f32_e32 v3, v147, v19
	v_fmac_f32_e32 v6, v148, v20
	v_fmac_f32_e32 v7, v148, v24
	v_fmac_f32_e32 v3, v148, v28
	v_fmac_f32_e32 v6, v149, v21
	v_fmac_f32_e32 v7, v149, v25
	v_fmac_f32_e32 v3, v149, v29
	v_fmac_f32_e32 v6, v150, v22
	v_fmac_f32_e32 v7, v150, v26
	v_fmac_f32_e32 v3, v150, v30
	v_fmac_f32_e32 v6, v151, v23
	v_fmac_f32_e32 v7, v151, v27
	v_fmac_f32_e32 v3, v151, v31
	v_fmac_f32_e32 v6, v152, v188
	v_fmac_f32_e32 v7, v152, v192
	v_fmac_f32_e32 v3, v152, v196
	v_fmac_f32_e32 v6, v153, v189
	v_fmac_f32_e32 v7, v153, v193
	v_fmac_f32_e32 v3, v153, v197
	v_fmac_f32_e32 v6, v154, v190
	v_fmac_f32_e32 v7, v154, v194
	v_fmac_f32_e32 v3, v154, v198
	v_fmac_f32_e32 v6, v155, v191
	v_fmac_f32_e32 v7, v155, v195
	v_fmac_f32_e32 v3, v155, v199
	v_fmac_f32_e32 v6, v156, v228
	v_fmac_f32_e32 v7, v156, v232
	v_fmac_f32_e32 v3, v156, v236
	v_fmac_f32_e32 v6, v157, v229
	v_fmac_f32_e32 v7, v157, v233
	v_fmac_f32_e32 v3, v157, v237
	v_fmac_f32_e32 v6, v158, v230
	v_fmac_f32_e32 v7, v158, v234
	v_fmac_f32_e32 v3, v158, v238
	v_fmac_f32_e32 v6, v159, v231
	v_fmac_f32_e32 v7, v159, v235
	v_fmac_f32_e32 v3, v159, v239
	ds_read_b128 v[8:11], v186 offset:384
	ds_read_b128 v[12:15], v186 offset:4480
	ds_read_b128 v[16:19], v186 offset:8576
	ds_read_b128 v[20:23], v186 offset:400
	ds_read_b128 v[24:27], v186 offset:4496
	ds_read_b128 v[28:31], v186 offset:8592
	ds_read_b128 v[188:191], v186 offset:416
	ds_read_b128 v[192:195], v186 offset:4512
	ds_read_b128 v[196:199], v186 offset:8608
	ds_read_b128 v[228:231], v186 offset:432
	ds_read_b128 v[232:235], v186 offset:4528
	ds_read_b128 v[236:239], v186 offset:8624
	s_waitcnt vmcnt(16)
	s_waitcnt lgkmcnt(0)
	v_fmac_f32_e32 v6, v112, v8
	v_fmac_f32_e32 v7, v112, v12
	v_fmac_f32_e32 v3, v112, v16
	v_fmac_f32_e32 v6, v113, v9
	v_fmac_f32_e32 v7, v113, v13
	v_fmac_f32_e32 v3, v113, v17
	v_fmac_f32_e32 v6, v114, v10
	v_fmac_f32_e32 v7, v114, v14
	v_fmac_f32_e32 v3, v114, v18
	v_fmac_f32_e32 v6, v115, v11
	v_fmac_f32_e32 v7, v115, v15
	v_fmac_f32_e32 v3, v115, v19
	v_fmac_f32_e32 v6, v116, v20
	v_fmac_f32_e32 v7, v116, v24
	v_fmac_f32_e32 v3, v116, v28
	v_fmac_f32_e32 v6, v117, v21
	v_fmac_f32_e32 v7, v117, v25
	v_fmac_f32_e32 v3, v117, v29
	v_fmac_f32_e32 v6, v118, v22
	v_fmac_f32_e32 v7, v118, v26
	v_fmac_f32_e32 v3, v118, v30
	v_fmac_f32_e32 v6, v119, v23
	v_fmac_f32_e32 v7, v119, v27
	v_fmac_f32_e32 v3, v119, v31
	v_fmac_f32_e32 v6, v120, v188
	v_fmac_f32_e32 v7, v120, v192
	v_fmac_f32_e32 v3, v120, v196
	v_fmac_f32_e32 v6, v121, v189
	v_fmac_f32_e32 v7, v121, v193
	v_fmac_f32_e32 v3, v121, v197
	v_fmac_f32_e32 v6, v122, v190
	v_fmac_f32_e32 v7, v122, v194
	v_fmac_f32_e32 v3, v122, v198
	v_fmac_f32_e32 v6, v123, v191
	v_fmac_f32_e32 v7, v123, v195
	v_fmac_f32_e32 v3, v123, v199
	v_fmac_f32_e32 v6, v124, v228
	v_fmac_f32_e32 v7, v124, v232
	v_fmac_f32_e32 v3, v124, v236
	v_fmac_f32_e32 v6, v125, v229
	v_fmac_f32_e32 v7, v125, v233
	v_fmac_f32_e32 v3, v125, v237
	v_fmac_f32_e32 v6, v126, v230
	v_fmac_f32_e32 v7, v126, v234
	v_fmac_f32_e32 v3, v126, v238
	v_fmac_f32_e32 v6, v127, v231
	v_fmac_f32_e32 v7, v127, v235
	v_fmac_f32_e32 v3, v127, v239
	ds_read_b128 v[8:11], v186 offset:448
	ds_read_b128 v[12:15], v186 offset:4544
	ds_read_b128 v[16:19], v186 offset:8640
	ds_read_b128 v[20:23], v186 offset:464
	ds_read_b128 v[24:27], v186 offset:4560
	ds_read_b128 v[28:31], v186 offset:8656
	ds_read_b128 v[188:191], v186 offset:480
	ds_read_b128 v[192:195], v186 offset:4576
	ds_read_b128 v[196:199], v186 offset:8672
	ds_read_b128 v[228:231], v186 offset:496
	ds_read_b128 v[232:235], v186 offset:4592
	ds_read_b128 v[236:239], v186 offset:8688
	s_waitcnt vmcnt(0)
	s_waitcnt lgkmcnt(0)
	v_fmac_f32_e32 v6, v128, v8
	v_fmac_f32_e32 v7, v128, v12
	v_fmac_f32_e32 v3, v128, v16
	v_fmac_f32_e32 v6, v129, v9
	v_fmac_f32_e32 v7, v129, v13
	v_fmac_f32_e32 v3, v129, v17
	v_fmac_f32_e32 v6, v130, v10
	v_fmac_f32_e32 v7, v130, v14
	v_fmac_f32_e32 v3, v130, v18
	v_fmac_f32_e32 v6, v131, v11
	v_fmac_f32_e32 v7, v131, v15
	v_fmac_f32_e32 v3, v131, v19
	v_fmac_f32_e32 v6, v132, v20
	v_fmac_f32_e32 v7, v132, v24
	v_fmac_f32_e32 v3, v132, v28
	v_fmac_f32_e32 v6, v133, v21
	v_fmac_f32_e32 v7, v133, v25
	v_fmac_f32_e32 v3, v133, v29
	v_fmac_f32_e32 v6, v134, v22
	v_fmac_f32_e32 v7, v134, v26
	v_fmac_f32_e32 v3, v134, v30
	v_fmac_f32_e32 v6, v135, v23
	v_fmac_f32_e32 v7, v135, v27
	v_fmac_f32_e32 v3, v135, v31
	v_fmac_f32_e32 v6, v136, v188
	v_fmac_f32_e32 v7, v136, v192
	v_fmac_f32_e32 v3, v136, v196
	v_fmac_f32_e32 v6, v137, v189
	v_fmac_f32_e32 v7, v137, v193
	v_fmac_f32_e32 v3, v137, v197
	v_fmac_f32_e32 v6, v138, v190
	v_fmac_f32_e32 v7, v138, v194
	v_fmac_f32_e32 v3, v138, v198
	v_fmac_f32_e32 v6, v139, v191
	v_fmac_f32_e32 v7, v139, v195
	v_fmac_f32_e32 v3, v139, v199
	v_fmac_f32_e32 v6, v140, v228
	v_fmac_f32_e32 v7, v140, v232
	v_fmac_f32_e32 v3, v140, v236
	v_fmac_f32_e32 v6, v141, v229
	v_fmac_f32_e32 v7, v141, v233
	v_fmac_f32_e32 v3, v141, v237
	v_fmac_f32_e32 v6, v142, v230
	v_fmac_f32_e32 v7, v142, v234
	v_fmac_f32_e32 v3, v142, v238
	v_fmac_f32_e32 v6, v143, v231
	v_fmac_f32_e32 v7, v143, v235
	v_fmac_f32_e32 v3, v143, v239
	ds_write2st64_b32 v35, v6, v7 offset1:1
	ds_write_b32 v35, v3 offset:512
	s_waitcnt lgkmcnt(0)
	s_barrier
	s_and_saveexec_b64 s[18:19], s[40:41]
	s_cbranch_execz .LBB0_1225
	v_mov_b64_e32 v[4:5], s[70:71]
	s_movk_i32 s3, 0x6000
	v_mad_u64_u32 v[4:5], s[12:13], v2, s3, v[4:5]
	v_lshlrev_b32_e32 v0, 2, v0
	v_lshl_add_u64 v[4:5], v[4:5], 0, v[0:1]
	v_lshlrev_b32_e32 v6, 2, v34
	v_mov_b32_e32 v7, v1
	v_lshl_add_u64 v[4:5], v[4:5], 0, v[6:7]
	global_load_dword v14, v[4:5], off
	v_mad_u64_u32 v[2:3], s[12:13], v2, 3, v[36:37]
	v_readlane_b32 s12, v254, 49
	ds_read2st64_b32 v[4:5], v55 offset0:3 offset1:6
	ds_read2st64_b32 v[8:9], v55 offset0:9 offset1:12
	ds_read2st64_b32 v[10:11], v55 offset0:15 offset1:18
	ds_read_b32 v15, v54
	ds_read_b32 v16, v55 offset:5376
	v_readlane_b32 s13, v254, 50
	s_nop 1
	v_mov_b64_e32 v[12:13], s[12:13]
	v_mad_u64_u32 v[12:13], s[12:13], v2, s3, v[12:13]
	v_mad_i32_i24 v13, v3, s3, v13
	v_lshl_add_u64 v[2:3], v[12:13], 0, v[0:1]
	v_lshl_add_u64 v[2:3], v[2:3], 0, v[6:7]
	s_waitcnt vmcnt(0) lgkmcnt(1)
	v_add_f32_e32 v0, v14, v15
	v_add_f32_e32 v0, v0, v4
	v_add_f32_e32 v0, v0, v5
	v_add_f32_e32 v0, v0, v8
	v_add_f32_e32 v0, v0, v9
	v_add_f32_e32 v0, v0, v10
	v_add_f32_e32 v0, v0, v11
	s_waitcnt lgkmcnt(0)
	v_add_f32_e32 v0, v0, v16
	global_store_dword v[2:3], v0, off

.LBB0_1241:
	v_mov_b32_e32 v184, v18
	v_mov_b32_e32 v185, v19
	global_load_dword v112, v[184:185], off
	v_add_co_u32_e32 v184, vcc, 0x1000, v184
	s_nop 1
	v_addc_co_u32_e32 v185, vcc, 0, v185, vcc
	global_load_dword v113, v[184:185], off
	v_add_co_u32_e32 v184, vcc, 0x1000, v184
	s_nop 1
	v_addc_co_u32_e32 v185, vcc, 0, v185, vcc
	global_load_dword v114, v[184:185], off
	v_add_co_u32_e32 v184, vcc, 0x1000, v184
	s_nop 1
	v_addc_co_u32_e32 v185, vcc, 0, v185, vcc
	global_load_dword v115, v[184:185], off
	v_add_co_u32_e32 v184, vcc, 0x1000, v184
	s_nop 1
	v_addc_co_u32_e32 v185, vcc, 0, v185, vcc
	global_load_dword v116, v[184:185], off
	v_add_co_u32_e32 v184, vcc, 0x1000, v184
	s_nop 1
	v_addc_co_u32_e32 v185, vcc, 0, v185, vcc
	global_load_dword v117, v[184:185], off
	v_add_co_u32_e32 v184, vcc, 0x1000, v184
	s_nop 1
	v_addc_co_u32_e32 v185, vcc, 0, v185, vcc
	global_load_dword v118, v[184:185], off
	v_add_co_u32_e32 v184, vcc, 0x1000, v184
	s_nop 1
	v_addc_co_u32_e32 v185, vcc, 0, v185, vcc
	global_load_dword v119, v[184:185], off
	v_add_co_u32_e32 v184, vcc, 0x1000, v184
	s_nop 1
	v_addc_co_u32_e32 v185, vcc, 0, v185, vcc
	global_load_dword v120, v[184:185], off
	v_add_co_u32_e32 v184, vcc, 0x1000, v184
	s_nop 1
	v_addc_co_u32_e32 v185, vcc, 0, v185, vcc
	global_load_dword v121, v[184:185], off
	v_add_co_u32_e32 v184, vcc, 0x1000, v184
	s_nop 1
	v_addc_co_u32_e32 v185, vcc, 0, v185, vcc
	global_load_dword v122, v[184:185], off
	v_add_co_u32_e32 v184, vcc, 0x1000, v184
	s_nop 1
	v_addc_co_u32_e32 v185, vcc, 0, v185, vcc
	global_load_dword v123, v[184:185], off
	v_add_co_u32_e32 v184, vcc, 0x1000, v184
	s_nop 1
	v_addc_co_u32_e32 v185, vcc, 0, v185, vcc
	global_load_dword v124, v[184:185], off
	v_add_co_u32_e32 v184, vcc, 0x1000, v184
	s_nop 1
	v_addc_co_u32_e32 v185, vcc, 0, v185, vcc
	global_load_dword v125, v[184:185], off
	v_add_co_u32_e32 v184, vcc, 0x1000, v184
	s_nop 1
	v_addc_co_u32_e32 v185, vcc, 0, v185, vcc
	global_load_dword v126, v[184:185], off
	v_add_co_u32_e32 v184, vcc, 0x1000, v184
	s_nop 1
	v_addc_co_u32_e32 v185, vcc, 0, v185, vcc
	global_load_dword v127, v[184:185], off
	v_add_co_u32_e32 v184, vcc, 0x1000, v184
	s_nop 1
	v_addc_co_u32_e32 v185, vcc, 0, v185, vcc
	global_load_dword v128, v[184:185], off
	v_add_co_u32_e32 v184, vcc, 0x1000, v184
	s_nop 1
	v_addc_co_u32_e32 v185, vcc, 0, v185, vcc
	global_load_dword v129, v[184:185], off
	v_add_co_u32_e32 v184, vcc, 0x1000, v184
	s_nop 1
	v_addc_co_u32_e32 v185, vcc, 0, v185, vcc
	global_load_dword v130, v[184:185], off
	v_add_co_u32_e32 v184, vcc, 0x1000, v184
	s_nop 1
	v_addc_co_u32_e32 v185, vcc, 0, v185, vcc
	global_load_dword v131, v[184:185], off
	v_add_co_u32_e32 v184, vcc, 0x1000, v184
	s_nop 1
	v_addc_co_u32_e32 v185, vcc, 0, v185, vcc
	global_load_dword v132, v[184:185], off
	v_add_co_u32_e32 v184, vcc, 0x1000, v184
	s_nop 1
	v_addc_co_u32_e32 v185, vcc, 0, v185, vcc
	global_load_dword v133, v[184:185], off
	v_add_co_u32_e32 v184, vcc, 0x1000, v184
	s_nop 1
	v_addc_co_u32_e32 v185, vcc, 0, v185, vcc
	global_load_dword v134, v[184:185], off
	v_add_co_u32_e32 v184, vcc, 0x1000, v184
	s_nop 1
	v_addc_co_u32_e32 v185, vcc, 0, v185, vcc
	global_load_dword v135, v[184:185], off
	v_add_co_u32_e32 v184, vcc, 0x1000, v184
	s_nop 1
	v_addc_co_u32_e32 v185, vcc, 0, v185, vcc
	global_load_dword v136, v[184:185], off
	v_add_co_u32_e32 v184, vcc, 0x1000, v184
	s_nop 1
	v_addc_co_u32_e32 v185, vcc, 0, v185, vcc
	global_load_dword v137, v[184:185], off
	v_add_co_u32_e32 v184, vcc, 0x1000, v184
	s_nop 1
	v_addc_co_u32_e32 v185, vcc, 0, v185, vcc
	global_load_dword v138, v[184:185], off
	v_add_co_u32_e32 v184, vcc, 0x1000, v184
	s_nop 1
	v_addc_co_u32_e32 v185, vcc, 0, v185, vcc
	global_load_dword v139, v[184:185], off
	v_add_co_u32_e32 v184, vcc, 0x1000, v184
	s_nop 1
	v_addc_co_u32_e32 v185, vcc, 0, v185, vcc
	global_load_dword v140, v[184:185], off
	v_add_co_u32_e32 v184, vcc, 0x1000, v184
	s_nop 1
	v_addc_co_u32_e32 v185, vcc, 0, v185, vcc
	global_load_dword v141, v[184:185], off
	v_add_co_u32_e32 v184, vcc, 0x1000, v184
	s_nop 1
	v_addc_co_u32_e32 v185, vcc, 0, v185, vcc
	global_load_dword v142, v[184:185], off
	v_add_co_u32_e32 v184, vcc, 0x1000, v184
	s_nop 1
	v_addc_co_u32_e32 v185, vcc, 0, v185, vcc
	global_load_dword v143, v[184:185], off
	v_add_co_u32_e32 v184, vcc, 0x1000, v184
	s_nop 1
	v_addc_co_u32_e32 v185, vcc, 0, v185, vcc
	global_load_dword v144, v[184:185], off
	v_add_co_u32_e32 v184, vcc, 0x1000, v184
	s_nop 1
	v_addc_co_u32_e32 v185, vcc, 0, v185, vcc
	global_load_dword v145, v[184:185], off
	v_add_co_u32_e32 v184, vcc, 0x1000, v184
	s_nop 1
	v_addc_co_u32_e32 v185, vcc, 0, v185, vcc
	global_load_dword v146, v[184:185], off
	v_add_co_u32_e32 v184, vcc, 0x1000, v184
	s_nop 1
	v_addc_co_u32_e32 v185, vcc, 0, v185, vcc
	global_load_dword v147, v[184:185], off
	v_add_co_u32_e32 v184, vcc, 0x1000, v184
	s_nop 1
	v_addc_co_u32_e32 v185, vcc, 0, v185, vcc
	global_load_dword v148, v[184:185], off
	v_add_co_u32_e32 v184, vcc, 0x1000, v184
	s_nop 1
	v_addc_co_u32_e32 v185, vcc, 0, v185, vcc
	global_load_dword v149, v[184:185], off
	v_add_co_u32_e32 v184, vcc, 0x1000, v184
	s_nop 1
	v_addc_co_u32_e32 v185, vcc, 0, v185, vcc
	global_load_dword v150, v[184:185], off
	v_add_co_u32_e32 v184, vcc, 0x1000, v184
	s_nop 1
	v_addc_co_u32_e32 v185, vcc, 0, v185, vcc
	global_load_dword v151, v[184:185], off
	v_add_co_u32_e32 v184, vcc, 0x1000, v184
	s_nop 1
	v_addc_co_u32_e32 v185, vcc, 0, v185, vcc
	global_load_dword v152, v[184:185], off
	v_add_co_u32_e32 v184, vcc, 0x1000, v184
	s_nop 1
	v_addc_co_u32_e32 v185, vcc, 0, v185, vcc
	global_load_dword v153, v[184:185], off
	v_add_co_u32_e32 v184, vcc, 0x1000, v184
	s_nop 1
	v_addc_co_u32_e32 v185, vcc, 0, v185, vcc
	global_load_dword v154, v[184:185], off
	v_add_co_u32_e32 v184, vcc, 0x1000, v184
	s_nop 1
	v_addc_co_u32_e32 v185, vcc, 0, v185, vcc
	global_load_dword v155, v[184:185], off
	v_add_co_u32_e32 v184, vcc, 0x1000, v184
	s_nop 1
	v_addc_co_u32_e32 v185, vcc, 0, v185, vcc
	global_load_dword v156, v[184:185], off
	v_add_co_u32_e32 v184, vcc, 0x1000, v184
	s_nop 1
	v_addc_co_u32_e32 v185, vcc, 0, v185, vcc
	global_load_dword v157, v[184:185], off
	v_add_co_u32_e32 v184, vcc, 0x1000, v184
	s_nop 1
	v_addc_co_u32_e32 v185, vcc, 0, v185, vcc
	global_load_dword v158, v[184:185], off
	v_add_co_u32_e32 v184, vcc, 0x1000, v184
	s_nop 1
	v_addc_co_u32_e32 v185, vcc, 0, v185, vcc
	global_load_dword v159, v[184:185], off
	v_add_co_u32_e32 v184, vcc, 0x1000, v184
	s_nop 1
	v_addc_co_u32_e32 v185, vcc, 0, v185, vcc
	global_load_dword v160, v[184:185], off
	v_add_co_u32_e32 v184, vcc, 0x1000, v184
	s_nop 1
	v_addc_co_u32_e32 v185, vcc, 0, v185, vcc
	global_load_dword v161, v[184:185], off
	v_add_co_u32_e32 v184, vcc, 0x1000, v184
	s_nop 1
	v_addc_co_u32_e32 v185, vcc, 0, v185, vcc
	global_load_dword v162, v[184:185], off
	v_add_co_u32_e32 v184, vcc, 0x1000, v184
	s_nop 1
	v_addc_co_u32_e32 v185, vcc, 0, v185, vcc
	global_load_dword v163, v[184:185], off
	v_add_co_u32_e32 v184, vcc, 0x1000, v184
	s_nop 1
	v_addc_co_u32_e32 v185, vcc, 0, v185, vcc
	global_load_dword v164, v[184:185], off
	v_add_co_u32_e32 v184, vcc, 0x1000, v184
	s_nop 1
	v_addc_co_u32_e32 v185, vcc, 0, v185, vcc
	global_load_dword v165, v[184:185], off
	v_add_co_u32_e32 v184, vcc, 0x1000, v184
	s_nop 1
	v_addc_co_u32_e32 v185, vcc, 0, v185, vcc
	global_load_dword v166, v[184:185], off
	v_add_co_u32_e32 v184, vcc, 0x1000, v184
	s_nop 1
	v_addc_co_u32_e32 v185, vcc, 0, v185, vcc
	global_load_dword v167, v[184:185], off
	v_add_co_u32_e32 v184, vcc, 0x1000, v184
	s_nop 1
	v_addc_co_u32_e32 v185, vcc, 0, v185, vcc
	global_load_dword v168, v[184:185], off
	v_add_co_u32_e32 v184, vcc, 0x1000, v184
	s_nop 1
	v_addc_co_u32_e32 v185, vcc, 0, v185, vcc
	global_load_dword v169, v[184:185], off
	v_add_co_u32_e32 v184, vcc, 0x1000, v184
	s_nop 1
	v_addc_co_u32_e32 v185, vcc, 0, v185, vcc
	global_load_dword v175, v[184:185], off
	v_add_co_u32_e32 v184, vcc, 0x1000, v184
	s_nop 1
	v_addc_co_u32_e32 v185, vcc, 0, v185, vcc
	global_load_dword v176, v[184:185], off
	v_add_co_u32_e32 v184, vcc, 0x1000, v184
	s_nop 1
	v_addc_co_u32_e32 v185, vcc, 0, v185, vcc
	global_load_dword v177, v[184:185], off
	v_add_co_u32_e32 v184, vcc, 0x1000, v184
	s_nop 1
	v_addc_co_u32_e32 v185, vcc, 0, v185, vcc
	global_load_dword v178, v[184:185], off
	v_add_co_u32_e32 v184, vcc, 0x1000, v184
	s_nop 1
	v_addc_co_u32_e32 v185, vcc, 0, v185, vcc
	global_load_dword v179, v[184:185], off
	v_add_co_u32_e32 v184, vcc, 0x1000, v184
	s_nop 1
	v_addc_co_u32_e32 v185, vcc, 0, v185, vcc
	global_load_dword v180, v[184:185], off
	v_add_co_u32_e32 v184, vcc, 0x1000, v184
	s_nop 1
	v_addc_co_u32_e32 v185, vcc, 0, v185, vcc
	v_mov_b32_e32 v3, 0
	ds_read_b128 v[22:25], v3 offset:3328
	ds_read_b128 v[26:29], v3 offset:3584
	ds_read_b128 v[30:33], v3 offset:3840
	ds_read_b128 v[46:49], v3 offset:4096
	ds_read_b128 v[50:53], v3 offset:4352
	ds_read_b128 v[66:69], v3 offset:4608
	ds_read_b128 v[70:73], v3 offset:4864
	ds_read_b128 v[74:77], v3 offset:5120
	s_waitcnt vmcnt(60)
	s_waitcnt lgkmcnt(0)
	v_fmac_f32_e32 v14, v112, v22
	v_fmac_f32_e32 v15, v112, v26
	v_fmac_f32_e32 v12, v112, v30
	v_fmac_f32_e32 v13, v112, v46
	v_fmac_f32_e32 v10, v112, v50
	v_fmac_f32_e32 v11, v112, v66
	v_fmac_f32_e32 v8, v112, v70
	v_fmac_f32_e32 v9, v112, v74
	v_fmac_f32_e32 v14, v113, v23
	v_fmac_f32_e32 v15, v113, v27
	v_fmac_f32_e32 v12, v113, v31
	v_fmac_f32_e32 v13, v113, v47
	v_fmac_f32_e32 v10, v113, v51
	v_fmac_f32_e32 v11, v113, v67
	v_fmac_f32_e32 v8, v113, v71
	v_fmac_f32_e32 v9, v113, v75
	v_fmac_f32_e32 v14, v114, v24
	v_fmac_f32_e32 v15, v114, v28
	v_fmac_f32_e32 v12, v114, v32
	v_fmac_f32_e32 v13, v114, v48
	v_fmac_f32_e32 v10, v114, v52
	v_fmac_f32_e32 v11, v114, v68
	v_fmac_f32_e32 v8, v114, v72
	v_fmac_f32_e32 v9, v114, v76
	v_fmac_f32_e32 v14, v115, v25
	v_fmac_f32_e32 v15, v115, v29
	v_fmac_f32_e32 v12, v115, v33
	v_fmac_f32_e32 v13, v115, v49
	v_fmac_f32_e32 v10, v115, v53
	v_fmac_f32_e32 v11, v115, v69
	v_fmac_f32_e32 v8, v115, v73
	v_fmac_f32_e32 v9, v115, v77
	v_mov_b32_e32 v3, 16
	ds_read_b128 v[22:25], v3 offset:3328
	ds_read_b128 v[26:29], v3 offset:3584
	ds_read_b128 v[30:33], v3 offset:3840
	ds_read_b128 v[46:49], v3 offset:4096
	ds_read_b128 v[50:53], v3 offset:4352
	ds_read_b128 v[66:69], v3 offset:4608
	ds_read_b128 v[70:73], v3 offset:4864
	ds_read_b128 v[74:77], v3 offset:5120
	s_waitcnt vmcnt(56)
	s_waitcnt lgkmcnt(0)
	v_fmac_f32_e32 v14, v116, v22
	v_fmac_f32_e32 v15, v116, v26
	v_fmac_f32_e32 v12, v116, v30
	v_fmac_f32_e32 v13, v116, v46
	v_fmac_f32_e32 v10, v116, v50
	v_fmac_f32_e32 v11, v116, v66
	v_fmac_f32_e32 v8, v116, v70
	v_fmac_f32_e32 v9, v116, v74
	v_fmac_f32_e32 v14, v117, v23
	v_fmac_f32_e32 v15, v117, v27
	v_fmac_f32_e32 v12, v117, v31
	v_fmac_f32_e32 v13, v117, v47
	v_fmac_f32_e32 v10, v117, v51
	v_fmac_f32_e32 v11, v117, v67
	v_fmac_f32_e32 v8, v117, v71
	v_fmac_f32_e32 v9, v117, v75
	v_fmac_f32_e32 v14, v118, v24
	v_fmac_f32_e32 v15, v118, v28
	v_fmac_f32_e32 v12, v118, v32
	v_fmac_f32_e32 v13, v118, v48
	v_fmac_f32_e32 v10, v118, v52
	v_fmac_f32_e32 v11, v118, v68
	v_fmac_f32_e32 v8, v118, v72
	v_fmac_f32_e32 v9, v118, v76
	v_fmac_f32_e32 v14, v119, v25
	v_fmac_f32_e32 v15, v119, v29
	v_fmac_f32_e32 v12, v119, v33
	v_fmac_f32_e32 v13, v119, v49
	v_fmac_f32_e32 v10, v119, v53
	v_fmac_f32_e32 v11, v119, v69
	v_fmac_f32_e32 v8, v119, v73
	v_fmac_f32_e32 v9, v119, v77
	v_mov_b32_e32 v3, 32
	ds_read_b128 v[22:25], v3 offset:3328
	ds_read_b128 v[26:29], v3 offset:3584
	ds_read_b128 v[30:33], v3 offset:3840
	ds_read_b128 v[46:49], v3 offset:4096
	ds_read_b128 v[50:53], v3 offset:4352
	ds_read_b128 v[66:69], v3 offset:4608
	ds_read_b128 v[70:73], v3 offset:4864
	ds_read_b128 v[74:77], v3 offset:5120
	s_waitcnt vmcnt(52)
	s_waitcnt lgkmcnt(0)
	v_fmac_f32_e32 v14, v120, v22
	v_fmac_f32_e32 v15, v120, v26
	v_fmac_f32_e32 v12, v120, v30
	v_fmac_f32_e32 v13, v120, v46
	v_fmac_f32_e32 v10, v120, v50
	v_fmac_f32_e32 v11, v120, v66
	v_fmac_f32_e32 v8, v120, v70
	v_fmac_f32_e32 v9, v120, v74
	v_fmac_f32_e32 v14, v121, v23
	v_fmac_f32_e32 v15, v121, v27
	v_fmac_f32_e32 v12, v121, v31
	v_fmac_f32_e32 v13, v121, v47
	v_fmac_f32_e32 v10, v121, v51
	v_fmac_f32_e32 v11, v121, v67
	v_fmac_f32_e32 v8, v121, v71
	v_fmac_f32_e32 v9, v121, v75
	v_fmac_f32_e32 v14, v122, v24
	v_fmac_f32_e32 v15, v122, v28
	v_fmac_f32_e32 v12, v122, v32
	v_fmac_f32_e32 v13, v122, v48
	v_fmac_f32_e32 v10, v122, v52
	v_fmac_f32_e32 v11, v122, v68
	v_fmac_f32_e32 v8, v122, v72
	v_fmac_f32_e32 v9, v122, v76
	v_fmac_f32_e32 v14, v123, v25
	v_fmac_f32_e32 v15, v123, v29
	v_fmac_f32_e32 v12, v123, v33
	v_fmac_f32_e32 v13, v123, v49
	v_fmac_f32_e32 v10, v123, v53
	v_fmac_f32_e32 v11, v123, v69
	v_fmac_f32_e32 v8, v123, v73
	v_fmac_f32_e32 v9, v123, v77
	v_mov_b32_e32 v3, 48
	ds_read_b128 v[22:25], v3 offset:3328
	ds_read_b128 v[26:29], v3 offset:3584
	ds_read_b128 v[30:33], v3 offset:3840
	ds_read_b128 v[46:49], v3 offset:4096
	ds_read_b128 v[50:53], v3 offset:4352
	ds_read_b128 v[66:69], v3 offset:4608
	ds_read_b128 v[70:73], v3 offset:4864
	ds_read_b128 v[74:77], v3 offset:5120
	s_waitcnt vmcnt(48)
	s_waitcnt lgkmcnt(0)
	v_fmac_f32_e32 v14, v124, v22
	v_fmac_f32_e32 v15, v124, v26
	v_fmac_f32_e32 v12, v124, v30
	v_fmac_f32_e32 v13, v124, v46
	v_fmac_f32_e32 v10, v124, v50
	v_fmac_f32_e32 v11, v124, v66
	v_fmac_f32_e32 v8, v124, v70
	v_fmac_f32_e32 v9, v124, v74
	v_fmac_f32_e32 v14, v125, v23
	v_fmac_f32_e32 v15, v125, v27
	v_fmac_f32_e32 v12, v125, v31
	v_fmac_f32_e32 v13, v125, v47
	v_fmac_f32_e32 v10, v125, v51
	v_fmac_f32_e32 v11, v125, v67
	v_fmac_f32_e32 v8, v125, v71
	v_fmac_f32_e32 v9, v125, v75
	v_fmac_f32_e32 v14, v126, v24
	v_fmac_f32_e32 v15, v126, v28
	v_fmac_f32_e32 v12, v126, v32
	v_fmac_f32_e32 v13, v126, v48
	v_fmac_f32_e32 v10, v126, v52
	v_fmac_f32_e32 v11, v126, v68
	v_fmac_f32_e32 v8, v126, v72
	v_fmac_f32_e32 v9, v126, v76
	v_fmac_f32_e32 v14, v127, v25
	v_fmac_f32_e32 v15, v127, v29
	v_fmac_f32_e32 v12, v127, v33
	v_fmac_f32_e32 v13, v127, v49
	v_fmac_f32_e32 v10, v127, v53
	v_fmac_f32_e32 v11, v127, v69
	v_fmac_f32_e32 v8, v127, v73
	v_fmac_f32_e32 v9, v127, v77
	v_mov_b32_e32 v3, 64
	ds_read_b128 v[22:25], v3 offset:3328
	ds_read_b128 v[26:29], v3 offset:3584
	ds_read_b128 v[30:33], v3 offset:3840
	ds_read_b128 v[46:49], v3 offset:4096
	ds_read_b128 v[50:53], v3 offset:4352
	ds_read_b128 v[66:69], v3 offset:4608
	ds_read_b128 v[70:73], v3 offset:4864
	ds_read_b128 v[74:77], v3 offset:5120
	s_waitcnt vmcnt(44)
	s_waitcnt lgkmcnt(0)
	v_fmac_f32_e32 v14, v128, v22
	v_fmac_f32_e32 v15, v128, v26
	v_fmac_f32_e32 v12, v128, v30
	v_fmac_f32_e32 v13, v128, v46
	v_fmac_f32_e32 v10, v128, v50
	v_fmac_f32_e32 v11, v128, v66
	v_fmac_f32_e32 v8, v128, v70
	v_fmac_f32_e32 v9, v128, v74
	v_fmac_f32_e32 v14, v129, v23
	v_fmac_f32_e32 v15, v129, v27
	v_fmac_f32_e32 v12, v129, v31
	v_fmac_f32_e32 v13, v129, v47
	v_fmac_f32_e32 v10, v129, v51
	v_fmac_f32_e32 v11, v129, v67
	v_fmac_f32_e32 v8, v129, v71
	v_fmac_f32_e32 v9, v129, v75
	v_fmac_f32_e32 v14, v130, v24
	v_fmac_f32_e32 v15, v130, v28
	v_fmac_f32_e32 v12, v130, v32
	v_fmac_f32_e32 v13, v130, v48
	v_fmac_f32_e32 v10, v130, v52
	v_fmac_f32_e32 v11, v130, v68
	v_fmac_f32_e32 v8, v130, v72
	v_fmac_f32_e32 v9, v130, v76
	v_fmac_f32_e32 v14, v131, v25
	v_fmac_f32_e32 v15, v131, v29
	v_fmac_f32_e32 v12, v131, v33
	v_fmac_f32_e32 v13, v131, v49
	v_fmac_f32_e32 v10, v131, v53
	v_fmac_f32_e32 v11, v131, v69
	v_fmac_f32_e32 v8, v131, v73
	v_fmac_f32_e32 v9, v131, v77
	v_mov_b32_e32 v3, 80
	ds_read_b128 v[22:25], v3 offset:3328
	ds_read_b128 v[26:29], v3 offset:3584
	ds_read_b128 v[30:33], v3 offset:3840
	ds_read_b128 v[46:49], v3 offset:4096
	ds_read_b128 v[50:53], v3 offset:4352
	ds_read_b128 v[66:69], v3 offset:4608
	ds_read_b128 v[70:73], v3 offset:4864
	ds_read_b128 v[74:77], v3 offset:5120
	s_waitcnt vmcnt(40)
	s_waitcnt lgkmcnt(0)
	v_fmac_f32_e32 v14, v132, v22
	v_fmac_f32_e32 v15, v132, v26
	v_fmac_f32_e32 v12, v132, v30
	v_fmac_f32_e32 v13, v132, v46
	v_fmac_f32_e32 v10, v132, v50
	v_fmac_f32_e32 v11, v132, v66
	v_fmac_f32_e32 v8, v132, v70
	v_fmac_f32_e32 v9, v132, v74
	v_fmac_f32_e32 v14, v133, v23
	v_fmac_f32_e32 v15, v133, v27
	v_fmac_f32_e32 v12, v133, v31
	v_fmac_f32_e32 v13, v133, v47
	v_fmac_f32_e32 v10, v133, v51
	v_fmac_f32_e32 v11, v133, v67
	v_fmac_f32_e32 v8, v133, v71
	v_fmac_f32_e32 v9, v133, v75
	v_fmac_f32_e32 v14, v134, v24
	v_fmac_f32_e32 v15, v134, v28
	v_fmac_f32_e32 v12, v134, v32
	v_fmac_f32_e32 v13, v134, v48
	v_fmac_f32_e32 v10, v134, v52
	v_fmac_f32_e32 v11, v134, v68
	v_fmac_f32_e32 v8, v134, v72
	v_fmac_f32_e32 v9, v134, v76
	v_fmac_f32_e32 v14, v135, v25
	v_fmac_f32_e32 v15, v135, v29
	v_fmac_f32_e32 v12, v135, v33
	v_fmac_f32_e32 v13, v135, v49
	v_fmac_f32_e32 v10, v135, v53
	v_fmac_f32_e32 v11, v135, v69
	v_fmac_f32_e32 v8, v135, v73
	v_fmac_f32_e32 v9, v135, v77
	v_mov_b32_e32 v3, 96
	ds_read_b128 v[22:25], v3 offset:3328
	ds_read_b128 v[26:29], v3 offset:3584
	ds_read_b128 v[30:33], v3 offset:3840
	ds_read_b128 v[46:49], v3 offset:4096
	ds_read_b128 v[50:53], v3 offset:4352
	ds_read_b128 v[66:69], v3 offset:4608
	ds_read_b128 v[70:73], v3 offset:4864
	ds_read_b128 v[74:77], v3 offset:5120
	s_waitcnt vmcnt(36)
	s_waitcnt lgkmcnt(0)
	v_fmac_f32_e32 v14, v136, v22
	v_fmac_f32_e32 v15, v136, v26
	v_fmac_f32_e32 v12, v136, v30
	v_fmac_f32_e32 v13, v136, v46
	v_fmac_f32_e32 v10, v136, v50
	v_fmac_f32_e32 v11, v136, v66
	v_fmac_f32_e32 v8, v136, v70
	v_fmac_f32_e32 v9, v136, v74
	v_fmac_f32_e32 v14, v137, v23
	v_fmac_f32_e32 v15, v137, v27
	v_fmac_f32_e32 v12, v137, v31
	v_fmac_f32_e32 v13, v137, v47
	v_fmac_f32_e32 v10, v137, v51
	v_fmac_f32_e32 v11, v137, v67
	v_fmac_f32_e32 v8, v137, v71
	v_fmac_f32_e32 v9, v137, v75
	v_fmac_f32_e32 v14, v138, v24
	v_fmac_f32_e32 v15, v138, v28
	v_fmac_f32_e32 v12, v138, v32
	v_fmac_f32_e32 v13, v138, v48
	v_fmac_f32_e32 v10, v138, v52
	v_fmac_f32_e32 v11, v138, v68
	v_fmac_f32_e32 v8, v138, v72
	v_fmac_f32_e32 v9, v138, v76
	v_fmac_f32_e32 v14, v139, v25
	v_fmac_f32_e32 v15, v139, v29
	v_fmac_f32_e32 v12, v139, v33
	v_fmac_f32_e32 v13, v139, v49
	v_fmac_f32_e32 v10, v139, v53
	v_fmac_f32_e32 v11, v139, v69
	v_fmac_f32_e32 v8, v139, v73
	v_fmac_f32_e32 v9, v139, v77
	v_mov_b32_e32 v3, 112
	ds_read_b128 v[22:25], v3 offset:3328
	ds_read_b128 v[26:29], v3 offset:3584
	ds_read_b128 v[30:33], v3 offset:3840
	ds_read_b128 v[46:49], v3 offset:4096
	ds_read_b128 v[50:53], v3 offset:4352
	ds_read_b128 v[66:69], v3 offset:4608
	ds_read_b128 v[70:73], v3 offset:4864
	ds_read_b128 v[74:77], v3 offset:5120
	s_waitcnt vmcnt(32)
	s_waitcnt lgkmcnt(0)
	v_fmac_f32_e32 v14, v140, v22
	v_fmac_f32_e32 v15, v140, v26
	v_fmac_f32_e32 v12, v140, v30
	v_fmac_f32_e32 v13, v140, v46
	v_fmac_f32_e32 v10, v140, v50
	v_fmac_f32_e32 v11, v140, v66
	v_fmac_f32_e32 v8, v140, v70
	v_fmac_f32_e32 v9, v140, v74
	v_fmac_f32_e32 v14, v141, v23
	v_fmac_f32_e32 v15, v141, v27
	v_fmac_f32_e32 v12, v141, v31
	v_fmac_f32_e32 v13, v141, v47
	v_fmac_f32_e32 v10, v141, v51
	v_fmac_f32_e32 v11, v141, v67
	v_fmac_f32_e32 v8, v141, v71
	v_fmac_f32_e32 v9, v141, v75
	v_fmac_f32_e32 v14, v142, v24
	v_fmac_f32_e32 v15, v142, v28
	v_fmac_f32_e32 v12, v142, v32
	v_fmac_f32_e32 v13, v142, v48
	v_fmac_f32_e32 v10, v142, v52
	v_fmac_f32_e32 v11, v142, v68
	v_fmac_f32_e32 v8, v142, v72
	v_fmac_f32_e32 v9, v142, v76
	v_fmac_f32_e32 v14, v143, v25
	v_fmac_f32_e32 v15, v143, v29
	v_fmac_f32_e32 v12, v143, v33
	v_fmac_f32_e32 v13, v143, v49
	v_fmac_f32_e32 v10, v143, v53
	v_fmac_f32_e32 v11, v143, v69
	v_fmac_f32_e32 v8, v143, v73
	v_fmac_f32_e32 v9, v143, v77
	v_mov_b32_e32 v3, 128
	ds_read_b128 v[22:25], v3 offset:3328
	ds_read_b128 v[26:29], v3 offset:3584
	ds_read_b128 v[30:33], v3 offset:3840
	ds_read_b128 v[46:49], v3 offset:4096
	ds_read_b128 v[50:53], v3 offset:4352
	ds_read_b128 v[66:69], v3 offset:4608
	ds_read_b128 v[70:73], v3 offset:4864
	ds_read_b128 v[74:77], v3 offset:5120
	s_waitcnt vmcnt(28)
	s_waitcnt lgkmcnt(0)
	v_fmac_f32_e32 v14, v144, v22
	v_fmac_f32_e32 v15, v144, v26
	v_fmac_f32_e32 v12, v144, v30
	v_fmac_f32_e32 v13, v144, v46
	v_fmac_f32_e32 v10, v144, v50
	v_fmac_f32_e32 v11, v144, v66
	v_fmac_f32_e32 v8, v144, v70
	v_fmac_f32_e32 v9, v144, v74
	v_fmac_f32_e32 v14, v145, v23
	v_fmac_f32_e32 v15, v145, v27
	v_fmac_f32_e32 v12, v145, v31
	v_fmac_f32_e32 v13, v145, v47
	v_fmac_f32_e32 v10, v145, v51
	v_fmac_f32_e32 v11, v145, v67
	v_fmac_f32_e32 v8, v145, v71
	v_fmac_f32_e32 v9, v145, v75
	v_fmac_f32_e32 v14, v146, v24
	v_fmac_f32_e32 v15, v146, v28
	v_fmac_f32_e32 v12, v146, v32
	v_fmac_f32_e32 v13, v146, v48
	v_fmac_f32_e32 v10, v146, v52
	v_fmac_f32_e32 v11, v146, v68
	v_fmac_f32_e32 v8, v146, v72
	v_fmac_f32_e32 v9, v146, v76
	v_fmac_f32_e32 v14, v147, v25
	v_fmac_f32_e32 v15, v147, v29
	v_fmac_f32_e32 v12, v147, v33
	v_fmac_f32_e32 v13, v147, v49
	v_fmac_f32_e32 v10, v147, v53
	v_fmac_f32_e32 v11, v147, v69
	v_fmac_f32_e32 v8, v147, v73
	v_fmac_f32_e32 v9, v147, v77
	v_mov_b32_e32 v3, 144
	ds_read_b128 v[22:25], v3 offset:3328
	ds_read_b128 v[26:29], v3 offset:3584
	ds_read_b128 v[30:33], v3 offset:3840
	ds_read_b128 v[46:49], v3 offset:4096
	ds_read_b128 v[50:53], v3 offset:4352
	ds_read_b128 v[66:69], v3 offset:4608
	ds_read_b128 v[70:73], v3 offset:4864
	ds_read_b128 v[74:77], v3 offset:5120
	s_waitcnt vmcnt(24)
	s_waitcnt lgkmcnt(0)
	v_fmac_f32_e32 v14, v148, v22
	v_fmac_f32_e32 v15, v148, v26
	v_fmac_f32_e32 v12, v148, v30
	v_fmac_f32_e32 v13, v148, v46
	v_fmac_f32_e32 v10, v148, v50
	v_fmac_f32_e32 v11, v148, v66
	v_fmac_f32_e32 v8, v148, v70
	v_fmac_f32_e32 v9, v148, v74
	v_fmac_f32_e32 v14, v149, v23
	v_fmac_f32_e32 v15, v149, v27
	v_fmac_f32_e32 v12, v149, v31
	v_fmac_f32_e32 v13, v149, v47
	v_fmac_f32_e32 v10, v149, v51
	v_fmac_f32_e32 v11, v149, v67
	v_fmac_f32_e32 v8, v149, v71
	v_fmac_f32_e32 v9, v149, v75
	v_fmac_f32_e32 v14, v150, v24
	v_fmac_f32_e32 v15, v150, v28
	v_fmac_f32_e32 v12, v150, v32
	v_fmac_f32_e32 v13, v150, v48
	v_fmac_f32_e32 v10, v150, v52
	v_fmac_f32_e32 v11, v150, v68
	v_fmac_f32_e32 v8, v150, v72
	v_fmac_f32_e32 v9, v150, v76
	v_fmac_f32_e32 v14, v151, v25
	v_fmac_f32_e32 v15, v151, v29
	v_fmac_f32_e32 v12, v151, v33
	v_fmac_f32_e32 v13, v151, v49
	v_fmac_f32_e32 v10, v151, v53
	v_fmac_f32_e32 v11, v151, v69
	v_fmac_f32_e32 v8, v151, v73
	v_fmac_f32_e32 v9, v151, v77
	v_mov_b32_e32 v3, 160
	ds_read_b128 v[22:25], v3 offset:3328
	ds_read_b128 v[26:29], v3 offset:3584
	ds_read_b128 v[30:33], v3 offset:3840
	ds_read_b128 v[46:49], v3 offset:4096
	ds_read_b128 v[50:53], v3 offset:4352
	ds_read_b128 v[66:69], v3 offset:4608
	ds_read_b128 v[70:73], v3 offset:4864
	ds_read_b128 v[74:77], v3 offset:5120
	s_waitcnt vmcnt(20)
	s_waitcnt lgkmcnt(0)
	v_fmac_f32_e32 v14, v152, v22
	v_fmac_f32_e32 v15, v152, v26
	v_fmac_f32_e32 v12, v152, v30
	v_fmac_f32_e32 v13, v152, v46
	v_fmac_f32_e32 v10, v152, v50
	v_fmac_f32_e32 v11, v152, v66
	v_fmac_f32_e32 v8, v152, v70
	v_fmac_f32_e32 v9, v152, v74
	v_fmac_f32_e32 v14, v153, v23
	v_fmac_f32_e32 v15, v153, v27
	v_fmac_f32_e32 v12, v153, v31
	v_fmac_f32_e32 v13, v153, v47
	v_fmac_f32_e32 v10, v153, v51
	v_fmac_f32_e32 v11, v153, v67
	v_fmac_f32_e32 v8, v153, v71
	v_fmac_f32_e32 v9, v153, v75
	v_fmac_f32_e32 v14, v154, v24
	v_fmac_f32_e32 v15, v154, v28
	v_fmac_f32_e32 v12, v154, v32
	v_fmac_f32_e32 v13, v154, v48
	v_fmac_f32_e32 v10, v154, v52
	v_fmac_f32_e32 v11, v154, v68
	v_fmac_f32_e32 v8, v154, v72
	v_fmac_f32_e32 v9, v154, v76
	v_fmac_f32_e32 v14, v155, v25
	v_fmac_f32_e32 v15, v155, v29
	v_fmac_f32_e32 v12, v155, v33
	v_fmac_f32_e32 v13, v155, v49
	v_fmac_f32_e32 v10, v155, v53
	v_fmac_f32_e32 v11, v155, v69
	v_fmac_f32_e32 v8, v155, v73
	v_fmac_f32_e32 v9, v155, v77
	v_mov_b32_e32 v3, 176
	ds_read_b128 v[22:25], v3 offset:3328
	ds_read_b128 v[26:29], v3 offset:3584
	ds_read_b128 v[30:33], v3 offset:3840
	ds_read_b128 v[46:49], v3 offset:4096
	ds_read_b128 v[50:53], v3 offset:4352
	ds_read_b128 v[66:69], v3 offset:4608
	ds_read_b128 v[70:73], v3 offset:4864
	ds_read_b128 v[74:77], v3 offset:5120
	s_waitcnt vmcnt(16)
	s_waitcnt lgkmcnt(0)
	v_fmac_f32_e32 v14, v156, v22
	v_fmac_f32_e32 v15, v156, v26
	v_fmac_f32_e32 v12, v156, v30
	v_fmac_f32_e32 v13, v156, v46
	v_fmac_f32_e32 v10, v156, v50
	v_fmac_f32_e32 v11, v156, v66
	v_fmac_f32_e32 v8, v156, v70
	v_fmac_f32_e32 v9, v156, v74
	v_fmac_f32_e32 v14, v157, v23
	v_fmac_f32_e32 v15, v157, v27
	v_fmac_f32_e32 v12, v157, v31
	v_fmac_f32_e32 v13, v157, v47
	v_fmac_f32_e32 v10, v157, v51
	v_fmac_f32_e32 v11, v157, v67
	v_fmac_f32_e32 v8, v157, v71
	v_fmac_f32_e32 v9, v157, v75
	v_fmac_f32_e32 v14, v158, v24
	v_fmac_f32_e32 v15, v158, v28
	v_fmac_f32_e32 v12, v158, v32
	v_fmac_f32_e32 v13, v158, v48
	v_fmac_f32_e32 v10, v158, v52
	v_fmac_f32_e32 v11, v158, v68
	v_fmac_f32_e32 v8, v158, v72
	v_fmac_f32_e32 v9, v158, v76
	v_fmac_f32_e32 v14, v159, v25
	v_fmac_f32_e32 v15, v159, v29
	v_fmac_f32_e32 v12, v159, v33
	v_fmac_f32_e32 v13, v159, v49
	v_fmac_f32_e32 v10, v159, v53
	v_fmac_f32_e32 v11, v159, v69
	v_fmac_f32_e32 v8, v159, v73
	v_fmac_f32_e32 v9, v159, v77
	v_mov_b32_e32 v3, 192
	ds_read_b128 v[22:25], v3 offset:3328
	ds_read_b128 v[26:29], v3 offset:3584
	ds_read_b128 v[30:33], v3 offset:3840
	ds_read_b128 v[46:49], v3 offset:4096
	ds_read_b128 v[50:53], v3 offset:4352
	ds_read_b128 v[66:69], v3 offset:4608
	ds_read_b128 v[70:73], v3 offset:4864
	ds_read_b128 v[74:77], v3 offset:5120
	s_waitcnt vmcnt(12)
	s_waitcnt lgkmcnt(0)
	v_fmac_f32_e32 v14, v160, v22
	v_fmac_f32_e32 v15, v160, v26
	v_fmac_f32_e32 v12, v160, v30
	v_fmac_f32_e32 v13, v160, v46
	v_fmac_f32_e32 v10, v160, v50
	v_fmac_f32_e32 v11, v160, v66
	v_fmac_f32_e32 v8, v160, v70
	v_fmac_f32_e32 v9, v160, v74
	v_fmac_f32_e32 v14, v161, v23
	v_fmac_f32_e32 v15, v161, v27
	v_fmac_f32_e32 v12, v161, v31
	v_fmac_f32_e32 v13, v161, v47
	v_fmac_f32_e32 v10, v161, v51
	v_fmac_f32_e32 v11, v161, v67
	v_fmac_f32_e32 v8, v161, v71
	v_fmac_f32_e32 v9, v161, v75
	v_fmac_f32_e32 v14, v162, v24
	v_fmac_f32_e32 v15, v162, v28
	v_fmac_f32_e32 v12, v162, v32
	v_fmac_f32_e32 v13, v162, v48
	v_fmac_f32_e32 v10, v162, v52
	v_fmac_f32_e32 v11, v162, v68
	v_fmac_f32_e32 v8, v162, v72
	v_fmac_f32_e32 v9, v162, v76
	v_fmac_f32_e32 v14, v163, v25
	v_fmac_f32_e32 v15, v163, v29
	v_fmac_f32_e32 v12, v163, v33
	v_fmac_f32_e32 v13, v163, v49
	v_fmac_f32_e32 v10, v163, v53
	v_fmac_f32_e32 v11, v163, v69
	v_fmac_f32_e32 v8, v163, v73
	v_fmac_f32_e32 v9, v163, v77
	v_mov_b32_e32 v3, 208
	ds_read_b128 v[22:25], v3 offset:3328
	ds_read_b128 v[26:29], v3 offset:3584
	ds_read_b128 v[30:33], v3 offset:3840
	ds_read_b128 v[46:49], v3 offset:4096
	ds_read_b128 v[50:53], v3 offset:4352
	ds_read_b128 v[66:69], v3 offset:4608
	ds_read_b128 v[70:73], v3 offset:4864
	ds_read_b128 v[74:77], v3 offset:5120
	s_waitcnt vmcnt(8)
	s_waitcnt lgkmcnt(0)
	v_fmac_f32_e32 v14, v164, v22
	v_fmac_f32_e32 v15, v164, v26
	v_fmac_f32_e32 v12, v164, v30
	v_fmac_f32_e32 v13, v164, v46
	v_fmac_f32_e32 v10, v164, v50
	v_fmac_f32_e32 v11, v164, v66
	v_fmac_f32_e32 v8, v164, v70
	v_fmac_f32_e32 v9, v164, v74
	v_fmac_f32_e32 v14, v165, v23
	v_fmac_f32_e32 v15, v165, v27
	v_fmac_f32_e32 v12, v165, v31
	v_fmac_f32_e32 v13, v165, v47
	v_fmac_f32_e32 v10, v165, v51
	v_fmac_f32_e32 v11, v165, v67
	v_fmac_f32_e32 v8, v165, v71
	v_fmac_f32_e32 v9, v165, v75
	v_fmac_f32_e32 v14, v166, v24
	v_fmac_f32_e32 v15, v166, v28
	v_fmac_f32_e32 v12, v166, v32
	v_fmac_f32_e32 v13, v166, v48
	v_fmac_f32_e32 v10, v166, v52
	v_fmac_f32_e32 v11, v166, v68
	v_fmac_f32_e32 v8, v166, v72
	v_fmac_f32_e32 v9, v166, v76
	v_fmac_f32_e32 v14, v167, v25
	v_fmac_f32_e32 v15, v167, v29
	v_fmac_f32_e32 v12, v167, v33
	v_fmac_f32_e32 v13, v167, v49
	v_fmac_f32_e32 v10, v167, v53
	v_fmac_f32_e32 v11, v167, v69
	v_fmac_f32_e32 v8, v167, v73
	v_fmac_f32_e32 v9, v167, v77
	v_mov_b32_e32 v3, 224
	ds_read_b128 v[22:25], v3 offset:3328
	ds_read_b128 v[26:29], v3 offset:3584
	ds_read_b128 v[30:33], v3 offset:3840
	ds_read_b128 v[46:49], v3 offset:4096
	ds_read_b128 v[50:53], v3 offset:4352
	ds_read_b128 v[66:69], v3 offset:4608
	ds_read_b128 v[70:73], v3 offset:4864
	ds_read_b128 v[74:77], v3 offset:5120
	s_waitcnt vmcnt(4)
	s_waitcnt lgkmcnt(0)
	v_fmac_f32_e32 v14, v168, v22
	v_fmac_f32_e32 v15, v168, v26
	v_fmac_f32_e32 v12, v168, v30
	v_fmac_f32_e32 v13, v168, v46
	v_fmac_f32_e32 v10, v168, v50
	v_fmac_f32_e32 v11, v168, v66
	v_fmac_f32_e32 v8, v168, v70
	v_fmac_f32_e32 v9, v168, v74
	v_fmac_f32_e32 v14, v169, v23
	v_fmac_f32_e32 v15, v169, v27
	v_fmac_f32_e32 v12, v169, v31
	v_fmac_f32_e32 v13, v169, v47
	v_fmac_f32_e32 v10, v169, v51
	v_fmac_f32_e32 v11, v169, v67
	v_fmac_f32_e32 v8, v169, v71
	v_fmac_f32_e32 v9, v169, v75
	v_fmac_f32_e32 v14, v175, v24
	v_fmac_f32_e32 v15, v175, v28
	v_fmac_f32_e32 v12, v175, v32
	v_fmac_f32_e32 v13, v175, v48
	v_fmac_f32_e32 v10, v175, v52
	v_fmac_f32_e32 v11, v175, v68
	v_fmac_f32_e32 v8, v175, v72
	v_fmac_f32_e32 v9, v175, v76
	v_fmac_f32_e32 v14, v176, v25
	v_fmac_f32_e32 v15, v176, v29
	v_fmac_f32_e32 v12, v176, v33
	v_fmac_f32_e32 v13, v176, v49
	v_fmac_f32_e32 v10, v176, v53
	v_fmac_f32_e32 v11, v176, v69
	v_fmac_f32_e32 v8, v176, v73
	v_fmac_f32_e32 v9, v176, v77
	v_mov_b32_e32 v3, 240
	ds_read_b128 v[22:25], v3 offset:3328
	ds_read_b128 v[26:29], v3 offset:3584
	ds_read_b128 v[30:33], v3 offset:3840
	ds_read_b128 v[46:49], v3 offset:4096
	ds_read_b128 v[50:53], v3 offset:4352
	ds_read_b128 v[66:69], v3 offset:4608
	ds_read_b128 v[70:73], v3 offset:4864
	ds_read_b128 v[74:77], v3 offset:5120
	s_waitcnt vmcnt(0)
	s_waitcnt lgkmcnt(0)
	v_fmac_f32_e32 v14, v177, v22
	v_fmac_f32_e32 v15, v177, v26
	v_fmac_f32_e32 v12, v177, v30
	v_fmac_f32_e32 v13, v177, v46
	v_fmac_f32_e32 v10, v177, v50
	v_fmac_f32_e32 v11, v177, v66
	v_fmac_f32_e32 v8, v177, v70
	v_fmac_f32_e32 v9, v177, v74
	v_fmac_f32_e32 v14, v178, v23
	v_fmac_f32_e32 v15, v178, v27
	v_fmac_f32_e32 v12, v178, v31
	v_fmac_f32_e32 v13, v178, v47
	v_fmac_f32_e32 v10, v178, v51
	v_fmac_f32_e32 v11, v178, v67
	v_fmac_f32_e32 v8, v178, v71
	v_fmac_f32_e32 v9, v178, v75
	v_fmac_f32_e32 v14, v179, v24
	v_fmac_f32_e32 v15, v179, v28
	v_fmac_f32_e32 v12, v179, v32
	v_fmac_f32_e32 v13, v179, v48
	v_fmac_f32_e32 v10, v179, v52
	v_fmac_f32_e32 v11, v179, v68
	v_fmac_f32_e32 v8, v179, v72
	v_fmac_f32_e32 v9, v179, v76
	v_fmac_f32_e32 v14, v180, v25
	v_fmac_f32_e32 v15, v180, v29
	v_fmac_f32_e32 v12, v180, v33
	v_fmac_f32_e32 v13, v180, v49
	v_fmac_f32_e32 v10, v180, v53
	v_fmac_f32_e32 v11, v180, v69
	v_fmac_f32_e32 v8, v180, v73
	v_fmac_f32_e32 v9, v180, v77
	v_readlane_b32 s12, v253, 48
	v_readlane_b32 s13, v253, 49
	s_mov_b32 s3, 0x280000
	v_add_u32_e32 v16, -1, v21
	v_mov_b64_e32 v[4:5], s[12:13]
	v_mad_i64_i32 v[2:3], s[12:13], v2, s3, v[4:5]
	v_cvt_f32_u32_e32 v51, v16
	v_cvt_f32_i32_e32 v4, v20
	v_cndmask_b32_e64 v0, 0, v226, s[52:53]
	v_lshl_add_u64 v[2:3], v[2:3], 0, v[0:1]
	v_cndmask_b32_e64 v0, 9, 11, s[52:53]
	v_div_scale_f32 v5, s[12:13], v51, v51, v4
	v_rcp_f32_e32 v17, v5
	v_lshlrev_b32_e32 v0, v0, v59
	v_lshlrev_b32_e32 v0, 1, v0
	v_lshl_add_u64 v[2:3], v[2:3], 0, v[0:1]
	v_fma_f32 v18, -v5, v17, 1.0
	v_fmac_f32_e32 v17, v18, v17
	v_div_scale_f32 v18, vcc, v4, v51, v4
	v_mul_f32_e32 v19, v18, v17
	v_fma_f32 v22, -v5, v19, v18
	v_fmac_f32_e32 v19, v22, v17
	v_fma_f32 v5, -v5, v19, v18
	v_div_fmas_f32 v5, v5, v17, v19
	v_div_fixup_f32 v4, v5, v51, v4
	v_mul_f32_e64 v4, |v61|, v4
	v_mul_f32_e32 v4, 0xbfb8aa3b, v4
	v_exp_f32_e32 v19, v4
	v_lshlrev_b32_e32 v0, 2, v21
	v_lshl_add_u64 v[4:5], v[2:3], 0, v[0:1]
	v_mul_f32_e32 v0, v19, v14
	s_and_saveexec_b64 s[12:13], s[48:49]
	s_xor_b64 s[16:17], exec, s[12:13]
	s_cbranch_execz .LBB0_1248
	v_cmp_gt_i32_e32 vcc, 1, v20
	s_and_saveexec_b64 s[12:13], vcc
	s_xor_b64 s[18:19], exec, s[12:13]
	s_cbranch_execz .LBB0_1245
	global_store_short v[4:5], v1, off offset:-2

.LBB0_1307:
	v_add_co_u32_e32 v184, vcc, 0x800, v6
	s_nop 1
	v_addc_co_u32_e32 v185, vcc, 0, v7, vcc
	global_load_dword v112, v[184:185], off
	v_add_co_u32_e32 v184, vcc, 0x1000, v184
	s_nop 1
	v_addc_co_u32_e32 v185, vcc, 0, v185, vcc
	global_load_dword v113, v[184:185], off
	v_add_co_u32_e32 v184, vcc, 0x1000, v184
	s_nop 1
	v_addc_co_u32_e32 v185, vcc, 0, v185, vcc
	global_load_dword v114, v[184:185], off
	v_add_co_u32_e32 v184, vcc, 0x1000, v184
	s_nop 1
	v_addc_co_u32_e32 v185, vcc, 0, v185, vcc
	global_load_dword v115, v[184:185], off
	v_add_co_u32_e32 v184, vcc, 0x1000, v184
	s_nop 1
	v_addc_co_u32_e32 v185, vcc, 0, v185, vcc
	global_load_dword v116, v[184:185], off
	v_add_co_u32_e32 v184, vcc, 0x1000, v184
	s_nop 1
	v_addc_co_u32_e32 v185, vcc, 0, v185, vcc
	global_load_dword v117, v[184:185], off
	v_add_co_u32_e32 v184, vcc, 0x1000, v184
	s_nop 1
	v_addc_co_u32_e32 v185, vcc, 0, v185, vcc
	global_load_dword v118, v[184:185], off
	v_add_co_u32_e32 v184, vcc, 0x1000, v184
	s_nop 1
	v_addc_co_u32_e32 v185, vcc, 0, v185, vcc
	global_load_dword v119, v[184:185], off
	v_add_co_u32_e32 v184, vcc, 0x1000, v184
	s_nop 1
	v_addc_co_u32_e32 v185, vcc, 0, v185, vcc
	global_load_dword v120, v[184:185], off
	v_add_co_u32_e32 v184, vcc, 0x1000, v184
	s_nop 1
	v_addc_co_u32_e32 v185, vcc, 0, v185, vcc
	global_load_dword v121, v[184:185], off
	v_add_co_u32_e32 v184, vcc, 0x1000, v184
	s_nop 1
	v_addc_co_u32_e32 v185, vcc, 0, v185, vcc
	global_load_dword v122, v[184:185], off
	v_add_co_u32_e32 v184, vcc, 0x1000, v184
	s_nop 1
	v_addc_co_u32_e32 v185, vcc, 0, v185, vcc
	global_load_dword v123, v[184:185], off
	v_add_co_u32_e32 v184, vcc, 0x1000, v184
	s_nop 1
	v_addc_co_u32_e32 v185, vcc, 0, v185, vcc
	global_load_dword v124, v[184:185], off
	v_add_co_u32_e32 v184, vcc, 0x1000, v184
	s_nop 1
	v_addc_co_u32_e32 v185, vcc, 0, v185, vcc
	global_load_dword v125, v[184:185], off
	v_add_co_u32_e32 v184, vcc, 0x1000, v184
	s_nop 1
	v_addc_co_u32_e32 v185, vcc, 0, v185, vcc
	global_load_dword v126, v[184:185], off
	v_add_co_u32_e32 v184, vcc, 0x1000, v184
	s_nop 1
	v_addc_co_u32_e32 v185, vcc, 0, v185, vcc
	global_load_dword v127, v[184:185], off
	v_add_co_u32_e32 v184, vcc, 0x1000, v184
	s_nop 1
	v_addc_co_u32_e32 v185, vcc, 0, v185, vcc
	global_load_dword v128, v[184:185], off
	v_add_co_u32_e32 v184, vcc, 0x1000, v184
	s_nop 1
	v_addc_co_u32_e32 v185, vcc, 0, v185, vcc
	global_load_dword v129, v[184:185], off
	v_add_co_u32_e32 v184, vcc, 0x1000, v184
	s_nop 1
	v_addc_co_u32_e32 v185, vcc, 0, v185, vcc
	global_load_dword v130, v[184:185], off
	v_add_co_u32_e32 v184, vcc, 0x1000, v184
	s_nop 1
	v_addc_co_u32_e32 v185, vcc, 0, v185, vcc
	global_load_dword v131, v[184:185], off
	v_add_co_u32_e32 v184, vcc, 0x1000, v184
	s_nop 1
	v_addc_co_u32_e32 v185, vcc, 0, v185, vcc
	global_load_dword v132, v[184:185], off
	v_add_co_u32_e32 v184, vcc, 0x1000, v184
	s_nop 1
	v_addc_co_u32_e32 v185, vcc, 0, v185, vcc
	global_load_dword v133, v[184:185], off
	v_add_co_u32_e32 v184, vcc, 0x1000, v184
	s_nop 1
	v_addc_co_u32_e32 v185, vcc, 0, v185, vcc
	global_load_dword v134, v[184:185], off
	v_add_co_u32_e32 v184, vcc, 0x1000, v184
	s_nop 1
	v_addc_co_u32_e32 v185, vcc, 0, v185, vcc
	global_load_dword v135, v[184:185], off
	v_add_co_u32_e32 v184, vcc, 0x1000, v184
	s_nop 1
	v_addc_co_u32_e32 v185, vcc, 0, v185, vcc
	global_load_dword v136, v[184:185], off
	v_add_co_u32_e32 v184, vcc, 0x1000, v184
	s_nop 1
	v_addc_co_u32_e32 v185, vcc, 0, v185, vcc
	global_load_dword v137, v[184:185], off
	v_add_co_u32_e32 v184, vcc, 0x1000, v184
	s_nop 1
	v_addc_co_u32_e32 v185, vcc, 0, v185, vcc
	global_load_dword v138, v[184:185], off
	v_add_co_u32_e32 v184, vcc, 0x1000, v184
	s_nop 1
	v_addc_co_u32_e32 v185, vcc, 0, v185, vcc
	global_load_dword v139, v[184:185], off
	v_add_co_u32_e32 v184, vcc, 0x1000, v184
	s_nop 1
	v_addc_co_u32_e32 v185, vcc, 0, v185, vcc
	global_load_dword v140, v[184:185], off
	v_add_co_u32_e32 v184, vcc, 0x1000, v184
	s_nop 1
	v_addc_co_u32_e32 v185, vcc, 0, v185, vcc
	global_load_dword v141, v[184:185], off
	v_add_co_u32_e32 v184, vcc, 0x1000, v184
	s_nop 1
	v_addc_co_u32_e32 v185, vcc, 0, v185, vcc
	global_load_dword v142, v[184:185], off
	v_add_co_u32_e32 v184, vcc, 0x1000, v184
	s_nop 1
	v_addc_co_u32_e32 v185, vcc, 0, v185, vcc
	global_load_dword v143, v[184:185], off
	v_add_co_u32_e32 v184, vcc, 0x1000, v184
	s_nop 1
	v_addc_co_u32_e32 v185, vcc, 0, v185, vcc
	global_load_dword v144, v[184:185], off
	v_add_co_u32_e32 v184, vcc, 0x1000, v184
	s_nop 1
	v_addc_co_u32_e32 v185, vcc, 0, v185, vcc
	global_load_dword v145, v[184:185], off
	v_add_co_u32_e32 v184, vcc, 0x1000, v184
	s_nop 1
	v_addc_co_u32_e32 v185, vcc, 0, v185, vcc
	global_load_dword v146, v[184:185], off
	v_add_co_u32_e32 v184, vcc, 0x1000, v184
	s_nop 1
	v_addc_co_u32_e32 v185, vcc, 0, v185, vcc
	global_load_dword v147, v[184:185], off
	v_add_co_u32_e32 v184, vcc, 0x1000, v184
	s_nop 1
	v_addc_co_u32_e32 v185, vcc, 0, v185, vcc
	global_load_dword v148, v[184:185], off
	v_add_co_u32_e32 v184, vcc, 0x1000, v184
	s_nop 1
	v_addc_co_u32_e32 v185, vcc, 0, v185, vcc
	global_load_dword v149, v[184:185], off
	v_add_co_u32_e32 v184, vcc, 0x1000, v184
	s_nop 1
	v_addc_co_u32_e32 v185, vcc, 0, v185, vcc
	global_load_dword v150, v[184:185], off
	v_add_co_u32_e32 v184, vcc, 0x1000, v184
	s_nop 1
	v_addc_co_u32_e32 v185, vcc, 0, v185, vcc
	global_load_dword v151, v[184:185], off
	v_add_co_u32_e32 v184, vcc, 0x1000, v184
	s_nop 1
	v_addc_co_u32_e32 v185, vcc, 0, v185, vcc
	global_load_dword v152, v[184:185], off
	v_add_co_u32_e32 v184, vcc, 0x1000, v184
	s_nop 1
	v_addc_co_u32_e32 v185, vcc, 0, v185, vcc
	global_load_dword v153, v[184:185], off
	v_add_co_u32_e32 v184, vcc, 0x1000, v184
	s_nop 1
	v_addc_co_u32_e32 v185, vcc, 0, v185, vcc
	global_load_dword v154, v[184:185], off
	v_add_co_u32_e32 v184, vcc, 0x1000, v184
	s_nop 1
	v_addc_co_u32_e32 v185, vcc, 0, v185, vcc
	global_load_dword v155, v[184:185], off
	v_add_co_u32_e32 v184, vcc, 0x1000, v184
	s_nop 1
	v_addc_co_u32_e32 v185, vcc, 0, v185, vcc
	global_load_dword v156, v[184:185], off
	v_add_co_u32_e32 v184, vcc, 0x1000, v184
	s_nop 1
	v_addc_co_u32_e32 v185, vcc, 0, v185, vcc
	global_load_dword v157, v[184:185], off
	v_add_co_u32_e32 v184, vcc, 0x1000, v184
	s_nop 1
	v_addc_co_u32_e32 v185, vcc, 0, v185, vcc
	global_load_dword v158, v[184:185], off
	v_add_co_u32_e32 v184, vcc, 0x1000, v184
	s_nop 1
	v_addc_co_u32_e32 v185, vcc, 0, v185, vcc
	global_load_dword v159, v[184:185], off
	v_add_co_u32_e32 v184, vcc, 0x1000, v184
	s_nop 1
	v_addc_co_u32_e32 v185, vcc, 0, v185, vcc
	global_load_dword v160, v[184:185], off
	v_add_co_u32_e32 v184, vcc, 0x1000, v184
	s_nop 1
	v_addc_co_u32_e32 v185, vcc, 0, v185, vcc
	global_load_dword v161, v[184:185], off
	v_add_co_u32_e32 v184, vcc, 0x1000, v184
	s_nop 1
	v_addc_co_u32_e32 v185, vcc, 0, v185, vcc
	global_load_dword v162, v[184:185], off
	v_add_co_u32_e32 v184, vcc, 0x1000, v184
	s_nop 1
	v_addc_co_u32_e32 v185, vcc, 0, v185, vcc
	global_load_dword v163, v[184:185], off
	v_add_co_u32_e32 v184, vcc, 0x1000, v184
	s_nop 1
	v_addc_co_u32_e32 v185, vcc, 0, v185, vcc
	global_load_dword v164, v[184:185], off
	v_add_co_u32_e32 v184, vcc, 0x1000, v184
	s_nop 1
	v_addc_co_u32_e32 v185, vcc, 0, v185, vcc
	global_load_dword v165, v[184:185], off
	v_add_co_u32_e32 v184, vcc, 0x1000, v184
	s_nop 1
	v_addc_co_u32_e32 v185, vcc, 0, v185, vcc
	global_load_dword v166, v[184:185], off
	v_add_co_u32_e32 v184, vcc, 0x1000, v184
	s_nop 1
	v_addc_co_u32_e32 v185, vcc, 0, v185, vcc
	global_load_dword v167, v[184:185], off
	v_add_co_u32_e32 v184, vcc, 0x1000, v184
	s_nop 1
	v_addc_co_u32_e32 v185, vcc, 0, v185, vcc
	global_load_dword v168, v[184:185], off
	v_add_co_u32_e32 v184, vcc, 0x1000, v184
	s_nop 1
	v_addc_co_u32_e32 v185, vcc, 0, v185, vcc
	global_load_dword v169, v[184:185], off
	v_add_co_u32_e32 v184, vcc, 0x1000, v184
	s_nop 1
	v_addc_co_u32_e32 v185, vcc, 0, v185, vcc
	global_load_dword v175, v[184:185], off
	v_add_co_u32_e32 v184, vcc, 0x1000, v184
	s_nop 1
	v_addc_co_u32_e32 v185, vcc, 0, v185, vcc
	global_load_dword v176, v[184:185], off
	v_add_co_u32_e32 v184, vcc, 0x1000, v184
	s_nop 1
	v_addc_co_u32_e32 v185, vcc, 0, v185, vcc
	global_load_dword v177, v[184:185], off
	v_add_co_u32_e32 v184, vcc, 0x1000, v184
	s_nop 1
	v_addc_co_u32_e32 v185, vcc, 0, v185, vcc
	global_load_dword v178, v[184:185], off
	v_add_co_u32_e32 v184, vcc, 0x1000, v184
	s_nop 1
	v_addc_co_u32_e32 v185, vcc, 0, v185, vcc
	global_load_dword v179, v[184:185], off
	v_add_co_u32_e32 v184, vcc, 0x1000, v184
	s_nop 1
	v_addc_co_u32_e32 v185, vcc, 0, v185, vcc
	global_load_dword v180, v[184:185], off
	v_add_co_u32_e32 v184, vcc, 0x1000, v184
	s_nop 1
	v_addc_co_u32_e32 v185, vcc, 0, v185, vcc
	v_mov_b32_e32 v104, 0
	ds_read_b128 v[66:69], v104 offset:3328
	ds_read_b128 v[70:73], v104 offset:3584
	ds_read_b128 v[74:77], v104 offset:3840
	ds_read_b128 v[78:81], v104 offset:4096
	ds_read_b128 v[82:85], v104 offset:4352
	ds_read_b128 v[86:89], v104 offset:4608
	ds_read_b128 v[90:93], v104 offset:4864
	ds_read_b128 v[94:97], v104 offset:5120
	s_waitcnt vmcnt(60)
	s_waitcnt lgkmcnt(0)
	v_fmac_f32_e32 v14, v112, v66
	v_fmac_f32_e32 v15, v112, v70
	v_fmac_f32_e32 v12, v112, v74
	v_fmac_f32_e32 v13, v112, v78
	v_fmac_f32_e32 v10, v112, v82
	v_fmac_f32_e32 v11, v112, v86
	v_fmac_f32_e32 v8, v112, v90
	v_fmac_f32_e32 v9, v112, v94
	v_fmac_f32_e32 v14, v113, v67
	v_fmac_f32_e32 v15, v113, v71
	v_fmac_f32_e32 v12, v113, v75
	v_fmac_f32_e32 v13, v113, v79
	v_fmac_f32_e32 v10, v113, v83
	v_fmac_f32_e32 v11, v113, v87
	v_fmac_f32_e32 v8, v113, v91
	v_fmac_f32_e32 v9, v113, v95
	v_fmac_f32_e32 v14, v114, v68
	v_fmac_f32_e32 v15, v114, v72
	v_fmac_f32_e32 v12, v114, v76
	v_fmac_f32_e32 v13, v114, v80
	v_fmac_f32_e32 v10, v114, v84
	v_fmac_f32_e32 v11, v114, v88
	v_fmac_f32_e32 v8, v114, v92
	v_fmac_f32_e32 v9, v114, v96
	v_fmac_f32_e32 v14, v115, v69
	v_fmac_f32_e32 v15, v115, v73
	v_fmac_f32_e32 v12, v115, v77
	v_fmac_f32_e32 v13, v115, v81
	v_fmac_f32_e32 v10, v115, v85
	v_fmac_f32_e32 v11, v115, v89
	v_fmac_f32_e32 v8, v115, v93
	v_fmac_f32_e32 v9, v115, v97
	v_mov_b32_e32 v104, 16
	ds_read_b128 v[66:69], v104 offset:3328
	ds_read_b128 v[70:73], v104 offset:3584
	ds_read_b128 v[74:77], v104 offset:3840
	ds_read_b128 v[78:81], v104 offset:4096
	ds_read_b128 v[82:85], v104 offset:4352
	ds_read_b128 v[86:89], v104 offset:4608
	ds_read_b128 v[90:93], v104 offset:4864
	ds_read_b128 v[94:97], v104 offset:5120
	s_waitcnt vmcnt(56)
	s_waitcnt lgkmcnt(0)
	v_fmac_f32_e32 v14, v116, v66
	v_fmac_f32_e32 v15, v116, v70
	v_fmac_f32_e32 v12, v116, v74
	v_fmac_f32_e32 v13, v116, v78
	v_fmac_f32_e32 v10, v116, v82
	v_fmac_f32_e32 v11, v116, v86
	v_fmac_f32_e32 v8, v116, v90
	v_fmac_f32_e32 v9, v116, v94
	v_fmac_f32_e32 v14, v117, v67
	v_fmac_f32_e32 v15, v117, v71
	v_fmac_f32_e32 v12, v117, v75
	v_fmac_f32_e32 v13, v117, v79
	v_fmac_f32_e32 v10, v117, v83
	v_fmac_f32_e32 v11, v117, v87
	v_fmac_f32_e32 v8, v117, v91
	v_fmac_f32_e32 v9, v117, v95
	v_fmac_f32_e32 v14, v118, v68
	v_fmac_f32_e32 v15, v118, v72
	v_fmac_f32_e32 v12, v118, v76
	v_fmac_f32_e32 v13, v118, v80
	v_fmac_f32_e32 v10, v118, v84
	v_fmac_f32_e32 v11, v118, v88
	v_fmac_f32_e32 v8, v118, v92
	v_fmac_f32_e32 v9, v118, v96
	v_fmac_f32_e32 v14, v119, v69
	v_fmac_f32_e32 v15, v119, v73
	v_fmac_f32_e32 v12, v119, v77
	v_fmac_f32_e32 v13, v119, v81
	v_fmac_f32_e32 v10, v119, v85
	v_fmac_f32_e32 v11, v119, v89
	v_fmac_f32_e32 v8, v119, v93
	v_fmac_f32_e32 v9, v119, v97
	v_mov_b32_e32 v104, 32
	ds_read_b128 v[66:69], v104 offset:3328
	ds_read_b128 v[70:73], v104 offset:3584
	ds_read_b128 v[74:77], v104 offset:3840
	ds_read_b128 v[78:81], v104 offset:4096
	ds_read_b128 v[82:85], v104 offset:4352
	ds_read_b128 v[86:89], v104 offset:4608
	ds_read_b128 v[90:93], v104 offset:4864
	ds_read_b128 v[94:97], v104 offset:5120
	s_waitcnt vmcnt(52)
	s_waitcnt lgkmcnt(0)
	v_fmac_f32_e32 v14, v120, v66
	v_fmac_f32_e32 v15, v120, v70
	v_fmac_f32_e32 v12, v120, v74
	v_fmac_f32_e32 v13, v120, v78
	v_fmac_f32_e32 v10, v120, v82
	v_fmac_f32_e32 v11, v120, v86
	v_fmac_f32_e32 v8, v120, v90
	v_fmac_f32_e32 v9, v120, v94
	v_fmac_f32_e32 v14, v121, v67
	v_fmac_f32_e32 v15, v121, v71
	v_fmac_f32_e32 v12, v121, v75
	v_fmac_f32_e32 v13, v121, v79
	v_fmac_f32_e32 v10, v121, v83
	v_fmac_f32_e32 v11, v121, v87
	v_fmac_f32_e32 v8, v121, v91
	v_fmac_f32_e32 v9, v121, v95
	v_fmac_f32_e32 v14, v122, v68
	v_fmac_f32_e32 v15, v122, v72
	v_fmac_f32_e32 v12, v122, v76
	v_fmac_f32_e32 v13, v122, v80
	v_fmac_f32_e32 v10, v122, v84
	v_fmac_f32_e32 v11, v122, v88
	v_fmac_f32_e32 v8, v122, v92
	v_fmac_f32_e32 v9, v122, v96
	v_fmac_f32_e32 v14, v123, v69
	v_fmac_f32_e32 v15, v123, v73
	v_fmac_f32_e32 v12, v123, v77
	v_fmac_f32_e32 v13, v123, v81
	v_fmac_f32_e32 v10, v123, v85
	v_fmac_f32_e32 v11, v123, v89
	v_fmac_f32_e32 v8, v123, v93
	v_fmac_f32_e32 v9, v123, v97
	v_mov_b32_e32 v104, 48
	ds_read_b128 v[66:69], v104 offset:3328
	ds_read_b128 v[70:73], v104 offset:3584
	ds_read_b128 v[74:77], v104 offset:3840
	ds_read_b128 v[78:81], v104 offset:4096
	ds_read_b128 v[82:85], v104 offset:4352
	ds_read_b128 v[86:89], v104 offset:4608
	ds_read_b128 v[90:93], v104 offset:4864
	ds_read_b128 v[94:97], v104 offset:5120
	s_waitcnt vmcnt(48)
	s_waitcnt lgkmcnt(0)
	v_fmac_f32_e32 v14, v124, v66
	v_fmac_f32_e32 v15, v124, v70
	v_fmac_f32_e32 v12, v124, v74
	v_fmac_f32_e32 v13, v124, v78
	v_fmac_f32_e32 v10, v124, v82
	v_fmac_f32_e32 v11, v124, v86
	v_fmac_f32_e32 v8, v124, v90
	v_fmac_f32_e32 v9, v124, v94
	v_fmac_f32_e32 v14, v125, v67
	v_fmac_f32_e32 v15, v125, v71
	v_fmac_f32_e32 v12, v125, v75
	v_fmac_f32_e32 v13, v125, v79
	v_fmac_f32_e32 v10, v125, v83
	v_fmac_f32_e32 v11, v125, v87
	v_fmac_f32_e32 v8, v125, v91
	v_fmac_f32_e32 v9, v125, v95
	v_fmac_f32_e32 v14, v126, v68
	v_fmac_f32_e32 v15, v126, v72
	v_fmac_f32_e32 v12, v126, v76
	v_fmac_f32_e32 v13, v126, v80
	v_fmac_f32_e32 v10, v126, v84
	v_fmac_f32_e32 v11, v126, v88
	v_fmac_f32_e32 v8, v126, v92
	v_fmac_f32_e32 v9, v126, v96
	v_fmac_f32_e32 v14, v127, v69
	v_fmac_f32_e32 v15, v127, v73
	v_fmac_f32_e32 v12, v127, v77
	v_fmac_f32_e32 v13, v127, v81
	v_fmac_f32_e32 v10, v127, v85
	v_fmac_f32_e32 v11, v127, v89
	v_fmac_f32_e32 v8, v127, v93
	v_fmac_f32_e32 v9, v127, v97
	v_mov_b32_e32 v104, 64
	ds_read_b128 v[66:69], v104 offset:3328
	ds_read_b128 v[70:73], v104 offset:3584
	ds_read_b128 v[74:77], v104 offset:3840
	ds_read_b128 v[78:81], v104 offset:4096
	ds_read_b128 v[82:85], v104 offset:4352
	ds_read_b128 v[86:89], v104 offset:4608
	ds_read_b128 v[90:93], v104 offset:4864
	ds_read_b128 v[94:97], v104 offset:5120
	s_waitcnt vmcnt(44)
	s_waitcnt lgkmcnt(0)
	v_fmac_f32_e32 v14, v128, v66
	v_fmac_f32_e32 v15, v128, v70
	v_fmac_f32_e32 v12, v128, v74
	v_fmac_f32_e32 v13, v128, v78
	v_fmac_f32_e32 v10, v128, v82
	v_fmac_f32_e32 v11, v128, v86
	v_fmac_f32_e32 v8, v128, v90
	v_fmac_f32_e32 v9, v128, v94
	v_fmac_f32_e32 v14, v129, v67
	v_fmac_f32_e32 v15, v129, v71
	v_fmac_f32_e32 v12, v129, v75
	v_fmac_f32_e32 v13, v129, v79
	v_fmac_f32_e32 v10, v129, v83
	v_fmac_f32_e32 v11, v129, v87
	v_fmac_f32_e32 v8, v129, v91
	v_fmac_f32_e32 v9, v129, v95
	v_fmac_f32_e32 v14, v130, v68
	v_fmac_f32_e32 v15, v130, v72
	v_fmac_f32_e32 v12, v130, v76
	v_fmac_f32_e32 v13, v130, v80
	v_fmac_f32_e32 v10, v130, v84
	v_fmac_f32_e32 v11, v130, v88
	v_fmac_f32_e32 v8, v130, v92
	v_fmac_f32_e32 v9, v130, v96
	v_fmac_f32_e32 v14, v131, v69
	v_fmac_f32_e32 v15, v131, v73
	v_fmac_f32_e32 v12, v131, v77
	v_fmac_f32_e32 v13, v131, v81
	v_fmac_f32_e32 v10, v131, v85
	v_fmac_f32_e32 v11, v131, v89
	v_fmac_f32_e32 v8, v131, v93
	v_fmac_f32_e32 v9, v131, v97
	v_mov_b32_e32 v104, 80
	ds_read_b128 v[66:69], v104 offset:3328
	ds_read_b128 v[70:73], v104 offset:3584
	ds_read_b128 v[74:77], v104 offset:3840
	ds_read_b128 v[78:81], v104 offset:4096
	ds_read_b128 v[82:85], v104 offset:4352
	ds_read_b128 v[86:89], v104 offset:4608
	ds_read_b128 v[90:93], v104 offset:4864
	ds_read_b128 v[94:97], v104 offset:5120
	s_waitcnt vmcnt(40)
	s_waitcnt lgkmcnt(0)
	v_fmac_f32_e32 v14, v132, v66
	v_fmac_f32_e32 v15, v132, v70
	v_fmac_f32_e32 v12, v132, v74
	v_fmac_f32_e32 v13, v132, v78
	v_fmac_f32_e32 v10, v132, v82
	v_fmac_f32_e32 v11, v132, v86
	v_fmac_f32_e32 v8, v132, v90
	v_fmac_f32_e32 v9, v132, v94
	v_fmac_f32_e32 v14, v133, v67
	v_fmac_f32_e32 v15, v133, v71
	v_fmac_f32_e32 v12, v133, v75
	v_fmac_f32_e32 v13, v133, v79
	v_fmac_f32_e32 v10, v133, v83
	v_fmac_f32_e32 v11, v133, v87
	v_fmac_f32_e32 v8, v133, v91
	v_fmac_f32_e32 v9, v133, v95
	v_fmac_f32_e32 v14, v134, v68
	v_fmac_f32_e32 v15, v134, v72
	v_fmac_f32_e32 v12, v134, v76
	v_fmac_f32_e32 v13, v134, v80
	v_fmac_f32_e32 v10, v134, v84
	v_fmac_f32_e32 v11, v134, v88
	v_fmac_f32_e32 v8, v134, v92
	v_fmac_f32_e32 v9, v134, v96
	v_fmac_f32_e32 v14, v135, v69
	v_fmac_f32_e32 v15, v135, v73
	v_fmac_f32_e32 v12, v135, v77
	v_fmac_f32_e32 v13, v135, v81
	v_fmac_f32_e32 v10, v135, v85
	v_fmac_f32_e32 v11, v135, v89
	v_fmac_f32_e32 v8, v135, v93
	v_fmac_f32_e32 v9, v135, v97
	v_mov_b32_e32 v104, 96
	ds_read_b128 v[66:69], v104 offset:3328
	ds_read_b128 v[70:73], v104 offset:3584
	ds_read_b128 v[74:77], v104 offset:3840
	ds_read_b128 v[78:81], v104 offset:4096
	ds_read_b128 v[82:85], v104 offset:4352
	ds_read_b128 v[86:89], v104 offset:4608
	ds_read_b128 v[90:93], v104 offset:4864
	ds_read_b128 v[94:97], v104 offset:5120
	s_waitcnt vmcnt(36)
	s_waitcnt lgkmcnt(0)
	v_fmac_f32_e32 v14, v136, v66
	v_fmac_f32_e32 v15, v136, v70
	v_fmac_f32_e32 v12, v136, v74
	v_fmac_f32_e32 v13, v136, v78
	v_fmac_f32_e32 v10, v136, v82
	v_fmac_f32_e32 v11, v136, v86
	v_fmac_f32_e32 v8, v136, v90
	v_fmac_f32_e32 v9, v136, v94
	v_fmac_f32_e32 v14, v137, v67
	v_fmac_f32_e32 v15, v137, v71
	v_fmac_f32_e32 v12, v137, v75
	v_fmac_f32_e32 v13, v137, v79
	v_fmac_f32_e32 v10, v137, v83
	v_fmac_f32_e32 v11, v137, v87
	v_fmac_f32_e32 v8, v137, v91
	v_fmac_f32_e32 v9, v137, v95
	v_fmac_f32_e32 v14, v138, v68
	v_fmac_f32_e32 v15, v138, v72
	v_fmac_f32_e32 v12, v138, v76
	v_fmac_f32_e32 v13, v138, v80
	v_fmac_f32_e32 v10, v138, v84
	v_fmac_f32_e32 v11, v138, v88
	v_fmac_f32_e32 v8, v138, v92
	v_fmac_f32_e32 v9, v138, v96
	v_fmac_f32_e32 v14, v139, v69
	v_fmac_f32_e32 v15, v139, v73
	v_fmac_f32_e32 v12, v139, v77
	v_fmac_f32_e32 v13, v139, v81
	v_fmac_f32_e32 v10, v139, v85
	v_fmac_f32_e32 v11, v139, v89
	v_fmac_f32_e32 v8, v139, v93
	v_fmac_f32_e32 v9, v139, v97
	v_mov_b32_e32 v104, 112
	ds_read_b128 v[66:69], v104 offset:3328
	ds_read_b128 v[70:73], v104 offset:3584
	ds_read_b128 v[74:77], v104 offset:3840
	ds_read_b128 v[78:81], v104 offset:4096
	ds_read_b128 v[82:85], v104 offset:4352
	ds_read_b128 v[86:89], v104 offset:4608
	ds_read_b128 v[90:93], v104 offset:4864
	ds_read_b128 v[94:97], v104 offset:5120
	s_waitcnt vmcnt(32)
	s_waitcnt lgkmcnt(0)
	v_fmac_f32_e32 v14, v140, v66
	v_fmac_f32_e32 v15, v140, v70
	v_fmac_f32_e32 v12, v140, v74
	v_fmac_f32_e32 v13, v140, v78
	v_fmac_f32_e32 v10, v140, v82
	v_fmac_f32_e32 v11, v140, v86
	v_fmac_f32_e32 v8, v140, v90
	v_fmac_f32_e32 v9, v140, v94
	v_fmac_f32_e32 v14, v141, v67
	v_fmac_f32_e32 v15, v141, v71
	v_fmac_f32_e32 v12, v141, v75
	v_fmac_f32_e32 v13, v141, v79
	v_fmac_f32_e32 v10, v141, v83
	v_fmac_f32_e32 v11, v141, v87
	v_fmac_f32_e32 v8, v141, v91
	v_fmac_f32_e32 v9, v141, v95
	v_fmac_f32_e32 v14, v142, v68
	v_fmac_f32_e32 v15, v142, v72
	v_fmac_f32_e32 v12, v142, v76
	v_fmac_f32_e32 v13, v142, v80
	v_fmac_f32_e32 v10, v142, v84
	v_fmac_f32_e32 v11, v142, v88
	v_fmac_f32_e32 v8, v142, v92
	v_fmac_f32_e32 v9, v142, v96
	v_fmac_f32_e32 v14, v143, v69
	v_fmac_f32_e32 v15, v143, v73
	v_fmac_f32_e32 v12, v143, v77
	v_fmac_f32_e32 v13, v143, v81
	v_fmac_f32_e32 v10, v143, v85
	v_fmac_f32_e32 v11, v143, v89
	v_fmac_f32_e32 v8, v143, v93
	v_fmac_f32_e32 v9, v143, v97
	v_mov_b32_e32 v104, 128
	ds_read_b128 v[66:69], v104 offset:3328
	ds_read_b128 v[70:73], v104 offset:3584
	ds_read_b128 v[74:77], v104 offset:3840
	ds_read_b128 v[78:81], v104 offset:4096
	ds_read_b128 v[82:85], v104 offset:4352
	ds_read_b128 v[86:89], v104 offset:4608
	ds_read_b128 v[90:93], v104 offset:4864
	ds_read_b128 v[94:97], v104 offset:5120
	s_waitcnt vmcnt(28)
	s_waitcnt lgkmcnt(0)
	v_fmac_f32_e32 v14, v144, v66
	v_fmac_f32_e32 v15, v144, v70
	v_fmac_f32_e32 v12, v144, v74
	v_fmac_f32_e32 v13, v144, v78
	v_fmac_f32_e32 v10, v144, v82
	v_fmac_f32_e32 v11, v144, v86
	v_fmac_f32_e32 v8, v144, v90
	v_fmac_f32_e32 v9, v144, v94
	v_fmac_f32_e32 v14, v145, v67
	v_fmac_f32_e32 v15, v145, v71
	v_fmac_f32_e32 v12, v145, v75
	v_fmac_f32_e32 v13, v145, v79
	v_fmac_f32_e32 v10, v145, v83
	v_fmac_f32_e32 v11, v145, v87
	v_fmac_f32_e32 v8, v145, v91
	v_fmac_f32_e32 v9, v145, v95
	v_fmac_f32_e32 v14, v146, v68
	v_fmac_f32_e32 v15, v146, v72
	v_fmac_f32_e32 v12, v146, v76
	v_fmac_f32_e32 v13, v146, v80
	v_fmac_f32_e32 v10, v146, v84
	v_fmac_f32_e32 v11, v146, v88
	v_fmac_f32_e32 v8, v146, v92
	v_fmac_f32_e32 v9, v146, v96
	v_fmac_f32_e32 v14, v147, v69
	v_fmac_f32_e32 v15, v147, v73
	v_fmac_f32_e32 v12, v147, v77
	v_fmac_f32_e32 v13, v147, v81
	v_fmac_f32_e32 v10, v147, v85
	v_fmac_f32_e32 v11, v147, v89
	v_fmac_f32_e32 v8, v147, v93
	v_fmac_f32_e32 v9, v147, v97
	v_mov_b32_e32 v104, 144
	ds_read_b128 v[66:69], v104 offset:3328
	ds_read_b128 v[70:73], v104 offset:3584
	ds_read_b128 v[74:77], v104 offset:3840
	ds_read_b128 v[78:81], v104 offset:4096
	ds_read_b128 v[82:85], v104 offset:4352
	ds_read_b128 v[86:89], v104 offset:4608
	ds_read_b128 v[90:93], v104 offset:4864
	ds_read_b128 v[94:97], v104 offset:5120
	s_waitcnt vmcnt(24)
	s_waitcnt lgkmcnt(0)
	v_fmac_f32_e32 v14, v148, v66
	v_fmac_f32_e32 v15, v148, v70
	v_fmac_f32_e32 v12, v148, v74
	v_fmac_f32_e32 v13, v148, v78
	v_fmac_f32_e32 v10, v148, v82
	v_fmac_f32_e32 v11, v148, v86
	v_fmac_f32_e32 v8, v148, v90
	v_fmac_f32_e32 v9, v148, v94
	v_fmac_f32_e32 v14, v149, v67
	v_fmac_f32_e32 v15, v149, v71
	v_fmac_f32_e32 v12, v149, v75
	v_fmac_f32_e32 v13, v149, v79
	v_fmac_f32_e32 v10, v149, v83
	v_fmac_f32_e32 v11, v149, v87
	v_fmac_f32_e32 v8, v149, v91
	v_fmac_f32_e32 v9, v149, v95
	v_fmac_f32_e32 v14, v150, v68
	v_fmac_f32_e32 v15, v150, v72
	v_fmac_f32_e32 v12, v150, v76
	v_fmac_f32_e32 v13, v150, v80
	v_fmac_f32_e32 v10, v150, v84
	v_fmac_f32_e32 v11, v150, v88
	v_fmac_f32_e32 v8, v150, v92
	v_fmac_f32_e32 v9, v150, v96
	v_fmac_f32_e32 v14, v151, v69
	v_fmac_f32_e32 v15, v151, v73
	v_fmac_f32_e32 v12, v151, v77
	v_fmac_f32_e32 v13, v151, v81
	v_fmac_f32_e32 v10, v151, v85
	v_fmac_f32_e32 v11, v151, v89
	v_fmac_f32_e32 v8, v151, v93
	v_fmac_f32_e32 v9, v151, v97
	v_mov_b32_e32 v104, 160
	ds_read_b128 v[66:69], v104 offset:3328
	ds_read_b128 v[70:73], v104 offset:3584
	ds_read_b128 v[74:77], v104 offset:3840
	ds_read_b128 v[78:81], v104 offset:4096
	ds_read_b128 v[82:85], v104 offset:4352
	ds_read_b128 v[86:89], v104 offset:4608
	ds_read_b128 v[90:93], v104 offset:4864
	ds_read_b128 v[94:97], v104 offset:5120
	s_waitcnt vmcnt(20)
	s_waitcnt lgkmcnt(0)
	v_fmac_f32_e32 v14, v152, v66
	v_fmac_f32_e32 v15, v152, v70
	v_fmac_f32_e32 v12, v152, v74
	v_fmac_f32_e32 v13, v152, v78
	v_fmac_f32_e32 v10, v152, v82
	v_fmac_f32_e32 v11, v152, v86
	v_fmac_f32_e32 v8, v152, v90
	v_fmac_f32_e32 v9, v152, v94
	v_fmac_f32_e32 v14, v153, v67
	v_fmac_f32_e32 v15, v153, v71
	v_fmac_f32_e32 v12, v153, v75
	v_fmac_f32_e32 v13, v153, v79
	v_fmac_f32_e32 v10, v153, v83
	v_fmac_f32_e32 v11, v153, v87
	v_fmac_f32_e32 v8, v153, v91
	v_fmac_f32_e32 v9, v153, v95
	v_fmac_f32_e32 v14, v154, v68
	v_fmac_f32_e32 v15, v154, v72
	v_fmac_f32_e32 v12, v154, v76
	v_fmac_f32_e32 v13, v154, v80
	v_fmac_f32_e32 v10, v154, v84
	v_fmac_f32_e32 v11, v154, v88
	v_fmac_f32_e32 v8, v154, v92
	v_fmac_f32_e32 v9, v154, v96
	v_fmac_f32_e32 v14, v155, v69
	v_fmac_f32_e32 v15, v155, v73
	v_fmac_f32_e32 v12, v155, v77
	v_fmac_f32_e32 v13, v155, v81
	v_fmac_f32_e32 v10, v155, v85
	v_fmac_f32_e32 v11, v155, v89
	v_fmac_f32_e32 v8, v155, v93
	v_fmac_f32_e32 v9, v155, v97
	v_mov_b32_e32 v104, 176
	ds_read_b128 v[66:69], v104 offset:3328
	ds_read_b128 v[70:73], v104 offset:3584
	ds_read_b128 v[74:77], v104 offset:3840
	ds_read_b128 v[78:81], v104 offset:4096
	ds_read_b128 v[82:85], v104 offset:4352
	ds_read_b128 v[86:89], v104 offset:4608
	ds_read_b128 v[90:93], v104 offset:4864
	ds_read_b128 v[94:97], v104 offset:5120
	s_waitcnt vmcnt(16)
	s_waitcnt lgkmcnt(0)
	v_fmac_f32_e32 v14, v156, v66
	v_fmac_f32_e32 v15, v156, v70
	v_fmac_f32_e32 v12, v156, v74
	v_fmac_f32_e32 v13, v156, v78
	v_fmac_f32_e32 v10, v156, v82
	v_fmac_f32_e32 v11, v156, v86
	v_fmac_f32_e32 v8, v156, v90
	v_fmac_f32_e32 v9, v156, v94
	v_fmac_f32_e32 v14, v157, v67
	v_fmac_f32_e32 v15, v157, v71
	v_fmac_f32_e32 v12, v157, v75
	v_fmac_f32_e32 v13, v157, v79
	v_fmac_f32_e32 v10, v157, v83
	v_fmac_f32_e32 v11, v157, v87
	v_fmac_f32_e32 v8, v157, v91
	v_fmac_f32_e32 v9, v157, v95
	v_fmac_f32_e32 v14, v158, v68
	v_fmac_f32_e32 v15, v158, v72
	v_fmac_f32_e32 v12, v158, v76
	v_fmac_f32_e32 v13, v158, v80
	v_fmac_f32_e32 v10, v158, v84
	v_fmac_f32_e32 v11, v158, v88
	v_fmac_f32_e32 v8, v158, v92
	v_fmac_f32_e32 v9, v158, v96
	v_fmac_f32_e32 v14, v159, v69
	v_fmac_f32_e32 v15, v159, v73
	v_fmac_f32_e32 v12, v159, v77
	v_fmac_f32_e32 v13, v159, v81
	v_fmac_f32_e32 v10, v159, v85
	v_fmac_f32_e32 v11, v159, v89
	v_fmac_f32_e32 v8, v159, v93
	v_fmac_f32_e32 v9, v159, v97
	v_mov_b32_e32 v104, 192
	ds_read_b128 v[66:69], v104 offset:3328
	ds_read_b128 v[70:73], v104 offset:3584
	ds_read_b128 v[74:77], v104 offset:3840
	ds_read_b128 v[78:81], v104 offset:4096
	ds_read_b128 v[82:85], v104 offset:4352
	ds_read_b128 v[86:89], v104 offset:4608
	ds_read_b128 v[90:93], v104 offset:4864
	ds_read_b128 v[94:97], v104 offset:5120
	s_waitcnt vmcnt(12)
	s_waitcnt lgkmcnt(0)
	v_fmac_f32_e32 v14, v160, v66
	v_fmac_f32_e32 v15, v160, v70
	v_fmac_f32_e32 v12, v160, v74
	v_fmac_f32_e32 v13, v160, v78
	v_fmac_f32_e32 v10, v160, v82
	v_fmac_f32_e32 v11, v160, v86
	v_fmac_f32_e32 v8, v160, v90
	v_fmac_f32_e32 v9, v160, v94
	v_fmac_f32_e32 v14, v161, v67
	v_fmac_f32_e32 v15, v161, v71
	v_fmac_f32_e32 v12, v161, v75
	v_fmac_f32_e32 v13, v161, v79
	v_fmac_f32_e32 v10, v161, v83
	v_fmac_f32_e32 v11, v161, v87
	v_fmac_f32_e32 v8, v161, v91
	v_fmac_f32_e32 v9, v161, v95
	v_fmac_f32_e32 v14, v162, v68
	v_fmac_f32_e32 v15, v162, v72
	v_fmac_f32_e32 v12, v162, v76
	v_fmac_f32_e32 v13, v162, v80
	v_fmac_f32_e32 v10, v162, v84
	v_fmac_f32_e32 v11, v162, v88
	v_fmac_f32_e32 v8, v162, v92
	v_fmac_f32_e32 v9, v162, v96
	v_fmac_f32_e32 v14, v163, v69
	v_fmac_f32_e32 v15, v163, v73
	v_fmac_f32_e32 v12, v163, v77
	v_fmac_f32_e32 v13, v163, v81
	v_fmac_f32_e32 v10, v163, v85
	v_fmac_f32_e32 v11, v163, v89
	v_fmac_f32_e32 v8, v163, v93
	v_fmac_f32_e32 v9, v163, v97
	v_mov_b32_e32 v104, 208
	ds_read_b128 v[66:69], v104 offset:3328
	ds_read_b128 v[70:73], v104 offset:3584
	ds_read_b128 v[74:77], v104 offset:3840
	ds_read_b128 v[78:81], v104 offset:4096
	ds_read_b128 v[82:85], v104 offset:4352
	ds_read_b128 v[86:89], v104 offset:4608
	ds_read_b128 v[90:93], v104 offset:4864
	ds_read_b128 v[94:97], v104 offset:5120
	s_waitcnt vmcnt(8)
	s_waitcnt lgkmcnt(0)
	v_fmac_f32_e32 v14, v164, v66
	v_fmac_f32_e32 v15, v164, v70
	v_fmac_f32_e32 v12, v164, v74
	v_fmac_f32_e32 v13, v164, v78
	v_fmac_f32_e32 v10, v164, v82
	v_fmac_f32_e32 v11, v164, v86
	v_fmac_f32_e32 v8, v164, v90
	v_fmac_f32_e32 v9, v164, v94
	v_fmac_f32_e32 v14, v165, v67
	v_fmac_f32_e32 v15, v165, v71
	v_fmac_f32_e32 v12, v165, v75
	v_fmac_f32_e32 v13, v165, v79
	v_fmac_f32_e32 v10, v165, v83
	v_fmac_f32_e32 v11, v165, v87
	v_fmac_f32_e32 v8, v165, v91
	v_fmac_f32_e32 v9, v165, v95
	v_fmac_f32_e32 v14, v166, v68
	v_fmac_f32_e32 v15, v166, v72
	v_fmac_f32_e32 v12, v166, v76
	v_fmac_f32_e32 v13, v166, v80
	v_fmac_f32_e32 v10, v166, v84
	v_fmac_f32_e32 v11, v166, v88
	v_fmac_f32_e32 v8, v166, v92
	v_fmac_f32_e32 v9, v166, v96
	v_fmac_f32_e32 v14, v167, v69
	v_fmac_f32_e32 v15, v167, v73
	v_fmac_f32_e32 v12, v167, v77
	v_fmac_f32_e32 v13, v167, v81
	v_fmac_f32_e32 v10, v167, v85
	v_fmac_f32_e32 v11, v167, v89
	v_fmac_f32_e32 v8, v167, v93
	v_fmac_f32_e32 v9, v167, v97
	v_mov_b32_e32 v104, 224
	ds_read_b128 v[66:69], v104 offset:3328
	ds_read_b128 v[70:73], v104 offset:3584
	ds_read_b128 v[74:77], v104 offset:3840
	ds_read_b128 v[78:81], v104 offset:4096
	ds_read_b128 v[82:85], v104 offset:4352
	ds_read_b128 v[86:89], v104 offset:4608
	ds_read_b128 v[90:93], v104 offset:4864
	ds_read_b128 v[94:97], v104 offset:5120
	s_waitcnt vmcnt(4)
	s_waitcnt lgkmcnt(0)
	v_fmac_f32_e32 v14, v168, v66
	v_fmac_f32_e32 v15, v168, v70
	v_fmac_f32_e32 v12, v168, v74
	v_fmac_f32_e32 v13, v168, v78
	v_fmac_f32_e32 v10, v168, v82
	v_fmac_f32_e32 v11, v168, v86
	v_fmac_f32_e32 v8, v168, v90
	v_fmac_f32_e32 v9, v168, v94
	v_fmac_f32_e32 v14, v169, v67
	v_fmac_f32_e32 v15, v169, v71
	v_fmac_f32_e32 v12, v169, v75
	v_fmac_f32_e32 v13, v169, v79
	v_fmac_f32_e32 v10, v169, v83
	v_fmac_f32_e32 v11, v169, v87
	v_fmac_f32_e32 v8, v169, v91
	v_fmac_f32_e32 v9, v169, v95
	v_fmac_f32_e32 v14, v175, v68
	v_fmac_f32_e32 v15, v175, v72
	v_fmac_f32_e32 v12, v175, v76
	v_fmac_f32_e32 v13, v175, v80
	v_fmac_f32_e32 v10, v175, v84
	v_fmac_f32_e32 v11, v175, v88
	v_fmac_f32_e32 v8, v175, v92
	v_fmac_f32_e32 v9, v175, v96
	v_fmac_f32_e32 v14, v176, v69
	v_fmac_f32_e32 v15, v176, v73
	v_fmac_f32_e32 v12, v176, v77
	v_fmac_f32_e32 v13, v176, v81
	v_fmac_f32_e32 v10, v176, v85
	v_fmac_f32_e32 v11, v176, v89
	v_fmac_f32_e32 v8, v176, v93
	v_fmac_f32_e32 v9, v176, v97
	v_mov_b32_e32 v104, 240
	ds_read_b128 v[66:69], v104 offset:3328
	ds_read_b128 v[70:73], v104 offset:3584
	ds_read_b128 v[74:77], v104 offset:3840
	ds_read_b128 v[78:81], v104 offset:4096
	ds_read_b128 v[82:85], v104 offset:4352
	ds_read_b128 v[86:89], v104 offset:4608
	ds_read_b128 v[90:93], v104 offset:4864
	ds_read_b128 v[94:97], v104 offset:5120
	s_waitcnt vmcnt(0)
	s_waitcnt lgkmcnt(0)
	v_fmac_f32_e32 v14, v177, v66
	v_fmac_f32_e32 v15, v177, v70
	v_fmac_f32_e32 v12, v177, v74
	v_fmac_f32_e32 v13, v177, v78
	v_fmac_f32_e32 v10, v177, v82
	v_fmac_f32_e32 v11, v177, v86
	v_fmac_f32_e32 v8, v177, v90
	v_fmac_f32_e32 v9, v177, v94
	v_fmac_f32_e32 v14, v178, v67
	v_fmac_f32_e32 v15, v178, v71
	v_fmac_f32_e32 v12, v178, v75
	v_fmac_f32_e32 v13, v178, v79
	v_fmac_f32_e32 v10, v178, v83
	v_fmac_f32_e32 v11, v178, v87
	v_fmac_f32_e32 v8, v178, v91
	v_fmac_f32_e32 v9, v178, v95
	v_fmac_f32_e32 v14, v179, v68
	v_fmac_f32_e32 v15, v179, v72
	v_fmac_f32_e32 v12, v179, v76
	v_fmac_f32_e32 v13, v179, v80
	v_fmac_f32_e32 v10, v179, v84
	v_fmac_f32_e32 v11, v179, v88
	v_fmac_f32_e32 v8, v179, v92
	v_fmac_f32_e32 v9, v179, v96
	v_fmac_f32_e32 v14, v180, v69
	v_fmac_f32_e32 v15, v180, v73
	v_fmac_f32_e32 v12, v180, v77
	v_fmac_f32_e32 v13, v180, v81
	v_fmac_f32_e32 v10, v180, v85
	v_fmac_f32_e32 v11, v180, v89
	v_fmac_f32_e32 v8, v180, v93
	v_fmac_f32_e32 v9, v180, v97
	v_mul_f32_e32 v0, v19, v14
	s_and_saveexec_b64 s[12:13], s[50:51]
	s_xor_b64 s[16:17], exec, s[12:13]
	s_cbranch_execz .LBB0_1314
	v_cmp_gt_i32_e32 vcc, 1, v20
	s_and_saveexec_b64 s[12:13], vcc
	s_xor_b64 s[18:19], exec, s[12:13]
	s_cbranch_execz .LBB0_1311
	global_store_short v[4:5], v1, off offset:-2
